# K-loops: 75 LDS-DMA loads whose address was SGPR base + zero-extended per-lane offset (a 64-bit VALU add per load) now use the saddr form directly, removing that VALU issue from the loading wave
# speedup vs baseline: 1.0089x; 1.0089x over previous
; #define PG8_STAGE(bufoff, gbase, voff) do { _Pragma("unroll") for (int _i = 0; _i < 2; ++_i) \
;         __builtin_amdgcn_global_load_lds((const unsigned*)((const char*)(gbase) + (voff)[_i]), (PG8_LAS unsigned*)(lds + (bufoff) + ldsw + _i * 8192), 16, 0, 0); } while (0)
; #define PG8_LDA(dst, b, h) do { _Pragma("unroll") for (int m = 0; m < 4; ++m) _Pragma("unroll") for (int k = 0; k < 2; ++k) dst[m][k] = *(const PG8_LAS bf16x8*)(lds + PG8_SA(b, h) + aoff + m * 2048 + k * 1024); } while (0)
; #define PG8_LDB(dst, b, h) do { _Pragma("unroll") for (int n = 0; n < 2; ++n) _Pragma("unroll") for (int k = 0; k < 2; ++k) dst[n][k] = *(const PG8_LAS bf16x8*)(lds + PG8_SB(b, h) + boff + n * 2048 + k * 1024); } while (0)
; #define PG8_WAIT_V(n) asm volatile("s_waitcnt vmcnt(" #n ")" ::: "memory")
; #define PG8_WAIT_L(n) asm volatile("s_waitcnt lgkmcnt(" #n ")" ::: "memory")
; #define PG8_BAR __builtin_amdgcn_s_barrier()
; #define PG8_SCHED __builtin_amdgcn_sched_barrier(0)
; template <class Epi, class Sched, bool ALIGN_EPI = false, bool SP2 = false>
; __device__ __forceinline__ void gemm_phase(PG8_LAS unsigned char* lds, const Gemm g, const Sched& S, const Epi& E, int wave_s) {
;     ...
;         const bool has_next = S.next(ui + 1, nxt);
;         const char* nA = has_next ? (const char*)g.A + (size_t)nxt.pm * tstepA + (size_t)(nxt.pn / g.npg) * (size_t)(K * 2) : cA; const char* nB = has_next ? (const char*)g.Bt + (size_t)nxt.pn * tstepB : cB;
;         for (int t = 0; t < nt; t += 2) {
;             const bool last = (t == nt - 2);
;             const char* a1 = cA + (size_t)(t + 1) * kstep;
;             const char* a2 = last ? nA : cA + (size_t)(t + 2) * kstep; const char* b2 = last ? nB : cB + (size_t)(t + 2) * kstep;
;             const char* a3 = a2 + kstep; const char* b3 = b2 + kstep;
;             if (last && has_next) S.a_ready(nxt);
;             if constexpr (SP2) {
;             PG8_LDB(B0, 0, 0); PG8_LDB(B1, 0, 1); PG8_SCHED; PG8_LDA(At, 0, 0); PG8_STAGE(PG8_SA(1, 1), a1 + hstepA, voffA);
;             PG8_WAIT_V(8); PG8_WAIT_L(0); PG8_BAR; PG8_MMA(0, 0, At, B0); PG8_MMA(0, 1, At, B1); PG8_BAR; PG8_SCHED;
;             PG8_LDA(At, 0, 1); PG8_STAGE(PG8_SB(0, 0), b2, voffB); PG8_STAGE(PG8_SB(0, 1), b2 + hstepB, voffB); PG8_STAGE(PG8_SA(0, 0), a2, voffA);
.LBB0_313:
	s_ashr_i32 s29, s28, 31
	s_lshl_b64 s[2:3], s[28:29], 18
	s_add_u32 s96, s22, s2
	s_addc_u32 s97, s23, s3
	s_and_b64 s[2:3], s[4:5], exec
	s_cselect_b32 s2, s97, s31
	s_cselect_b32 s3, s96, s30
	s_add_u32 s4, s40, 0x80080
	s_addc_u32 s5, s41, 0
	s_add_u32 s29, s30, 0x100
	s_addc_u32 s81, s31, 0
	s_mov_b32 s84, -2
	s_add_u32 s30, s4, 0xfff80080
	s_addc_u32 s31, s5, -1
	s_add_i32 s85, 0, 0x10000
	s_cmp_eq_u32 s84, 4
	s_cselect_b32 s41, s91, s31
	s_cselect_b32 s40, s90, s30
	s_cselect_b32 s31, s2, s81
	s_cselect_b32 s30, s3, s29
	s_add_i32 s89, 0, 0x14000
	v_add_u32_e32 v118, s85, v229
	v_add_u32_e32 v150, s89, v229
	ds_read_b128 v[106:109], v118
	ds_read_b128 v[110:113], v118 offset:1024
	ds_read_b128 v[114:117], v118 offset:2048
	ds_read_b128 v[118:121], v118 offset:3072
	ds_read_b128 v[122:125], v150
	ds_read_b128 v[126:129], v150 offset:1024
	ds_read_b128 v[142:145], v150 offset:2048
	ds_read_b128 v[150:153], v150 offset:3072
	s_add_i32 m0, s35, 0xc000
	ds_read_b128 v[162:165], v230
	ds_read_b128 v[166:169], v230 offset:1024
	ds_read_b128 v[170:173], v230 offset:2048
	ds_read_b128 v[174:177], v230 offset:3072
	ds_read_b128 v[178:181], v230 offset:4096
	ds_read_b128 v[182:185], v230 offset:5120
	ds_read_b128 v[186:189], v230 offset:6144
	ds_read_b128 v[190:193], v230 offset:7168
	global_load_lds_dwordx4 v218, s[4:5]
	s_add_i32 m0, s35, 0xe000
	s_nop 0
	global_load_lds_dwordx4 v220, s[4:5]
	s_waitcnt vmcnt(8)
	s_waitcnt lgkmcnt(0)
	s_barrier
	s_waitcnt lgkmcnt(0)
	v_mfma_f32_16x16x32_bf16 v[158:161], v[106:109], v[162:165], 0
	v_mfma_f32_16x16x32_bf16 v[154:157], v[114:117], v[162:165], 0
	v_mfma_f32_16x16x32_bf16 v[134:137], v[106:109], v[170:173], 0
	v_mfma_f32_16x16x32_bf16 v[130:133], v[114:117], v[170:173], 0
	v_mfma_f32_16x16x32_bf16 v[94:97], v[106:109], v[178:181], 0
	v_mfma_f32_16x16x32_bf16 v[90:93], v[114:117], v[178:181], 0
	v_mfma_f32_16x16x32_bf16 v[78:81], v[106:109], v[186:189], 0
	v_mfma_f32_16x16x32_bf16 v[74:77], v[114:117], v[186:189], 0
	v_mfma_f32_16x16x32_bf16 v[158:161], v[110:113], v[166:169], v[158:161]
	v_mfma_f32_16x16x32_bf16 v[154:157], v[118:121], v[166:169], v[154:157]
	v_mfma_f32_16x16x32_bf16 v[134:137], v[110:113], v[174:177], v[134:137]
	v_mfma_f32_16x16x32_bf16 v[130:133], v[118:121], v[174:177], v[130:133]
	v_mfma_f32_16x16x32_bf16 v[94:97], v[110:113], v[182:185], v[94:97]
	v_mfma_f32_16x16x32_bf16 v[90:93], v[118:121], v[182:185], v[90:93]
	v_mfma_f32_16x16x32_bf16 v[78:81], v[110:113], v[190:193], v[78:81]
	v_mfma_f32_16x16x32_bf16 v[74:77], v[118:121], v[190:193], v[74:77]
	v_mfma_f32_16x16x32_bf16 v[146:149], v[122:125], v[162:165], 0
	v_mfma_f32_16x16x32_bf16 v[138:141], v[142:145], v[162:165], 0
	v_mfma_f32_16x16x32_bf16 v[102:105], v[122:125], v[170:173], 0
	v_mfma_f32_16x16x32_bf16 v[98:101], v[142:145], v[170:173], 0
	v_mfma_f32_16x16x32_bf16 v[86:89], v[122:125], v[178:181], 0
	v_mfma_f32_16x16x32_bf16 v[82:85], v[142:145], v[178:181], 0
	v_mfma_f32_16x16x32_bf16 v[70:73], v[122:125], v[186:189], 0
	v_mfma_f32_16x16x32_bf16 v[66:69], v[142:145], v[186:189], 0
	v_mfma_f32_16x16x32_bf16 v[146:149], v[126:129], v[166:169], v[146:149]
	v_mfma_f32_16x16x32_bf16 v[138:141], v[150:153], v[166:169], v[138:141]
	v_mfma_f32_16x16x32_bf16 v[102:105], v[126:129], v[174:177], v[102:105]
	v_mfma_f32_16x16x32_bf16 v[98:101], v[150:153], v[174:177], v[98:101]
	v_mfma_f32_16x16x32_bf16 v[86:89], v[126:129], v[182:185], v[86:89]
	v_mfma_f32_16x16x32_bf16 v[82:85], v[150:153], v[182:185], v[82:85]
	v_mfma_f32_16x16x32_bf16 v[70:73], v[126:129], v[190:193], v[70:73]
	v_mfma_f32_16x16x32_bf16 v[66:69], v[150:153], v[190:193], v[66:69]
	s_barrier
	s_add_i32 s85, s85, s34
	v_lshl_add_u64 v[194:195], s[30:31], 0, v[214:215]
	s_mov_b32 m0, s85
	ds_read_b128 v[162:165], v230 offset:16384
	ds_read_b128 v[166:169], v230 offset:17408
	ds_read_b128 v[170:173], v230 offset:18432
	ds_read_b128 v[174:177], v230 offset:19456
	ds_read_b128 v[178:181], v230 offset:20480
	ds_read_b128 v[182:185], v230 offset:21504
	ds_read_b128 v[186:189], v230 offset:22528
	ds_read_b128 v[190:193], v230 offset:23552
	global_load_lds_dwordx4 v[194:195], off
	s_add_i32 m0, s85, 0x2000
	s_add_u32 s94, s30, 0x20000
	v_lshl_add_u64 v[196:197], s[30:31], 0, v[210:211]
	s_addc_u32 s95, s31, 0
	s_add_i32 s85, s89, s34
	global_load_lds_dwordx4 v[196:197], off
	s_mov_b32 m0, s85
	v_lshl_add_u64 v[200:201], s[40:41], 0, v[212:213]
	global_load_lds_dwordx4 v214, s[94:95]
	s_add_i32 m0, s85, 0x2000
	s_nop 0
	global_load_lds_dwordx4 v210, s[94:95]
	v_lshl_add_u64 v[198:199], s[40:41], 0, v[216:217]
	s_mov_b32 m0, s35
	s_nop 0
	global_load_lds_dwordx4 v[198:199], off
	s_mov_b32 m0, s36
	s_nop 0
	global_load_lds_dwordx4 v[200:201], off
	s_waitcnt vmcnt(8)
	s_waitcnt lgkmcnt(0)
	s_barrier
; #define PG8_STAGE(bufoff, gbase, voff) do { _Pragma("unroll") for (int _i = 0; _i < 2; ++_i) \
;         __builtin_amdgcn_global_load_lds((const unsigned*)((const char*)(gbase) + (voff)[_i]), (PG8_LAS unsigned*)(lds + (bufoff) + ldsw + _i * 8192), 16, 0, 0); } while (0)
; #define PG8_LDA(dst, b, h) do { _Pragma("unroll") for (int m = 0; m < 4; ++m) _Pragma("unroll") for (int k = 0; k < 2; ++k) dst[m][k] = *(const PG8_LAS bf16x8*)(lds + PG8_SA(b, h) + aoff + m * 2048 + k * 1024); } while (0)
; #define PG8_LDB(dst, b, h) do { _Pragma("unroll") for (int n = 0; n < 2; ++n) _Pragma("unroll") for (int k = 0; k < 2; ++k) dst[n][k] = *(const PG8_LAS bf16x8*)(lds + PG8_SB(b, h) + boff + n * 2048 + k * 1024); } while (0)
; #define PG8_MMA(ai, bj, At, Bt) do { __builtin_amdgcn_s_setprio(1); _Pragma("unroll") for (int m = 0; m < 4; ++m) _Pragma("unroll") for (int n = 0; n < 2; ++n) _Pragma("unroll") for (int k = 0; k < 2; ++k) \
;         acc[ai][bj][m][n] = __builtin_amdgcn_mfma_f32_16x16x32_bf16(Bt[n][k], At[m][k], acc[ai][bj][m][n], 0, 0, 0); __builtin_amdgcn_s_setprio(0); } while (0)
; #define PG8_WAIT_V(n) asm volatile("s_waitcnt vmcnt(" #n ")" ::: "memory")
; #define PG8_WAIT_L(n) asm volatile("s_waitcnt lgkmcnt(" #n ")" ::: "memory")
; #define PG8_BAR __builtin_amdgcn_s_barrier()
; #define PG8_SCHED __builtin_amdgcn_sched_barrier(0)
; template <class Epi, class Sched, bool ALIGN_EPI = false, bool SP2 = false>
; __device__ __forceinline__ void gemm_phase(PG8_LAS unsigned char* lds, const Gemm g, const Sched& S, const Epi& E, int wave_s) {
;     ...
;             PG8_LDA(At, 0, 1); PG8_STAGE(PG8_SB(0, 0), b2, voffB); PG8_STAGE(PG8_SB(0, 1), b2 + hstepB, voffB); PG8_STAGE(PG8_SA(0, 0), a2, voffA);
;             PG8_WAIT_V(8); PG8_WAIT_L(0); PG8_BAR; PG8_MMA(1, 0, At, B0); PG8_MMA(1, 1, At, B1); PG8_BAR; PG8_SCHED;
;             PG8_LDB(B0, 1, 0); PG8_LDB(B1, 1, 1); PG8_SCHED; PG8_LDA(At, 1, 0); PG8_STAGE(PG8_SA(0, 1), a2 + hstepA, voffA);
;             PG8_WAIT_V(8); PG8_WAIT_L(0); PG8_BAR; PG8_MMA(0, 0, At, B0); PG8_MMA(0, 1, At, B1); PG8_BAR; PG8_SCHED;
	s_waitcnt lgkmcnt(0)
	v_mfma_f32_16x16x32_bf16 v[62:65], v[106:109], v[162:165], 0
	v_mfma_f32_16x16x32_bf16 v[58:61], v[114:117], v[162:165], 0
	v_mfma_f32_16x16x32_bf16 v[46:49], v[106:109], v[170:173], 0
	v_mfma_f32_16x16x32_bf16 v[42:45], v[114:117], v[170:173], 0
	v_mfma_f32_16x16x32_bf16 v[30:33], v[106:109], v[178:181], 0
	v_mfma_f32_16x16x32_bf16 v[26:29], v[114:117], v[178:181], 0
	v_mfma_f32_16x16x32_bf16 v[14:17], v[106:109], v[186:189], 0
	v_mfma_f32_16x16x32_bf16 v[10:13], v[114:117], v[186:189], 0
	v_mfma_f32_16x16x32_bf16 v[62:65], v[110:113], v[166:169], v[62:65]
	v_mfma_f32_16x16x32_bf16 v[58:61], v[118:121], v[166:169], v[58:61]
	v_mfma_f32_16x16x32_bf16 v[46:49], v[110:113], v[174:177], v[46:49]
	v_mfma_f32_16x16x32_bf16 v[42:45], v[118:121], v[174:177], v[42:45]
	v_mfma_f32_16x16x32_bf16 v[30:33], v[110:113], v[182:185], v[30:33]
	v_mfma_f32_16x16x32_bf16 v[26:29], v[118:121], v[182:185], v[26:29]
	v_mfma_f32_16x16x32_bf16 v[14:17], v[110:113], v[190:193], v[14:17]
	v_mfma_f32_16x16x32_bf16 v[10:13], v[118:121], v[190:193], v[10:13]
	v_mfma_f32_16x16x32_bf16 v[54:57], v[122:125], v[162:165], 0
	v_mfma_f32_16x16x32_bf16 v[50:53], v[142:145], v[162:165], 0
	v_mfma_f32_16x16x32_bf16 v[38:41], v[122:125], v[170:173], 0
	v_mfma_f32_16x16x32_bf16 v[34:37], v[142:145], v[170:173], 0
	v_mfma_f32_16x16x32_bf16 v[22:25], v[122:125], v[178:181], 0
	v_mfma_f32_16x16x32_bf16 v[18:21], v[142:145], v[178:181], 0
	v_mfma_f32_16x16x32_bf16 v[6:9], v[122:125], v[186:189], 0
	v_mfma_f32_16x16x32_bf16 v[2:5], v[142:145], v[186:189], 0
	v_mfma_f32_16x16x32_bf16 v[54:57], v[126:129], v[166:169], v[54:57]
	v_mfma_f32_16x16x32_bf16 v[50:53], v[150:153], v[166:169], v[50:53]
	v_mfma_f32_16x16x32_bf16 v[38:41], v[126:129], v[174:177], v[38:41]
	v_mfma_f32_16x16x32_bf16 v[34:37], v[150:153], v[174:177], v[34:37]
	v_mfma_f32_16x16x32_bf16 v[22:25], v[126:129], v[182:185], v[22:25]
	v_mfma_f32_16x16x32_bf16 v[18:21], v[150:153], v[182:185], v[18:21]
	v_mfma_f32_16x16x32_bf16 v[6:9], v[126:129], v[190:193], v[6:9]
	v_mfma_f32_16x16x32_bf16 v[2:5], v[150:153], v[190:193], v[2:5]
	s_barrier
	s_add_i32 s85, 0, 0x18000
	s_add_i32 s89, 0, 0x1c000
	v_add_u32_e32 v118, s85, v229
	v_add_u32_e32 v150, s89, v229
	ds_read_b128 v[106:109], v118
	ds_read_b128 v[110:113], v118 offset:1024
	ds_read_b128 v[114:117], v118 offset:2048
	ds_read_b128 v[118:121], v118 offset:3072
	ds_read_b128 v[122:125], v150
	ds_read_b128 v[126:129], v150 offset:1024
	ds_read_b128 v[142:145], v150 offset:2048
	ds_read_b128 v[150:153], v150 offset:3072
	s_add_u32 s40, s40, 0x80000
	s_addc_u32 s41, s41, 0
	s_mov_b32 m0, s37
	ds_read_b128 v[162:165], v230 offset:32768
	ds_read_b128 v[166:169], v230 offset:33792
	ds_read_b128 v[170:173], v230 offset:34816
	ds_read_b128 v[174:177], v230 offset:35840
	ds_read_b128 v[178:181], v230 offset:36864
	ds_read_b128 v[182:185], v230 offset:37888
	ds_read_b128 v[186:189], v230 offset:38912
	ds_read_b128 v[190:193], v230 offset:39936
	global_load_lds_dwordx4 v216, s[40:41]
	s_mov_b32 m0, s42
	s_nop 0
	global_load_lds_dwordx4 v212, s[40:41]
	s_waitcnt vmcnt(8)
	s_waitcnt lgkmcnt(0)
	s_barrier
	s_waitcnt lgkmcnt(0)
	v_mfma_f32_16x16x32_bf16 v[158:161], v[106:109], v[162:165], v[158:161]
	v_mfma_f32_16x16x32_bf16 v[154:157], v[114:117], v[162:165], v[154:157]
	v_mfma_f32_16x16x32_bf16 v[134:137], v[106:109], v[170:173], v[134:137]
	v_mfma_f32_16x16x32_bf16 v[130:133], v[114:117], v[170:173], v[130:133]
	v_mfma_f32_16x16x32_bf16 v[94:97], v[106:109], v[178:181], v[94:97]
	v_mfma_f32_16x16x32_bf16 v[90:93], v[114:117], v[178:181], v[90:93]
	v_mfma_f32_16x16x32_bf16 v[78:81], v[106:109], v[186:189], v[78:81]
	v_mfma_f32_16x16x32_bf16 v[74:77], v[114:117], v[186:189], v[74:77]
	v_mfma_f32_16x16x32_bf16 v[158:161], v[110:113], v[166:169], v[158:161]
	v_mfma_f32_16x16x32_bf16 v[154:157], v[118:121], v[166:169], v[154:157]
	v_mfma_f32_16x16x32_bf16 v[134:137], v[110:113], v[174:177], v[134:137]
	v_mfma_f32_16x16x32_bf16 v[130:133], v[118:121], v[174:177], v[130:133]
	v_mfma_f32_16x16x32_bf16 v[94:97], v[110:113], v[182:185], v[94:97]
	v_mfma_f32_16x16x32_bf16 v[90:93], v[118:121], v[182:185], v[90:93]
	v_mfma_f32_16x16x32_bf16 v[78:81], v[110:113], v[190:193], v[78:81]
	v_mfma_f32_16x16x32_bf16 v[74:77], v[118:121], v[190:193], v[74:77]
	v_mfma_f32_16x16x32_bf16 v[146:149], v[122:125], v[162:165], v[146:149]
	v_mfma_f32_16x16x32_bf16 v[138:141], v[142:145], v[162:165], v[138:141]
	v_mfma_f32_16x16x32_bf16 v[102:105], v[122:125], v[170:173], v[102:105]
	v_mfma_f32_16x16x32_bf16 v[98:101], v[142:145], v[170:173], v[98:101]
	v_mfma_f32_16x16x32_bf16 v[86:89], v[122:125], v[178:181], v[86:89]
	v_mfma_f32_16x16x32_bf16 v[82:85], v[142:145], v[178:181], v[82:85]
	v_mfma_f32_16x16x32_bf16 v[70:73], v[122:125], v[186:189], v[70:73]
	v_mfma_f32_16x16x32_bf16 v[66:69], v[142:145], v[186:189], v[66:69]
	v_mfma_f32_16x16x32_bf16 v[146:149], v[126:129], v[166:169], v[146:149]
	v_mfma_f32_16x16x32_bf16 v[138:141], v[150:153], v[166:169], v[138:141]
	v_mfma_f32_16x16x32_bf16 v[102:105], v[126:129], v[174:177], v[102:105]
	v_mfma_f32_16x16x32_bf16 v[98:101], v[150:153], v[174:177], v[98:101]
	v_mfma_f32_16x16x32_bf16 v[86:89], v[126:129], v[182:185], v[86:89]
	v_mfma_f32_16x16x32_bf16 v[82:85], v[150:153], v[182:185], v[82:85]
	v_mfma_f32_16x16x32_bf16 v[70:73], v[126:129], v[190:193], v[70:73]
	v_mfma_f32_16x16x32_bf16 v[66:69], v[150:153], v[190:193], v[66:69]
	s_barrier
; #define PG8_STAGE(bufoff, gbase, voff) do { _Pragma("unroll") for (int _i = 0; _i < 2; ++_i) \
;         __builtin_amdgcn_global_load_lds((const unsigned*)((const char*)(gbase) + (voff)[_i]), (PG8_LAS unsigned*)(lds + (bufoff) + ldsw + _i * 8192), 16, 0, 0); } while (0)
; #define PG8_LDA(dst, b, h) do { _Pragma("unroll") for (int m = 0; m < 4; ++m) _Pragma("unroll") for (int k = 0; k < 2; ++k) dst[m][k] = *(const PG8_LAS bf16x8*)(lds + PG8_SA(b, h) + aoff + m * 2048 + k * 1024); } while (0)
; #define PG8_LDB(dst, b, h) do { _Pragma("unroll") for (int n = 0; n < 2; ++n) _Pragma("unroll") for (int k = 0; k < 2; ++k) dst[n][k] = *(const PG8_LAS bf16x8*)(lds + PG8_SB(b, h) + boff + n * 2048 + k * 1024); } while (0)
; #define PG8_WAIT_V(n) asm volatile("s_waitcnt vmcnt(" #n ")" ::: "memory")
; #define PG8_WAIT_L(n) asm volatile("s_waitcnt lgkmcnt(" #n ")" ::: "memory")
; #define PG8_BAR __builtin_amdgcn_s_barrier()
; #define PG8_SCHED __builtin_amdgcn_sched_barrier(0)
; template <class Epi, class Sched, bool ALIGN_EPI = false, bool SP2 = false>
; __device__ __forceinline__ void gemm_phase(PG8_LAS unsigned char* lds, const Gemm g, const Sched& S, const Epi& E, int wave_s) {
;     ...
;         for (int t = 0; t < nt; t += 2) {
;             const bool last = (t == nt - 2);
;             const char* a1 = cA + (size_t)(t + 1) * kstep;
;             const char* a2 = last ? nA : cA + (size_t)(t + 2) * kstep; const char* b2 = last ? nB : cB + (size_t)(t + 2) * kstep;
;             const char* a3 = a2 + kstep; const char* b3 = b2 + kstep;
;             if (last && has_next) S.a_ready(nxt);
;             if constexpr (SP2) {
;             PG8_LDB(B0, 0, 0); PG8_LDB(B1, 0, 1); PG8_SCHED; PG8_LDA(At, 0, 0); PG8_STAGE(PG8_SA(1, 1), a1 + hstepA, voffA);
;             PG8_WAIT_V(8); PG8_WAIT_L(0); PG8_BAR; PG8_MMA(0, 0, At, B0); PG8_MMA(0, 1, At, B1); PG8_BAR; PG8_SCHED;
;             PG8_LDA(At, 0, 1); PG8_STAGE(PG8_SB(0, 0), b2, voffB); PG8_STAGE(PG8_SB(0, 1), b2 + hstepB, voffB); PG8_STAGE(PG8_SA(0, 0), a2, voffA);
;     ...
;             PG8_LDA(At, 1, 1); PG8_STAGE(PG8_SB(1, 0), b3, voffB); PG8_STAGE(PG8_SB(1, 1), b3 + hstepB, voffB); PG8_STAGE(PG8_SA(1, 0), a3, voffA);
;             PG8_WAIT_V(8); PG8_WAIT_L(0); PG8_BAR; PG8_MMA(1, 0, At, B0); PG8_MMA(1, 1, At, B1); PG8_BAR; PG8_SCHED;
	s_add_i32 s40, s85, s34
	v_lshl_add_u64 v[194:195], v[194:195], 0, s[60:61]
	s_mov_b32 m0, s40
	ds_read_b128 v[162:165], v230 offset:49152
	ds_read_b128 v[166:169], v230 offset:50176
	ds_read_b128 v[170:173], v230 offset:51200
	ds_read_b128 v[174:177], v230 offset:52224
	ds_read_b128 v[178:181], v230 offset:53248
	ds_read_b128 v[182:185], v230 offset:54272
	ds_read_b128 v[186:189], v230 offset:55296
	ds_read_b128 v[190:193], v230 offset:56320
	global_load_lds_dwordx4 v[194:195], off
	s_add_i32 m0, s40, 0x2000
	s_add_u32 s30, s30, 0x20080
	v_lshl_add_u64 v[194:195], v[196:197], 0, s[60:61]
	s_addc_u32 s31, s31, 0
	s_add_i32 s40, s89, s34
	global_load_lds_dwordx4 v[194:195], off
	s_mov_b32 m0, s40
	s_nop 0
	global_load_lds_dwordx4 v214, s[30:31]
	s_add_i32 m0, s40, 0x2000
	s_nop 0
	global_load_lds_dwordx4 v210, s[30:31]
	v_lshl_add_u64 v[194:195], v[198:199], 0, s[60:61]
	s_mov_b32 m0, s46
	s_nop 0
	global_load_lds_dwordx4 v[194:195], off
	v_lshl_add_u64 v[194:195], v[200:201], 0, s[60:61]
	s_mov_b32 m0, s47
	s_nop 0
	global_load_lds_dwordx4 v[194:195], off
	s_waitcnt vmcnt(8)
	s_waitcnt lgkmcnt(0)
	s_barrier
	s_waitcnt lgkmcnt(0)
	v_mfma_f32_16x16x32_bf16 v[62:65], v[106:109], v[162:165], v[62:65]
	v_mfma_f32_16x16x32_bf16 v[58:61], v[114:117], v[162:165], v[58:61]
	v_mfma_f32_16x16x32_bf16 v[46:49], v[106:109], v[170:173], v[46:49]
	v_mfma_f32_16x16x32_bf16 v[42:45], v[114:117], v[170:173], v[42:45]
	v_mfma_f32_16x16x32_bf16 v[30:33], v[106:109], v[178:181], v[30:33]
	v_mfma_f32_16x16x32_bf16 v[26:29], v[114:117], v[178:181], v[26:29]
	v_mfma_f32_16x16x32_bf16 v[14:17], v[106:109], v[186:189], v[14:17]
	v_mfma_f32_16x16x32_bf16 v[10:13], v[114:117], v[186:189], v[10:13]
	v_mfma_f32_16x16x32_bf16 v[62:65], v[110:113], v[166:169], v[62:65]
	v_mfma_f32_16x16x32_bf16 v[58:61], v[118:121], v[166:169], v[58:61]
	v_mfma_f32_16x16x32_bf16 v[46:49], v[110:113], v[174:177], v[46:49]
	v_mfma_f32_16x16x32_bf16 v[42:45], v[118:121], v[174:177], v[42:45]
	v_mfma_f32_16x16x32_bf16 v[30:33], v[110:113], v[182:185], v[30:33]
	v_mfma_f32_16x16x32_bf16 v[26:29], v[118:121], v[182:185], v[26:29]
	v_mfma_f32_16x16x32_bf16 v[14:17], v[110:113], v[190:193], v[14:17]
	v_mfma_f32_16x16x32_bf16 v[10:13], v[118:121], v[190:193], v[10:13]
	v_mfma_f32_16x16x32_bf16 v[54:57], v[122:125], v[162:165], v[54:57]
	v_mfma_f32_16x16x32_bf16 v[50:53], v[142:145], v[162:165], v[50:53]
	v_mfma_f32_16x16x32_bf16 v[38:41], v[122:125], v[170:173], v[38:41]
	v_mfma_f32_16x16x32_bf16 v[34:37], v[142:145], v[170:173], v[34:37]
	v_mfma_f32_16x16x32_bf16 v[22:25], v[122:125], v[178:181], v[22:25]
	v_mfma_f32_16x16x32_bf16 v[18:21], v[142:145], v[178:181], v[18:21]
	v_mfma_f32_16x16x32_bf16 v[6:9], v[122:125], v[186:189], v[6:9]
	v_mfma_f32_16x16x32_bf16 v[2:5], v[142:145], v[186:189], v[2:5]
	v_mfma_f32_16x16x32_bf16 v[54:57], v[126:129], v[166:169], v[54:57]
	v_mfma_f32_16x16x32_bf16 v[50:53], v[150:153], v[166:169], v[50:53]
	v_mfma_f32_16x16x32_bf16 v[38:41], v[126:129], v[174:177], v[38:41]
	v_mfma_f32_16x16x32_bf16 v[34:37], v[150:153], v[174:177], v[34:37]
	v_mfma_f32_16x16x32_bf16 v[22:25], v[126:129], v[182:185], v[22:25]
	v_mfma_f32_16x16x32_bf16 v[18:21], v[150:153], v[182:185], v[18:21]
	v_mfma_f32_16x16x32_bf16 v[6:9], v[126:129], v[190:193], v[6:9]
	v_mfma_f32_16x16x32_bf16 v[2:5], v[150:153], v[190:193], v[2:5]
	s_barrier
	s_add_i32 s84, s84, 2
	s_add_u32 s4, s4, 0x100
	s_addc_u32 s5, s5, 0
	s_add_u32 s29, s29, 0x100
	s_addc_u32 s81, s81, 0
	s_cmp_gt_u32 s84, 5
.LBB0_314:
	s_add_u32 s30, s4, 0xfff80080
	s_addc_u32 s31, s5, -1
	s_add_i32 s85, 0, 0x10000
	s_cmp_eq_u32 s84, 4
	s_cselect_b32 s41, s91, s31
	s_cselect_b32 s40, s90, s30
	s_cselect_b32 s31, s2, s81
	s_cselect_b32 s30, s3, s29
	s_add_i32 s89, 0, 0x14000
	v_add_u32_e32 v118, s85, v229
	v_add_u32_e32 v150, s89, v229
	ds_read_b128 v[106:109], v118
	ds_read_b128 v[110:113], v118 offset:1024
	ds_read_b128 v[114:117], v118 offset:2048
	ds_read_b128 v[118:121], v118 offset:3072
	ds_read_b128 v[122:125], v150
	ds_read_b128 v[126:129], v150 offset:1024
	ds_read_b128 v[142:145], v150 offset:2048
	ds_read_b128 v[150:153], v150 offset:3072
	s_add_i32 m0, s35, 0xc000
	ds_read_b128 v[162:165], v230
	ds_read_b128 v[166:169], v230 offset:1024
	ds_read_b128 v[170:173], v230 offset:2048
	ds_read_b128 v[174:177], v230 offset:3072
	ds_read_b128 v[178:181], v230 offset:4096
	ds_read_b128 v[182:185], v230 offset:5120
	ds_read_b128 v[186:189], v230 offset:6144
	ds_read_b128 v[190:193], v230 offset:7168
	global_load_lds_dwordx4 v218, s[4:5]
	s_add_i32 m0, s35, 0xe000
	s_nop 0
	global_load_lds_dwordx4 v220, s[4:5]
	s_waitcnt vmcnt(8)
	s_waitcnt lgkmcnt(0)
	s_barrier
; #define PG8_STAGE(bufoff, gbase, voff) do { _Pragma("unroll") for (int _i = 0; _i < 2; ++_i) \
;         __builtin_amdgcn_global_load_lds((const unsigned*)((const char*)(gbase) + (voff)[_i]), (PG8_LAS unsigned*)(lds + (bufoff) + ldsw + _i * 8192), 16, 0, 0); } while (0)
; #define PG8_LDA(dst, b, h) do { _Pragma("unroll") for (int m = 0; m < 4; ++m) _Pragma("unroll") for (int k = 0; k < 2; ++k) dst[m][k] = *(const PG8_LAS bf16x8*)(lds + PG8_SA(b, h) + aoff + m * 2048 + k * 1024); } while (0)
; #define PG8_LDB(dst, b, h) do { _Pragma("unroll") for (int n = 0; n < 2; ++n) _Pragma("unroll") for (int k = 0; k < 2; ++k) dst[n][k] = *(const PG8_LAS bf16x8*)(lds + PG8_SB(b, h) + boff + n * 2048 + k * 1024); } while (0)
; #define PG8_MMA(ai, bj, At, Bt) do { __builtin_amdgcn_s_setprio(1); _Pragma("unroll") for (int m = 0; m < 4; ++m) _Pragma("unroll") for (int n = 0; n < 2; ++n) _Pragma("unroll") for (int k = 0; k < 2; ++k) \
;         acc[ai][bj][m][n] = __builtin_amdgcn_mfma_f32_16x16x32_bf16(Bt[n][k], At[m][k], acc[ai][bj][m][n], 0, 0, 0); __builtin_amdgcn_s_setprio(0); } while (0)
; #define PG8_WAIT_V(n) asm volatile("s_waitcnt vmcnt(" #n ")" ::: "memory")
; #define PG8_WAIT_L(n) asm volatile("s_waitcnt lgkmcnt(" #n ")" ::: "memory")
; #define PG8_BAR __builtin_amdgcn_s_barrier()
; #define PG8_SCHED __builtin_amdgcn_sched_barrier(0)
; template <class Epi, class Sched, bool ALIGN_EPI = false, bool SP2 = false>
; __device__ __forceinline__ void gemm_phase(PG8_LAS unsigned char* lds, const Gemm g, const Sched& S, const Epi& E, int wave_s) {
;     ...
;             PG8_LDB(B0, 0, 0); PG8_LDB(B1, 0, 1); PG8_SCHED; PG8_LDA(At, 0, 0); PG8_STAGE(PG8_SA(1, 1), a1 + hstepA, voffA);
;             PG8_WAIT_V(8); PG8_WAIT_L(0); PG8_BAR; PG8_MMA(0, 0, At, B0); PG8_MMA(0, 1, At, B1); PG8_BAR; PG8_SCHED;
;             PG8_LDA(At, 0, 1); PG8_STAGE(PG8_SB(0, 0), b2, voffB); PG8_STAGE(PG8_SB(0, 1), b2 + hstepB, voffB); PG8_STAGE(PG8_SA(0, 0), a2, voffA);
;             PG8_WAIT_V(8); PG8_WAIT_L(0); PG8_BAR; PG8_MMA(1, 0, At, B0); PG8_MMA(1, 1, At, B1); PG8_BAR; PG8_SCHED;
;             PG8_LDB(B0, 1, 0); PG8_LDB(B1, 1, 1); PG8_SCHED; PG8_LDA(At, 1, 0); PG8_STAGE(PG8_SA(0, 1), a2 + hstepA, voffA);
;             PG8_WAIT_V(8); PG8_WAIT_L(0); PG8_BAR; PG8_MMA(0, 0, At, B0); PG8_MMA(0, 1, At, B1); PG8_BAR; PG8_SCHED;
	s_waitcnt lgkmcnt(0)
	v_mfma_f32_16x16x32_bf16 v[158:161], v[106:109], v[162:165], v[158:161]
	v_mfma_f32_16x16x32_bf16 v[154:157], v[114:117], v[162:165], v[154:157]
	v_mfma_f32_16x16x32_bf16 v[134:137], v[106:109], v[170:173], v[134:137]
	v_mfma_f32_16x16x32_bf16 v[130:133], v[114:117], v[170:173], v[130:133]
	v_mfma_f32_16x16x32_bf16 v[94:97], v[106:109], v[178:181], v[94:97]
	v_mfma_f32_16x16x32_bf16 v[90:93], v[114:117], v[178:181], v[90:93]
	v_mfma_f32_16x16x32_bf16 v[78:81], v[106:109], v[186:189], v[78:81]
	v_mfma_f32_16x16x32_bf16 v[74:77], v[114:117], v[186:189], v[74:77]
	v_mfma_f32_16x16x32_bf16 v[158:161], v[110:113], v[166:169], v[158:161]
	v_mfma_f32_16x16x32_bf16 v[154:157], v[118:121], v[166:169], v[154:157]
	v_mfma_f32_16x16x32_bf16 v[134:137], v[110:113], v[174:177], v[134:137]
	v_mfma_f32_16x16x32_bf16 v[130:133], v[118:121], v[174:177], v[130:133]
	v_mfma_f32_16x16x32_bf16 v[94:97], v[110:113], v[182:185], v[94:97]
	v_mfma_f32_16x16x32_bf16 v[90:93], v[118:121], v[182:185], v[90:93]
	v_mfma_f32_16x16x32_bf16 v[78:81], v[110:113], v[190:193], v[78:81]
	v_mfma_f32_16x16x32_bf16 v[74:77], v[118:121], v[190:193], v[74:77]
	v_mfma_f32_16x16x32_bf16 v[146:149], v[122:125], v[162:165], v[146:149]
	v_mfma_f32_16x16x32_bf16 v[138:141], v[142:145], v[162:165], v[138:141]
	v_mfma_f32_16x16x32_bf16 v[102:105], v[122:125], v[170:173], v[102:105]
	v_mfma_f32_16x16x32_bf16 v[98:101], v[142:145], v[170:173], v[98:101]
	v_mfma_f32_16x16x32_bf16 v[86:89], v[122:125], v[178:181], v[86:89]
	v_mfma_f32_16x16x32_bf16 v[82:85], v[142:145], v[178:181], v[82:85]
	v_mfma_f32_16x16x32_bf16 v[70:73], v[122:125], v[186:189], v[70:73]
	v_mfma_f32_16x16x32_bf16 v[66:69], v[142:145], v[186:189], v[66:69]
	v_mfma_f32_16x16x32_bf16 v[146:149], v[126:129], v[166:169], v[146:149]
	v_mfma_f32_16x16x32_bf16 v[138:141], v[150:153], v[166:169], v[138:141]
	v_mfma_f32_16x16x32_bf16 v[102:105], v[126:129], v[174:177], v[102:105]
	v_mfma_f32_16x16x32_bf16 v[98:101], v[150:153], v[174:177], v[98:101]
	v_mfma_f32_16x16x32_bf16 v[86:89], v[126:129], v[182:185], v[86:89]
	v_mfma_f32_16x16x32_bf16 v[82:85], v[150:153], v[182:185], v[82:85]
	v_mfma_f32_16x16x32_bf16 v[70:73], v[126:129], v[190:193], v[70:73]
	v_mfma_f32_16x16x32_bf16 v[66:69], v[150:153], v[190:193], v[66:69]
	s_barrier
	s_add_i32 s85, s85, s34
	v_lshl_add_u64 v[194:195], s[30:31], 0, v[214:215]
	s_mov_b32 m0, s85
	ds_read_b128 v[162:165], v230 offset:16384
	ds_read_b128 v[166:169], v230 offset:17408
	ds_read_b128 v[170:173], v230 offset:18432
	ds_read_b128 v[174:177], v230 offset:19456
	ds_read_b128 v[178:181], v230 offset:20480
	ds_read_b128 v[182:185], v230 offset:21504
	ds_read_b128 v[186:189], v230 offset:22528
	ds_read_b128 v[190:193], v230 offset:23552
	global_load_lds_dwordx4 v[194:195], off
	s_add_i32 m0, s85, 0x2000
	s_add_u32 s94, s30, 0x20000
	v_lshl_add_u64 v[196:197], s[30:31], 0, v[210:211]
	s_addc_u32 s95, s31, 0
	s_add_i32 s85, s89, s34
	global_load_lds_dwordx4 v[196:197], off
	s_mov_b32 m0, s85
	v_lshl_add_u64 v[200:201], s[40:41], 0, v[212:213]
	global_load_lds_dwordx4 v214, s[94:95]
	s_add_i32 m0, s85, 0x2000
	s_nop 0
	global_load_lds_dwordx4 v210, s[94:95]
	v_lshl_add_u64 v[198:199], s[40:41], 0, v[216:217]
	s_mov_b32 m0, s35
	s_nop 0
	global_load_lds_dwordx4 v[198:199], off
	s_mov_b32 m0, s36
	s_nop 0
	global_load_lds_dwordx4 v[200:201], off
	s_waitcnt vmcnt(8)
	s_waitcnt lgkmcnt(0)
	s_barrier
	s_waitcnt lgkmcnt(0)
	v_mfma_f32_16x16x32_bf16 v[62:65], v[106:109], v[162:165], v[62:65]
	v_mfma_f32_16x16x32_bf16 v[58:61], v[114:117], v[162:165], v[58:61]
	v_mfma_f32_16x16x32_bf16 v[46:49], v[106:109], v[170:173], v[46:49]
	v_mfma_f32_16x16x32_bf16 v[42:45], v[114:117], v[170:173], v[42:45]
	v_mfma_f32_16x16x32_bf16 v[30:33], v[106:109], v[178:181], v[30:33]
	v_mfma_f32_16x16x32_bf16 v[26:29], v[114:117], v[178:181], v[26:29]
	v_mfma_f32_16x16x32_bf16 v[14:17], v[106:109], v[186:189], v[14:17]
	v_mfma_f32_16x16x32_bf16 v[10:13], v[114:117], v[186:189], v[10:13]
	v_mfma_f32_16x16x32_bf16 v[62:65], v[110:113], v[166:169], v[62:65]
	v_mfma_f32_16x16x32_bf16 v[58:61], v[118:121], v[166:169], v[58:61]
	v_mfma_f32_16x16x32_bf16 v[46:49], v[110:113], v[174:177], v[46:49]
	v_mfma_f32_16x16x32_bf16 v[42:45], v[118:121], v[174:177], v[42:45]
	v_mfma_f32_16x16x32_bf16 v[30:33], v[110:113], v[182:185], v[30:33]
	v_mfma_f32_16x16x32_bf16 v[26:29], v[118:121], v[182:185], v[26:29]
	v_mfma_f32_16x16x32_bf16 v[14:17], v[110:113], v[190:193], v[14:17]
	v_mfma_f32_16x16x32_bf16 v[10:13], v[118:121], v[190:193], v[10:13]
	v_mfma_f32_16x16x32_bf16 v[54:57], v[122:125], v[162:165], v[54:57]
	v_mfma_f32_16x16x32_bf16 v[50:53], v[142:145], v[162:165], v[50:53]
	v_mfma_f32_16x16x32_bf16 v[38:41], v[122:125], v[170:173], v[38:41]
	v_mfma_f32_16x16x32_bf16 v[34:37], v[142:145], v[170:173], v[34:37]
	v_mfma_f32_16x16x32_bf16 v[22:25], v[122:125], v[178:181], v[22:25]
	v_mfma_f32_16x16x32_bf16 v[18:21], v[142:145], v[178:181], v[18:21]
	v_mfma_f32_16x16x32_bf16 v[6:9], v[122:125], v[186:189], v[6:9]
	v_mfma_f32_16x16x32_bf16 v[2:5], v[142:145], v[186:189], v[2:5]
	v_mfma_f32_16x16x32_bf16 v[54:57], v[126:129], v[166:169], v[54:57]
	v_mfma_f32_16x16x32_bf16 v[50:53], v[150:153], v[166:169], v[50:53]
	v_mfma_f32_16x16x32_bf16 v[38:41], v[126:129], v[174:177], v[38:41]
	v_mfma_f32_16x16x32_bf16 v[34:37], v[150:153], v[174:177], v[34:37]
	v_mfma_f32_16x16x32_bf16 v[22:25], v[126:129], v[182:185], v[22:25]
	v_mfma_f32_16x16x32_bf16 v[18:21], v[150:153], v[182:185], v[18:21]
	v_mfma_f32_16x16x32_bf16 v[6:9], v[126:129], v[190:193], v[6:9]
	v_mfma_f32_16x16x32_bf16 v[2:5], v[150:153], v[190:193], v[2:5]
	s_barrier
; #define PG8_STAGE(bufoff, gbase, voff) do { _Pragma("unroll") for (int _i = 0; _i < 2; ++_i) \
;         __builtin_amdgcn_global_load_lds((const unsigned*)((const char*)(gbase) + (voff)[_i]), (PG8_LAS unsigned*)(lds + (bufoff) + ldsw + _i * 8192), 16, 0, 0); } while (0)
; #define PG8_LDA(dst, b, h) do { _Pragma("unroll") for (int m = 0; m < 4; ++m) _Pragma("unroll") for (int k = 0; k < 2; ++k) dst[m][k] = *(const PG8_LAS bf16x8*)(lds + PG8_SA(b, h) + aoff + m * 2048 + k * 1024); } while (0)
; #define PG8_LDB(dst, b, h) do { _Pragma("unroll") for (int n = 0; n < 2; ++n) _Pragma("unroll") for (int k = 0; k < 2; ++k) dst[n][k] = *(const PG8_LAS bf16x8*)(lds + PG8_SB(b, h) + boff + n * 2048 + k * 1024); } while (0)
; #define PG8_MMA(ai, bj, At, Bt) do { __builtin_amdgcn_s_setprio(1); _Pragma("unroll") for (int m = 0; m < 4; ++m) _Pragma("unroll") for (int n = 0; n < 2; ++n) _Pragma("unroll") for (int k = 0; k < 2; ++k) \
;         acc[ai][bj][m][n] = __builtin_amdgcn_mfma_f32_16x16x32_bf16(Bt[n][k], At[m][k], acc[ai][bj][m][n], 0, 0, 0); __builtin_amdgcn_s_setprio(0); } while (0)
; #define PG8_WAIT_V(n) asm volatile("s_waitcnt vmcnt(" #n ")" ::: "memory")
; #define PG8_WAIT_L(n) asm volatile("s_waitcnt lgkmcnt(" #n ")" ::: "memory")
; #define PG8_BAR __builtin_amdgcn_s_barrier()
; #define PG8_SCHED __builtin_amdgcn_sched_barrier(0)
; template <class Epi, class Sched, bool ALIGN_EPI = false, bool SP2 = false>
; __device__ __forceinline__ void gemm_phase(PG8_LAS unsigned char* lds, const Gemm g, const Sched& S, const Epi& E, int wave_s) {
;     ...
;             PG8_LDA(At, 0, 1); PG8_STAGE(PG8_SB(0, 0), b2, voffB); PG8_STAGE(PG8_SB(0, 1), b2 + hstepB, voffB); PG8_STAGE(PG8_SA(0, 0), a2, voffA);
;             PG8_WAIT_V(8); PG8_WAIT_L(0); PG8_BAR; PG8_MMA(1, 0, At, B0); PG8_MMA(1, 1, At, B1); PG8_BAR; PG8_SCHED;
;             PG8_LDB(B0, 1, 0); PG8_LDB(B1, 1, 1); PG8_SCHED; PG8_LDA(At, 1, 0); PG8_STAGE(PG8_SA(0, 1), a2 + hstepA, voffA);
;             PG8_WAIT_V(8); PG8_WAIT_L(0); PG8_BAR; PG8_MMA(0, 0, At, B0); PG8_MMA(0, 1, At, B1); PG8_BAR; PG8_SCHED;
;             PG8_LDA(At, 1, 1); PG8_STAGE(PG8_SB(1, 0), b3, voffB); PG8_STAGE(PG8_SB(1, 1), b3 + hstepB, voffB); PG8_STAGE(PG8_SA(1, 0), a3, voffA);
;             PG8_WAIT_V(8); PG8_WAIT_L(0); PG8_BAR; PG8_MMA(1, 0, At, B0); PG8_MMA(1, 1, At, B1); PG8_BAR; PG8_SCHED;
	s_add_i32 s85, 0, 0x18000
	s_add_i32 s89, 0, 0x1c000
	v_add_u32_e32 v118, s85, v229
	v_add_u32_e32 v150, s89, v229
	ds_read_b128 v[106:109], v118
	ds_read_b128 v[110:113], v118 offset:1024
	ds_read_b128 v[114:117], v118 offset:2048
	ds_read_b128 v[118:121], v118 offset:3072
	ds_read_b128 v[122:125], v150
	ds_read_b128 v[126:129], v150 offset:1024
	ds_read_b128 v[142:145], v150 offset:2048
	ds_read_b128 v[150:153], v150 offset:3072
	s_add_u32 s40, s40, 0x80000
	s_addc_u32 s41, s41, 0
	s_mov_b32 m0, s37
	ds_read_b128 v[162:165], v230 offset:32768
	ds_read_b128 v[166:169], v230 offset:33792
	ds_read_b128 v[170:173], v230 offset:34816
	ds_read_b128 v[174:177], v230 offset:35840
	ds_read_b128 v[178:181], v230 offset:36864
	ds_read_b128 v[182:185], v230 offset:37888
	ds_read_b128 v[186:189], v230 offset:38912
	ds_read_b128 v[190:193], v230 offset:39936
	global_load_lds_dwordx4 v216, s[40:41]
	v_lshl_add_u64 v[202:203], s[40:41], 0, v[212:213]
	s_mov_b32 m0, s42
	s_nop 0
	global_load_lds_dwordx4 v[202:203], off
	s_waitcnt vmcnt(8)
	s_waitcnt lgkmcnt(0)
	s_barrier
	s_waitcnt lgkmcnt(0)
	v_mfma_f32_16x16x32_bf16 v[158:161], v[106:109], v[162:165], v[158:161]
	v_mfma_f32_16x16x32_bf16 v[154:157], v[114:117], v[162:165], v[154:157]
	v_mfma_f32_16x16x32_bf16 v[134:137], v[106:109], v[170:173], v[134:137]
	v_mfma_f32_16x16x32_bf16 v[130:133], v[114:117], v[170:173], v[130:133]
	v_mfma_f32_16x16x32_bf16 v[94:97], v[106:109], v[178:181], v[94:97]
	v_mfma_f32_16x16x32_bf16 v[90:93], v[114:117], v[178:181], v[90:93]
	v_mfma_f32_16x16x32_bf16 v[78:81], v[106:109], v[186:189], v[78:81]
	v_mfma_f32_16x16x32_bf16 v[74:77], v[114:117], v[186:189], v[74:77]
	v_mfma_f32_16x16x32_bf16 v[158:161], v[110:113], v[166:169], v[158:161]
	v_mfma_f32_16x16x32_bf16 v[154:157], v[118:121], v[166:169], v[154:157]
	v_mfma_f32_16x16x32_bf16 v[134:137], v[110:113], v[174:177], v[134:137]
	v_mfma_f32_16x16x32_bf16 v[130:133], v[118:121], v[174:177], v[130:133]
	v_mfma_f32_16x16x32_bf16 v[94:97], v[110:113], v[182:185], v[94:97]
	v_mfma_f32_16x16x32_bf16 v[90:93], v[118:121], v[182:185], v[90:93]
	v_mfma_f32_16x16x32_bf16 v[78:81], v[110:113], v[190:193], v[78:81]
	v_mfma_f32_16x16x32_bf16 v[74:77], v[118:121], v[190:193], v[74:77]
	v_mfma_f32_16x16x32_bf16 v[146:149], v[122:125], v[162:165], v[146:149]
	v_mfma_f32_16x16x32_bf16 v[138:141], v[142:145], v[162:165], v[138:141]
	v_mfma_f32_16x16x32_bf16 v[102:105], v[122:125], v[170:173], v[102:105]
	v_mfma_f32_16x16x32_bf16 v[98:101], v[142:145], v[170:173], v[98:101]
	v_mfma_f32_16x16x32_bf16 v[86:89], v[122:125], v[178:181], v[86:89]
	v_mfma_f32_16x16x32_bf16 v[82:85], v[142:145], v[178:181], v[82:85]
	v_mfma_f32_16x16x32_bf16 v[70:73], v[122:125], v[186:189], v[70:73]
	v_mfma_f32_16x16x32_bf16 v[66:69], v[142:145], v[186:189], v[66:69]
	v_mfma_f32_16x16x32_bf16 v[146:149], v[126:129], v[166:169], v[146:149]
	v_mfma_f32_16x16x32_bf16 v[138:141], v[150:153], v[166:169], v[138:141]
	v_mfma_f32_16x16x32_bf16 v[102:105], v[126:129], v[174:177], v[102:105]
	v_mfma_f32_16x16x32_bf16 v[98:101], v[150:153], v[174:177], v[98:101]
	v_mfma_f32_16x16x32_bf16 v[86:89], v[126:129], v[182:185], v[86:89]
	v_mfma_f32_16x16x32_bf16 v[82:85], v[150:153], v[182:185], v[82:85]
	v_mfma_f32_16x16x32_bf16 v[70:73], v[126:129], v[190:193], v[70:73]
	v_mfma_f32_16x16x32_bf16 v[66:69], v[150:153], v[190:193], v[66:69]
	s_barrier
	s_add_i32 s40, s85, s34
	v_lshl_add_u64 v[194:195], v[194:195], 0, s[60:61]
	s_mov_b32 m0, s40
	ds_read_b128 v[162:165], v230 offset:49152
	ds_read_b128 v[166:169], v230 offset:50176
	ds_read_b128 v[170:173], v230 offset:51200
	ds_read_b128 v[174:177], v230 offset:52224
	ds_read_b128 v[178:181], v230 offset:53248
	ds_read_b128 v[182:185], v230 offset:54272
	ds_read_b128 v[186:189], v230 offset:55296
	ds_read_b128 v[190:193], v230 offset:56320
	global_load_lds_dwordx4 v[194:195], off
	s_add_i32 m0, s40, 0x2000
	s_add_u32 s30, s30, 0x20080
	v_lshl_add_u64 v[194:195], v[196:197], 0, s[60:61]
	s_addc_u32 s31, s31, 0
	s_add_i32 s40, s89, s34
	global_load_lds_dwordx4 v[194:195], off
	s_mov_b32 m0, s40
	s_nop 0
	global_load_lds_dwordx4 v214, s[30:31]
	s_add_i32 m0, s40, 0x2000
	s_nop 0
	global_load_lds_dwordx4 v210, s[30:31]
	v_lshl_add_u64 v[194:195], v[198:199], 0, s[60:61]
	s_mov_b32 m0, s46
	s_nop 0
	global_load_lds_dwordx4 v[194:195], off
	v_lshl_add_u64 v[194:195], v[200:201], 0, s[60:61]
	s_mov_b32 m0, s47
	s_nop 0
	global_load_lds_dwordx4 v[194:195], off
	s_waitcnt vmcnt(8)
	s_waitcnt lgkmcnt(0)
	s_barrier
	s_waitcnt lgkmcnt(0)
	v_mfma_f32_16x16x32_bf16 v[62:65], v[106:109], v[162:165], v[62:65]
	v_mfma_f32_16x16x32_bf16 v[58:61], v[114:117], v[162:165], v[58:61]
	v_mfma_f32_16x16x32_bf16 v[46:49], v[106:109], v[170:173], v[46:49]
	v_mfma_f32_16x16x32_bf16 v[42:45], v[114:117], v[170:173], v[42:45]
	v_mfma_f32_16x16x32_bf16 v[30:33], v[106:109], v[178:181], v[30:33]
	v_mfma_f32_16x16x32_bf16 v[26:29], v[114:117], v[178:181], v[26:29]
	v_mfma_f32_16x16x32_bf16 v[14:17], v[106:109], v[186:189], v[14:17]
	v_mfma_f32_16x16x32_bf16 v[10:13], v[114:117], v[186:189], v[10:13]
	v_mfma_f32_16x16x32_bf16 v[62:65], v[110:113], v[166:169], v[62:65]
	v_mfma_f32_16x16x32_bf16 v[58:61], v[118:121], v[166:169], v[58:61]
	v_mfma_f32_16x16x32_bf16 v[46:49], v[110:113], v[174:177], v[46:49]
	v_mfma_f32_16x16x32_bf16 v[42:45], v[118:121], v[174:177], v[42:45]
	v_mfma_f32_16x16x32_bf16 v[30:33], v[110:113], v[182:185], v[30:33]
	v_mfma_f32_16x16x32_bf16 v[26:29], v[118:121], v[182:185], v[26:29]
	v_mfma_f32_16x16x32_bf16 v[14:17], v[110:113], v[190:193], v[14:17]
	v_mfma_f32_16x16x32_bf16 v[10:13], v[118:121], v[190:193], v[10:13]
	v_mfma_f32_16x16x32_bf16 v[54:57], v[122:125], v[162:165], v[54:57]
	v_mfma_f32_16x16x32_bf16 v[50:53], v[142:145], v[162:165], v[50:53]
	v_mfma_f32_16x16x32_bf16 v[38:41], v[122:125], v[170:173], v[38:41]
	v_mfma_f32_16x16x32_bf16 v[34:37], v[142:145], v[170:173], v[34:37]
	v_mfma_f32_16x16x32_bf16 v[22:25], v[122:125], v[178:181], v[22:25]
	v_mfma_f32_16x16x32_bf16 v[18:21], v[142:145], v[178:181], v[18:21]
	v_mfma_f32_16x16x32_bf16 v[6:9], v[122:125], v[186:189], v[6:9]
	v_mfma_f32_16x16x32_bf16 v[2:5], v[142:145], v[186:189], v[2:5]
	v_mfma_f32_16x16x32_bf16 v[54:57], v[126:129], v[166:169], v[54:57]
	v_mfma_f32_16x16x32_bf16 v[50:53], v[150:153], v[166:169], v[50:53]
	v_mfma_f32_16x16x32_bf16 v[38:41], v[126:129], v[174:177], v[38:41]
	v_mfma_f32_16x16x32_bf16 v[34:37], v[150:153], v[174:177], v[34:37]
	v_mfma_f32_16x16x32_bf16 v[22:25], v[126:129], v[182:185], v[22:25]
	v_mfma_f32_16x16x32_bf16 v[18:21], v[150:153], v[182:185], v[18:21]
	v_mfma_f32_16x16x32_bf16 v[6:9], v[126:129], v[190:193], v[6:9]
	v_mfma_f32_16x16x32_bf16 v[2:5], v[150:153], v[190:193], v[2:5]
	s_barrier
	s_add_i32 s84, s84, 2
	s_add_u32 s4, s4, 0x100
	s_addc_u32 s5, s5, 0
	s_add_u32 s29, s29, 0x100
	s_addc_u32 s81, s81, 0
	s_cmp_gt_u32 s84, 5
	s_cbranch_scc0 .LBB0_314
	s_and_b64 vcc, exec, s[20:21]
	s_cbranch_vccz .LBB0_317
	s_barrier

; #define PG8_STAGE(bufoff, gbase, voff) do { _Pragma("unroll") for (int _i = 0; _i < 2; ++_i) \
;         __builtin_amdgcn_global_load_lds((const unsigned*)((const char*)(gbase) + (voff)[_i]), (PG8_LAS unsigned*)(lds + (bufoff) + ldsw + _i * 8192), 16, 0, 0); } while (0)
; #define PG8_LDA(dst, b, h) do { _Pragma("unroll") for (int m = 0; m < 4; ++m) _Pragma("unroll") for (int k = 0; k < 2; ++k) dst[m][k] = *(const PG8_LAS bf16x8*)(lds + PG8_SA(b, h) + aoff + m * 2048 + k * 1024); } while (0)
; #define PG8_LDB(dst, b, h) do { _Pragma("unroll") for (int n = 0; n < 2; ++n) _Pragma("unroll") for (int k = 0; k < 2; ++k) dst[n][k] = *(const PG8_LAS bf16x8*)(lds + PG8_SB(b, h) + boff + n * 2048 + k * 1024); } while (0)
; #define PG8_WAIT_V(n) asm volatile("s_waitcnt vmcnt(" #n ")" ::: "memory")
; #define PG8_WAIT_L(n) asm volatile("s_waitcnt lgkmcnt(" #n ")" ::: "memory")
; #define PG8_BAR __builtin_amdgcn_s_barrier()
; #define PG8_SCHED __builtin_amdgcn_sched_barrier(0)
; template <class Epi, class Sched, bool ALIGN_EPI = false, bool SP2 = false>
; __device__ __forceinline__ void gemm_phase(PG8_LAS unsigned char* lds, const Gemm g, const Sched& S, const Epi& E, int wave_s) {
;     ...
;         const bool has_next = S.next(ui + 1, nxt);
;         const char* nA = has_next ? (const char*)g.A + (size_t)nxt.pm * tstepA + (size_t)(nxt.pn / g.npg) * (size_t)(K * 2) : cA; const char* nB = has_next ? (const char*)g.Bt + (size_t)nxt.pn * tstepB : cB;
;         for (int t = 0; t < nt; t += 2) {
;             const bool last = (t == nt - 2);
;             const char* a1 = cA + (size_t)(t + 1) * kstep;
;             const char* a2 = last ? nA : cA + (size_t)(t + 2) * kstep; const char* b2 = last ? nB : cB + (size_t)(t + 2) * kstep;
;             const char* a3 = a2 + kstep; const char* b3 = b2 + kstep;
;             if (last && has_next) S.a_ready(nxt);
;             if constexpr (SP2) {
;             PG8_LDB(B0, 0, 0); PG8_LDB(B1, 0, 1); PG8_SCHED; PG8_LDA(At, 0, 0); PG8_STAGE(PG8_SA(1, 1), a1 + hstepA, voffA);
;             PG8_WAIT_V(8); PG8_WAIT_L(0); PG8_BAR; PG8_MMA(0, 0, At, B0); PG8_MMA(0, 1, At, B1); PG8_BAR; PG8_SCHED;
;             PG8_LDA(At, 0, 1); PG8_STAGE(PG8_SB(0, 0), b2, voffB); PG8_STAGE(PG8_SB(0, 1), b2 + hstepB, voffB); PG8_STAGE(PG8_SA(0, 0), a2, voffA);
.LBB0_411:
	s_ashr_i32 s15, s14, 31
	s_lshl_b64 s[2:3], s[14:15], 20
	s_add_u32 s28, s22, s2
	s_addc_u32 s29, s23, s3
	s_and_b64 s[2:3], s[4:5], exec
	s_cselect_b32 s2, s29, s31
	s_cselect_b32 s3, s28, s30
	s_add_u32 s4, s40, 0x80080
	s_addc_u32 s5, s41, 0
	s_add_u32 s15, s30, 0x100
	s_addc_u32 s21, s31, 0
	s_mov_b32 s94, -2
	s_add_u32 s30, s4, 0xfff80080
	s_addc_u32 s31, s5, -1
	s_add_i32 s95, 0, 0x10000
	s_cmp_eq_u32 s94, 28
	s_cselect_b32 s41, s27, s31
	s_cselect_b32 s40, s26, s30
	v_add_u32_e32 v149, s95, v147
	s_cselect_b32 s31, s2, s21
	s_cselect_b32 s30, s3, s15
	s_add_i32 vcc_lo, 0, 0x14000
	ds_read_b128 v[142:145], v149
	ds_read_b128 v[150:153], v149 offset:1024
	ds_read_b128 v[154:157], v149 offset:2048
	ds_read_b128 v[158:161], v149 offset:3072
	v_add_u32_e32 v149, vcc_lo, v147
	ds_read_b128 v[162:165], v149
	ds_read_b128 v[166:169], v149 offset:1024
	ds_read_b128 v[170:173], v149 offset:2048
	ds_read_b128 v[174:177], v149 offset:3072
	s_add_i32 m0, s35, 0xc000
	ds_read_b128 v[178:181], v148
	ds_read_b128 v[182:185], v148 offset:1024
	ds_read_b128 v[186:189], v148 offset:2048
	ds_read_b128 v[190:193], v148 offset:3072
	ds_read_b128 v[194:197], v148 offset:4096
	ds_read_b128 v[198:201], v148 offset:5120
	ds_read_b128 v[202:205], v148 offset:6144
	ds_read_b128 v[206:209], v148 offset:7168
	global_load_lds_dwordx4 v138, s[4:5]
	s_add_i32 m0, s35, 0xe000
	s_nop 0
	global_load_lds_dwordx4 v140, s[4:5]
	s_waitcnt vmcnt(8)
	s_waitcnt lgkmcnt(0)
	s_barrier
	s_waitcnt lgkmcnt(0)
	v_mfma_f32_16x16x32_bf16 v[126:129], v[142:145], v[178:181], 0
	v_mfma_f32_16x16x32_bf16 v[122:125], v[154:157], v[178:181], 0
	v_mfma_f32_16x16x32_bf16 v[110:113], v[142:145], v[186:189], 0
	v_mfma_f32_16x16x32_bf16 v[106:109], v[154:157], v[186:189], 0
	v_mfma_f32_16x16x32_bf16 v[94:97], v[142:145], v[194:197], 0
	v_mfma_f32_16x16x32_bf16 v[90:93], v[154:157], v[194:197], 0
	v_mfma_f32_16x16x32_bf16 v[78:81], v[142:145], v[202:205], 0
	v_mfma_f32_16x16x32_bf16 v[74:77], v[154:157], v[202:205], 0
	v_mfma_f32_16x16x32_bf16 v[126:129], v[150:153], v[182:185], v[126:129]
	v_mfma_f32_16x16x32_bf16 v[122:125], v[158:161], v[182:185], v[122:125]
	v_mfma_f32_16x16x32_bf16 v[110:113], v[150:153], v[190:193], v[110:113]
	v_mfma_f32_16x16x32_bf16 v[106:109], v[158:161], v[190:193], v[106:109]
	v_mfma_f32_16x16x32_bf16 v[94:97], v[150:153], v[198:201], v[94:97]
	v_mfma_f32_16x16x32_bf16 v[90:93], v[158:161], v[198:201], v[90:93]
	v_mfma_f32_16x16x32_bf16 v[78:81], v[150:153], v[206:209], v[78:81]
	v_mfma_f32_16x16x32_bf16 v[74:77], v[158:161], v[206:209], v[74:77]
	v_mfma_f32_16x16x32_bf16 v[118:121], v[162:165], v[178:181], 0
	v_mfma_f32_16x16x32_bf16 v[114:117], v[170:173], v[178:181], 0
	v_mfma_f32_16x16x32_bf16 v[102:105], v[162:165], v[186:189], 0
	v_mfma_f32_16x16x32_bf16 v[98:101], v[170:173], v[186:189], 0
	v_mfma_f32_16x16x32_bf16 v[86:89], v[162:165], v[194:197], 0
	v_mfma_f32_16x16x32_bf16 v[82:85], v[170:173], v[194:197], 0
	v_mfma_f32_16x16x32_bf16 v[70:73], v[162:165], v[202:205], 0
	v_mfma_f32_16x16x32_bf16 v[66:69], v[170:173], v[202:205], 0
	v_mfma_f32_16x16x32_bf16 v[118:121], v[166:169], v[182:185], v[118:121]
	v_mfma_f32_16x16x32_bf16 v[114:117], v[174:177], v[182:185], v[114:117]
	v_mfma_f32_16x16x32_bf16 v[102:105], v[166:169], v[190:193], v[102:105]
	v_mfma_f32_16x16x32_bf16 v[98:101], v[174:177], v[190:193], v[98:101]
	v_mfma_f32_16x16x32_bf16 v[86:89], v[166:169], v[198:201], v[86:89]
	v_mfma_f32_16x16x32_bf16 v[82:85], v[174:177], v[198:201], v[82:85]
	v_mfma_f32_16x16x32_bf16 v[70:73], v[166:169], v[206:209], v[70:73]
	v_mfma_f32_16x16x32_bf16 v[66:69], v[174:177], v[206:209], v[66:69]
	s_barrier
	s_add_i32 s95, s95, s34
	v_lshl_add_u64 v[210:211], s[30:31], 0, v[132:133]
	s_mov_b32 m0, s95
	ds_read_b128 v[178:181], v148 offset:16384
	ds_read_b128 v[182:185], v148 offset:17408
	ds_read_b128 v[186:189], v148 offset:18432
	ds_read_b128 v[190:193], v148 offset:19456
	ds_read_b128 v[194:197], v148 offset:20480
	ds_read_b128 v[198:201], v148 offset:21504
	ds_read_b128 v[202:205], v148 offset:22528
	ds_read_b128 v[206:209], v148 offset:23552
	global_load_lds_dwordx4 v[210:211], off
	s_add_i32 m0, s95, 0x2000
	s_add_u32 s96, s30, 0x80000
	v_lshl_add_u64 v[212:213], s[30:31], 0, v[136:137]
	s_addc_u32 s97, s31, 0
	s_add_i32 s95, vcc_lo, s34
	global_load_lds_dwordx4 v[212:213], off
	s_mov_b32 m0, s95
	v_lshl_add_u64 v[216:217], s[40:41], 0, v[134:135]
	global_load_lds_dwordx4 v132, s[96:97]
	s_add_i32 m0, s95, 0x2000
	s_nop 0
	global_load_lds_dwordx4 v136, s[96:97]
	v_lshl_add_u64 v[214:215], s[40:41], 0, v[130:131]
	s_mov_b32 m0, s35
	s_nop 0
	global_load_lds_dwordx4 v[214:215], off
	s_mov_b32 m0, s36
	s_nop 0
	global_load_lds_dwordx4 v[216:217], off
	s_waitcnt vmcnt(8)
	s_waitcnt lgkmcnt(0)
	s_barrier
; #define PG8_STAGE(bufoff, gbase, voff) do { _Pragma("unroll") for (int _i = 0; _i < 2; ++_i) \
;         __builtin_amdgcn_global_load_lds((const unsigned*)((const char*)(gbase) + (voff)[_i]), (PG8_LAS unsigned*)(lds + (bufoff) + ldsw + _i * 8192), 16, 0, 0); } while (0)
; #define PG8_LDA(dst, b, h) do { _Pragma("unroll") for (int m = 0; m < 4; ++m) _Pragma("unroll") for (int k = 0; k < 2; ++k) dst[m][k] = *(const PG8_LAS bf16x8*)(lds + PG8_SA(b, h) + aoff + m * 2048 + k * 1024); } while (0)
; #define PG8_LDB(dst, b, h) do { _Pragma("unroll") for (int n = 0; n < 2; ++n) _Pragma("unroll") for (int k = 0; k < 2; ++k) dst[n][k] = *(const PG8_LAS bf16x8*)(lds + PG8_SB(b, h) + boff + n * 2048 + k * 1024); } while (0)
; #define PG8_MMA(ai, bj, At, Bt) do { __builtin_amdgcn_s_setprio(1); _Pragma("unroll") for (int m = 0; m < 4; ++m) _Pragma("unroll") for (int n = 0; n < 2; ++n) _Pragma("unroll") for (int k = 0; k < 2; ++k) \
;         acc[ai][bj][m][n] = __builtin_amdgcn_mfma_f32_16x16x32_bf16(Bt[n][k], At[m][k], acc[ai][bj][m][n], 0, 0, 0); __builtin_amdgcn_s_setprio(0); } while (0)
; #define PG8_WAIT_V(n) asm volatile("s_waitcnt vmcnt(" #n ")" ::: "memory")
; #define PG8_WAIT_L(n) asm volatile("s_waitcnt lgkmcnt(" #n ")" ::: "memory")
; #define PG8_BAR __builtin_amdgcn_s_barrier()
; #define PG8_SCHED __builtin_amdgcn_sched_barrier(0)
; template <class Epi, class Sched, bool ALIGN_EPI = false, bool SP2 = false>
; __device__ __forceinline__ void gemm_phase(PG8_LAS unsigned char* lds, const Gemm g, const Sched& S, const Epi& E, int wave_s) {
;     ...
;             PG8_LDA(At, 0, 1); PG8_STAGE(PG8_SB(0, 0), b2, voffB); PG8_STAGE(PG8_SB(0, 1), b2 + hstepB, voffB); PG8_STAGE(PG8_SA(0, 0), a2, voffA);
;             PG8_WAIT_V(8); PG8_WAIT_L(0); PG8_BAR; PG8_MMA(1, 0, At, B0); PG8_MMA(1, 1, At, B1); PG8_BAR; PG8_SCHED;
;             PG8_LDB(B0, 1, 0); PG8_LDB(B1, 1, 1); PG8_SCHED; PG8_LDA(At, 1, 0); PG8_STAGE(PG8_SA(0, 1), a2 + hstepA, voffA);
;             PG8_WAIT_V(8); PG8_WAIT_L(0); PG8_BAR; PG8_MMA(0, 0, At, B0); PG8_MMA(0, 1, At, B1); PG8_BAR; PG8_SCHED;
	s_waitcnt lgkmcnt(0)
	v_mfma_f32_16x16x32_bf16 v[62:65], v[142:145], v[178:181], 0
	v_mfma_f32_16x16x32_bf16 v[58:61], v[154:157], v[178:181], 0
	v_mfma_f32_16x16x32_bf16 v[46:49], v[142:145], v[186:189], 0
	v_mfma_f32_16x16x32_bf16 v[42:45], v[154:157], v[186:189], 0
	v_mfma_f32_16x16x32_bf16 v[30:33], v[142:145], v[194:197], 0
	v_mfma_f32_16x16x32_bf16 v[26:29], v[154:157], v[194:197], 0
	v_mfma_f32_16x16x32_bf16 v[14:17], v[142:145], v[202:205], 0
	v_mfma_f32_16x16x32_bf16 v[10:13], v[154:157], v[202:205], 0
	v_mfma_f32_16x16x32_bf16 v[62:65], v[150:153], v[182:185], v[62:65]
	v_mfma_f32_16x16x32_bf16 v[58:61], v[158:161], v[182:185], v[58:61]
	v_mfma_f32_16x16x32_bf16 v[46:49], v[150:153], v[190:193], v[46:49]
	v_mfma_f32_16x16x32_bf16 v[42:45], v[158:161], v[190:193], v[42:45]
	v_mfma_f32_16x16x32_bf16 v[30:33], v[150:153], v[198:201], v[30:33]
	v_mfma_f32_16x16x32_bf16 v[26:29], v[158:161], v[198:201], v[26:29]
	v_mfma_f32_16x16x32_bf16 v[14:17], v[150:153], v[206:209], v[14:17]
	v_mfma_f32_16x16x32_bf16 v[10:13], v[158:161], v[206:209], v[10:13]
	v_mfma_f32_16x16x32_bf16 v[54:57], v[162:165], v[178:181], 0
	v_mfma_f32_16x16x32_bf16 v[50:53], v[170:173], v[178:181], 0
	v_mfma_f32_16x16x32_bf16 v[38:41], v[162:165], v[186:189], 0
	v_mfma_f32_16x16x32_bf16 v[34:37], v[170:173], v[186:189], 0
	v_mfma_f32_16x16x32_bf16 v[22:25], v[162:165], v[194:197], 0
	v_mfma_f32_16x16x32_bf16 v[18:21], v[170:173], v[194:197], 0
	v_mfma_f32_16x16x32_bf16 v[6:9], v[162:165], v[202:205], 0
	v_mfma_f32_16x16x32_bf16 v[2:5], v[170:173], v[202:205], 0
	v_mfma_f32_16x16x32_bf16 v[54:57], v[166:169], v[182:185], v[54:57]
	v_mfma_f32_16x16x32_bf16 v[50:53], v[174:177], v[182:185], v[50:53]
	v_mfma_f32_16x16x32_bf16 v[38:41], v[166:169], v[190:193], v[38:41]
	v_mfma_f32_16x16x32_bf16 v[34:37], v[174:177], v[190:193], v[34:37]
	v_mfma_f32_16x16x32_bf16 v[22:25], v[166:169], v[198:201], v[22:25]
	v_mfma_f32_16x16x32_bf16 v[18:21], v[174:177], v[198:201], v[18:21]
	v_mfma_f32_16x16x32_bf16 v[6:9], v[166:169], v[206:209], v[6:9]
	v_mfma_f32_16x16x32_bf16 v[2:5], v[174:177], v[206:209], v[2:5]
	s_barrier
	s_add_i32 s95, 0, 0x18000
	v_add_u32_e32 v149, s95, v147
	s_add_i32 s96, 0, 0x1c000
	ds_read_b128 v[142:145], v149
	ds_read_b128 v[150:153], v149 offset:1024
	ds_read_b128 v[154:157], v149 offset:2048
	ds_read_b128 v[158:161], v149 offset:3072
	v_add_u32_e32 v149, s96, v147
	ds_read_b128 v[162:165], v149
	ds_read_b128 v[166:169], v149 offset:1024
	ds_read_b128 v[170:173], v149 offset:2048
	ds_read_b128 v[174:177], v149 offset:3072
	s_add_u32 s40, s40, 0x80000
	s_addc_u32 s41, s41, 0
	s_mov_b32 m0, s37
	ds_read_b128 v[178:181], v148 offset:32768
	ds_read_b128 v[182:185], v148 offset:33792
	ds_read_b128 v[186:189], v148 offset:34816
	ds_read_b128 v[190:193], v148 offset:35840
	ds_read_b128 v[194:197], v148 offset:36864
	ds_read_b128 v[198:201], v148 offset:37888
	ds_read_b128 v[202:205], v148 offset:38912
	ds_read_b128 v[206:209], v148 offset:39936
	global_load_lds_dwordx4 v130, s[40:41]
	s_mov_b32 m0, s42
	s_nop 0
	global_load_lds_dwordx4 v134, s[40:41]
	s_waitcnt vmcnt(8)
	s_waitcnt lgkmcnt(0)
	s_barrier
	s_waitcnt lgkmcnt(0)
	v_mfma_f32_16x16x32_bf16 v[126:129], v[142:145], v[178:181], v[126:129]
	v_mfma_f32_16x16x32_bf16 v[122:125], v[154:157], v[178:181], v[122:125]
	v_mfma_f32_16x16x32_bf16 v[110:113], v[142:145], v[186:189], v[110:113]
	v_mfma_f32_16x16x32_bf16 v[106:109], v[154:157], v[186:189], v[106:109]
	v_mfma_f32_16x16x32_bf16 v[94:97], v[142:145], v[194:197], v[94:97]
	v_mfma_f32_16x16x32_bf16 v[90:93], v[154:157], v[194:197], v[90:93]
	v_mfma_f32_16x16x32_bf16 v[78:81], v[142:145], v[202:205], v[78:81]
	v_mfma_f32_16x16x32_bf16 v[74:77], v[154:157], v[202:205], v[74:77]
	v_mfma_f32_16x16x32_bf16 v[126:129], v[150:153], v[182:185], v[126:129]
	v_mfma_f32_16x16x32_bf16 v[122:125], v[158:161], v[182:185], v[122:125]
	v_mfma_f32_16x16x32_bf16 v[110:113], v[150:153], v[190:193], v[110:113]
	v_mfma_f32_16x16x32_bf16 v[106:109], v[158:161], v[190:193], v[106:109]
	v_mfma_f32_16x16x32_bf16 v[94:97], v[150:153], v[198:201], v[94:97]
	v_mfma_f32_16x16x32_bf16 v[90:93], v[158:161], v[198:201], v[90:93]
	v_mfma_f32_16x16x32_bf16 v[78:81], v[150:153], v[206:209], v[78:81]
	v_mfma_f32_16x16x32_bf16 v[74:77], v[158:161], v[206:209], v[74:77]
	v_mfma_f32_16x16x32_bf16 v[118:121], v[162:165], v[178:181], v[118:121]
	v_mfma_f32_16x16x32_bf16 v[114:117], v[170:173], v[178:181], v[114:117]
	v_mfma_f32_16x16x32_bf16 v[102:105], v[162:165], v[186:189], v[102:105]
	v_mfma_f32_16x16x32_bf16 v[98:101], v[170:173], v[186:189], v[98:101]
	v_mfma_f32_16x16x32_bf16 v[86:89], v[162:165], v[194:197], v[86:89]
	v_mfma_f32_16x16x32_bf16 v[82:85], v[170:173], v[194:197], v[82:85]
	v_mfma_f32_16x16x32_bf16 v[70:73], v[162:165], v[202:205], v[70:73]
	v_mfma_f32_16x16x32_bf16 v[66:69], v[170:173], v[202:205], v[66:69]
	v_mfma_f32_16x16x32_bf16 v[118:121], v[166:169], v[182:185], v[118:121]
	v_mfma_f32_16x16x32_bf16 v[114:117], v[174:177], v[182:185], v[114:117]
	v_mfma_f32_16x16x32_bf16 v[102:105], v[166:169], v[190:193], v[102:105]
	v_mfma_f32_16x16x32_bf16 v[98:101], v[174:177], v[190:193], v[98:101]
	v_mfma_f32_16x16x32_bf16 v[86:89], v[166:169], v[198:201], v[86:89]
	v_mfma_f32_16x16x32_bf16 v[82:85], v[174:177], v[198:201], v[82:85]
	v_mfma_f32_16x16x32_bf16 v[70:73], v[166:169], v[206:209], v[70:73]
	v_mfma_f32_16x16x32_bf16 v[66:69], v[174:177], v[206:209], v[66:69]
	s_barrier
; #define PG8_STAGE(bufoff, gbase, voff) do { _Pragma("unroll") for (int _i = 0; _i < 2; ++_i) \
;         __builtin_amdgcn_global_load_lds((const unsigned*)((const char*)(gbase) + (voff)[_i]), (PG8_LAS unsigned*)(lds + (bufoff) + ldsw + _i * 8192), 16, 0, 0); } while (0)
; #define PG8_LDA(dst, b, h) do { _Pragma("unroll") for (int m = 0; m < 4; ++m) _Pragma("unroll") for (int k = 0; k < 2; ++k) dst[m][k] = *(const PG8_LAS bf16x8*)(lds + PG8_SA(b, h) + aoff + m * 2048 + k * 1024); } while (0)
; #define PG8_LDB(dst, b, h) do { _Pragma("unroll") for (int n = 0; n < 2; ++n) _Pragma("unroll") for (int k = 0; k < 2; ++k) dst[n][k] = *(const PG8_LAS bf16x8*)(lds + PG8_SB(b, h) + boff + n * 2048 + k * 1024); } while (0)
; #define PG8_WAIT_V(n) asm volatile("s_waitcnt vmcnt(" #n ")" ::: "memory")
; #define PG8_WAIT_L(n) asm volatile("s_waitcnt lgkmcnt(" #n ")" ::: "memory")
; #define PG8_BAR __builtin_amdgcn_s_barrier()
; #define PG8_SCHED __builtin_amdgcn_sched_barrier(0)
; template <class Epi, class Sched, bool ALIGN_EPI = false, bool SP2 = false>
; __device__ __forceinline__ void gemm_phase(PG8_LAS unsigned char* lds, const Gemm g, const Sched& S, const Epi& E, int wave_s) {
;     ...
;         for (int t = 0; t < nt; t += 2) {
;             const bool last = (t == nt - 2);
;             const char* a1 = cA + (size_t)(t + 1) * kstep;
;             const char* a2 = last ? nA : cA + (size_t)(t + 2) * kstep; const char* b2 = last ? nB : cB + (size_t)(t + 2) * kstep;
;             const char* a3 = a2 + kstep; const char* b3 = b2 + kstep;
;             if (last && has_next) S.a_ready(nxt);
;             if constexpr (SP2) {
;             PG8_LDB(B0, 0, 0); PG8_LDB(B1, 0, 1); PG8_SCHED; PG8_LDA(At, 0, 0); PG8_STAGE(PG8_SA(1, 1), a1 + hstepA, voffA);
;             PG8_WAIT_V(8); PG8_WAIT_L(0); PG8_BAR; PG8_MMA(0, 0, At, B0); PG8_MMA(0, 1, At, B1); PG8_BAR; PG8_SCHED;
;             PG8_LDA(At, 0, 1); PG8_STAGE(PG8_SB(0, 0), b2, voffB); PG8_STAGE(PG8_SB(0, 1), b2 + hstepB, voffB); PG8_STAGE(PG8_SA(0, 0), a2, voffA);
;     ...
;             PG8_LDA(At, 1, 1); PG8_STAGE(PG8_SB(1, 0), b3, voffB); PG8_STAGE(PG8_SB(1, 1), b3 + hstepB, voffB); PG8_STAGE(PG8_SA(1, 0), a3, voffA);
;             PG8_WAIT_V(8); PG8_WAIT_L(0); PG8_BAR; PG8_MMA(1, 0, At, B0); PG8_MMA(1, 1, At, B1); PG8_BAR; PG8_SCHED;
	s_add_i32 s40, s95, s34
	v_lshl_add_u64 v[210:211], v[210:211], 0, s[60:61]
	s_mov_b32 m0, s40
	ds_read_b128 v[178:181], v148 offset:49152
	ds_read_b128 v[182:185], v148 offset:50176
	ds_read_b128 v[186:189], v148 offset:51200
	ds_read_b128 v[190:193], v148 offset:52224
	ds_read_b128 v[194:197], v148 offset:53248
	ds_read_b128 v[198:201], v148 offset:54272
	ds_read_b128 v[202:205], v148 offset:55296
	ds_read_b128 v[206:209], v148 offset:56320
	global_load_lds_dwordx4 v[210:211], off
	s_add_i32 m0, s40, 0x2000
	s_add_u32 s30, s30, 0x80080
	v_lshl_add_u64 v[210:211], v[212:213], 0, s[60:61]
	s_addc_u32 s31, s31, 0
	s_add_i32 s40, s96, s34
	global_load_lds_dwordx4 v[210:211], off
	s_mov_b32 m0, s40
	s_nop 0
	global_load_lds_dwordx4 v132, s[30:31]
	s_add_i32 m0, s40, 0x2000
	s_nop 0
	global_load_lds_dwordx4 v136, s[30:31]
	v_lshl_add_u64 v[210:211], v[214:215], 0, s[60:61]
	s_mov_b32 m0, s45
	s_nop 0
	global_load_lds_dwordx4 v[210:211], off
	v_lshl_add_u64 v[210:211], v[216:217], 0, s[60:61]
	s_mov_b32 m0, s46
	s_nop 0
	global_load_lds_dwordx4 v[210:211], off
	s_waitcnt vmcnt(8)
	s_waitcnt lgkmcnt(0)
	s_barrier
	s_waitcnt lgkmcnt(0)
	v_mfma_f32_16x16x32_bf16 v[62:65], v[142:145], v[178:181], v[62:65]
	v_mfma_f32_16x16x32_bf16 v[58:61], v[154:157], v[178:181], v[58:61]
	v_mfma_f32_16x16x32_bf16 v[46:49], v[142:145], v[186:189], v[46:49]
	v_mfma_f32_16x16x32_bf16 v[42:45], v[154:157], v[186:189], v[42:45]
	v_mfma_f32_16x16x32_bf16 v[30:33], v[142:145], v[194:197], v[30:33]
	v_mfma_f32_16x16x32_bf16 v[26:29], v[154:157], v[194:197], v[26:29]
	v_mfma_f32_16x16x32_bf16 v[14:17], v[142:145], v[202:205], v[14:17]
	v_mfma_f32_16x16x32_bf16 v[10:13], v[154:157], v[202:205], v[10:13]
	v_mfma_f32_16x16x32_bf16 v[62:65], v[150:153], v[182:185], v[62:65]
	v_mfma_f32_16x16x32_bf16 v[58:61], v[158:161], v[182:185], v[58:61]
	v_mfma_f32_16x16x32_bf16 v[46:49], v[150:153], v[190:193], v[46:49]
	v_mfma_f32_16x16x32_bf16 v[42:45], v[158:161], v[190:193], v[42:45]
	v_mfma_f32_16x16x32_bf16 v[30:33], v[150:153], v[198:201], v[30:33]
	v_mfma_f32_16x16x32_bf16 v[26:29], v[158:161], v[198:201], v[26:29]
	v_mfma_f32_16x16x32_bf16 v[14:17], v[150:153], v[206:209], v[14:17]
	v_mfma_f32_16x16x32_bf16 v[10:13], v[158:161], v[206:209], v[10:13]
	v_mfma_f32_16x16x32_bf16 v[54:57], v[162:165], v[178:181], v[54:57]
	v_mfma_f32_16x16x32_bf16 v[50:53], v[170:173], v[178:181], v[50:53]
	v_mfma_f32_16x16x32_bf16 v[38:41], v[162:165], v[186:189], v[38:41]
	v_mfma_f32_16x16x32_bf16 v[34:37], v[170:173], v[186:189], v[34:37]
	v_mfma_f32_16x16x32_bf16 v[22:25], v[162:165], v[194:197], v[22:25]
	v_mfma_f32_16x16x32_bf16 v[18:21], v[170:173], v[194:197], v[18:21]
	v_mfma_f32_16x16x32_bf16 v[6:9], v[162:165], v[202:205], v[6:9]
	v_mfma_f32_16x16x32_bf16 v[2:5], v[170:173], v[202:205], v[2:5]
	v_mfma_f32_16x16x32_bf16 v[54:57], v[166:169], v[182:185], v[54:57]
	v_mfma_f32_16x16x32_bf16 v[50:53], v[174:177], v[182:185], v[50:53]
	v_mfma_f32_16x16x32_bf16 v[38:41], v[166:169], v[190:193], v[38:41]
	v_mfma_f32_16x16x32_bf16 v[34:37], v[174:177], v[190:193], v[34:37]
	v_mfma_f32_16x16x32_bf16 v[22:25], v[166:169], v[198:201], v[22:25]
	v_mfma_f32_16x16x32_bf16 v[18:21], v[174:177], v[198:201], v[18:21]
	v_mfma_f32_16x16x32_bf16 v[6:9], v[166:169], v[206:209], v[6:9]
	v_mfma_f32_16x16x32_bf16 v[2:5], v[174:177], v[206:209], v[2:5]
	s_barrier
	s_add_i32 s94, s94, 2
	s_add_u32 s4, s4, 0x100
	s_addc_u32 s5, s5, 0
	s_add_u32 s15, s15, 0x100
	s_addc_u32 s21, s21, 0
	s_cmp_gt_u32 s94, 29
.LBB0_412:
	s_add_u32 s30, s4, 0xfff80080
	s_addc_u32 s31, s5, -1
	s_add_i32 s95, 0, 0x10000
	s_cmp_eq_u32 s94, 28
	s_cselect_b32 s41, s27, s31
	s_cselect_b32 s40, s26, s30
	v_add_u32_e32 v149, s95, v147
	s_cselect_b32 s31, s2, s21
	s_cselect_b32 s30, s3, s15
	s_add_i32 vcc_lo, 0, 0x14000
	ds_read_b128 v[142:145], v149
	ds_read_b128 v[150:153], v149 offset:1024
	ds_read_b128 v[154:157], v149 offset:2048
	ds_read_b128 v[158:161], v149 offset:3072
	v_add_u32_e32 v149, vcc_lo, v147
	ds_read_b128 v[162:165], v149
	ds_read_b128 v[166:169], v149 offset:1024
	ds_read_b128 v[170:173], v149 offset:2048
	ds_read_b128 v[174:177], v149 offset:3072
	s_add_i32 m0, s35, 0xc000
	ds_read_b128 v[178:181], v148
	ds_read_b128 v[182:185], v148 offset:1024
	ds_read_b128 v[186:189], v148 offset:2048
	ds_read_b128 v[190:193], v148 offset:3072
	ds_read_b128 v[194:197], v148 offset:4096
	ds_read_b128 v[198:201], v148 offset:5120
	ds_read_b128 v[202:205], v148 offset:6144
	ds_read_b128 v[206:209], v148 offset:7168
	global_load_lds_dwordx4 v138, s[4:5]
	s_add_i32 m0, s35, 0xe000
	s_nop 0
	global_load_lds_dwordx4 v140, s[4:5]
	s_waitcnt vmcnt(8)
	s_waitcnt lgkmcnt(0)
	s_barrier
; #define PG8_STAGE(bufoff, gbase, voff) do { _Pragma("unroll") for (int _i = 0; _i < 2; ++_i) \
;         __builtin_amdgcn_global_load_lds((const unsigned*)((const char*)(gbase) + (voff)[_i]), (PG8_LAS unsigned*)(lds + (bufoff) + ldsw + _i * 8192), 16, 0, 0); } while (0)
; #define PG8_LDA(dst, b, h) do { _Pragma("unroll") for (int m = 0; m < 4; ++m) _Pragma("unroll") for (int k = 0; k < 2; ++k) dst[m][k] = *(const PG8_LAS bf16x8*)(lds + PG8_SA(b, h) + aoff + m * 2048 + k * 1024); } while (0)
; #define PG8_LDB(dst, b, h) do { _Pragma("unroll") for (int n = 0; n < 2; ++n) _Pragma("unroll") for (int k = 0; k < 2; ++k) dst[n][k] = *(const PG8_LAS bf16x8*)(lds + PG8_SB(b, h) + boff + n * 2048 + k * 1024); } while (0)
; #define PG8_MMA(ai, bj, At, Bt) do { __builtin_amdgcn_s_setprio(1); _Pragma("unroll") for (int m = 0; m < 4; ++m) _Pragma("unroll") for (int n = 0; n < 2; ++n) _Pragma("unroll") for (int k = 0; k < 2; ++k) \
;         acc[ai][bj][m][n] = __builtin_amdgcn_mfma_f32_16x16x32_bf16(Bt[n][k], At[m][k], acc[ai][bj][m][n], 0, 0, 0); __builtin_amdgcn_s_setprio(0); } while (0)
; #define PG8_WAIT_V(n) asm volatile("s_waitcnt vmcnt(" #n ")" ::: "memory")
; #define PG8_WAIT_L(n) asm volatile("s_waitcnt lgkmcnt(" #n ")" ::: "memory")
; #define PG8_BAR __builtin_amdgcn_s_barrier()
; #define PG8_SCHED __builtin_amdgcn_sched_barrier(0)
; template <class Epi, class Sched, bool ALIGN_EPI = false, bool SP2 = false>
; __device__ __forceinline__ void gemm_phase(PG8_LAS unsigned char* lds, const Gemm g, const Sched& S, const Epi& E, int wave_s) {
;     ...
;             PG8_LDB(B0, 0, 0); PG8_LDB(B1, 0, 1); PG8_SCHED; PG8_LDA(At, 0, 0); PG8_STAGE(PG8_SA(1, 1), a1 + hstepA, voffA);
;             PG8_WAIT_V(8); PG8_WAIT_L(0); PG8_BAR; PG8_MMA(0, 0, At, B0); PG8_MMA(0, 1, At, B1); PG8_BAR; PG8_SCHED;
;             PG8_LDA(At, 0, 1); PG8_STAGE(PG8_SB(0, 0), b2, voffB); PG8_STAGE(PG8_SB(0, 1), b2 + hstepB, voffB); PG8_STAGE(PG8_SA(0, 0), a2, voffA);
;             PG8_WAIT_V(8); PG8_WAIT_L(0); PG8_BAR; PG8_MMA(1, 0, At, B0); PG8_MMA(1, 1, At, B1); PG8_BAR; PG8_SCHED;
;             PG8_LDB(B0, 1, 0); PG8_LDB(B1, 1, 1); PG8_SCHED; PG8_LDA(At, 1, 0); PG8_STAGE(PG8_SA(0, 1), a2 + hstepA, voffA);
;             PG8_WAIT_V(8); PG8_WAIT_L(0); PG8_BAR; PG8_MMA(0, 0, At, B0); PG8_MMA(0, 1, At, B1); PG8_BAR; PG8_SCHED;
	s_waitcnt lgkmcnt(0)
	v_mfma_f32_16x16x32_bf16 v[126:129], v[142:145], v[178:181], v[126:129]
	v_mfma_f32_16x16x32_bf16 v[122:125], v[154:157], v[178:181], v[122:125]
	v_mfma_f32_16x16x32_bf16 v[110:113], v[142:145], v[186:189], v[110:113]
	v_mfma_f32_16x16x32_bf16 v[106:109], v[154:157], v[186:189], v[106:109]
	v_mfma_f32_16x16x32_bf16 v[94:97], v[142:145], v[194:197], v[94:97]
	v_mfma_f32_16x16x32_bf16 v[90:93], v[154:157], v[194:197], v[90:93]
	v_mfma_f32_16x16x32_bf16 v[78:81], v[142:145], v[202:205], v[78:81]
	v_mfma_f32_16x16x32_bf16 v[74:77], v[154:157], v[202:205], v[74:77]
	v_mfma_f32_16x16x32_bf16 v[126:129], v[150:153], v[182:185], v[126:129]
	v_mfma_f32_16x16x32_bf16 v[122:125], v[158:161], v[182:185], v[122:125]
	v_mfma_f32_16x16x32_bf16 v[110:113], v[150:153], v[190:193], v[110:113]
	v_mfma_f32_16x16x32_bf16 v[106:109], v[158:161], v[190:193], v[106:109]
	v_mfma_f32_16x16x32_bf16 v[94:97], v[150:153], v[198:201], v[94:97]
	v_mfma_f32_16x16x32_bf16 v[90:93], v[158:161], v[198:201], v[90:93]
	v_mfma_f32_16x16x32_bf16 v[78:81], v[150:153], v[206:209], v[78:81]
	v_mfma_f32_16x16x32_bf16 v[74:77], v[158:161], v[206:209], v[74:77]
	v_mfma_f32_16x16x32_bf16 v[118:121], v[162:165], v[178:181], v[118:121]
	v_mfma_f32_16x16x32_bf16 v[114:117], v[170:173], v[178:181], v[114:117]
	v_mfma_f32_16x16x32_bf16 v[102:105], v[162:165], v[186:189], v[102:105]
	v_mfma_f32_16x16x32_bf16 v[98:101], v[170:173], v[186:189], v[98:101]
	v_mfma_f32_16x16x32_bf16 v[86:89], v[162:165], v[194:197], v[86:89]
	v_mfma_f32_16x16x32_bf16 v[82:85], v[170:173], v[194:197], v[82:85]
	v_mfma_f32_16x16x32_bf16 v[70:73], v[162:165], v[202:205], v[70:73]
	v_mfma_f32_16x16x32_bf16 v[66:69], v[170:173], v[202:205], v[66:69]
	v_mfma_f32_16x16x32_bf16 v[118:121], v[166:169], v[182:185], v[118:121]
	v_mfma_f32_16x16x32_bf16 v[114:117], v[174:177], v[182:185], v[114:117]
	v_mfma_f32_16x16x32_bf16 v[102:105], v[166:169], v[190:193], v[102:105]
	v_mfma_f32_16x16x32_bf16 v[98:101], v[174:177], v[190:193], v[98:101]
	v_mfma_f32_16x16x32_bf16 v[86:89], v[166:169], v[198:201], v[86:89]
	v_mfma_f32_16x16x32_bf16 v[82:85], v[174:177], v[198:201], v[82:85]
	v_mfma_f32_16x16x32_bf16 v[70:73], v[166:169], v[206:209], v[70:73]
	v_mfma_f32_16x16x32_bf16 v[66:69], v[174:177], v[206:209], v[66:69]
	s_barrier
	s_add_i32 s95, s95, s34
	v_lshl_add_u64 v[210:211], s[30:31], 0, v[132:133]
	s_mov_b32 m0, s95
	ds_read_b128 v[178:181], v148 offset:16384
	ds_read_b128 v[182:185], v148 offset:17408
	ds_read_b128 v[186:189], v148 offset:18432
	ds_read_b128 v[190:193], v148 offset:19456
	ds_read_b128 v[194:197], v148 offset:20480
	ds_read_b128 v[198:201], v148 offset:21504
	ds_read_b128 v[202:205], v148 offset:22528
	ds_read_b128 v[206:209], v148 offset:23552
	global_load_lds_dwordx4 v[210:211], off
	s_add_i32 m0, s95, 0x2000
	s_add_u32 s96, s30, 0x80000
	v_lshl_add_u64 v[212:213], s[30:31], 0, v[136:137]
	s_addc_u32 s97, s31, 0
	s_add_i32 s95, vcc_lo, s34
	global_load_lds_dwordx4 v[212:213], off
	s_mov_b32 m0, s95
	v_lshl_add_u64 v[216:217], s[40:41], 0, v[134:135]
	global_load_lds_dwordx4 v132, s[96:97]
	s_add_i32 m0, s95, 0x2000
	s_nop 0
	global_load_lds_dwordx4 v136, s[96:97]
	v_lshl_add_u64 v[214:215], s[40:41], 0, v[130:131]
	s_mov_b32 m0, s35
	s_nop 0
	global_load_lds_dwordx4 v[214:215], off
	s_mov_b32 m0, s36
	s_nop 0
	global_load_lds_dwordx4 v[216:217], off
	s_waitcnt vmcnt(8)
	s_waitcnt lgkmcnt(0)
	s_barrier
	s_waitcnt lgkmcnt(0)
	v_mfma_f32_16x16x32_bf16 v[62:65], v[142:145], v[178:181], v[62:65]
	v_mfma_f32_16x16x32_bf16 v[58:61], v[154:157], v[178:181], v[58:61]
	v_mfma_f32_16x16x32_bf16 v[46:49], v[142:145], v[186:189], v[46:49]
	v_mfma_f32_16x16x32_bf16 v[42:45], v[154:157], v[186:189], v[42:45]
	v_mfma_f32_16x16x32_bf16 v[30:33], v[142:145], v[194:197], v[30:33]
	v_mfma_f32_16x16x32_bf16 v[26:29], v[154:157], v[194:197], v[26:29]
	v_mfma_f32_16x16x32_bf16 v[14:17], v[142:145], v[202:205], v[14:17]
	v_mfma_f32_16x16x32_bf16 v[10:13], v[154:157], v[202:205], v[10:13]
	v_mfma_f32_16x16x32_bf16 v[62:65], v[150:153], v[182:185], v[62:65]
	v_mfma_f32_16x16x32_bf16 v[58:61], v[158:161], v[182:185], v[58:61]
	v_mfma_f32_16x16x32_bf16 v[46:49], v[150:153], v[190:193], v[46:49]
	v_mfma_f32_16x16x32_bf16 v[42:45], v[158:161], v[190:193], v[42:45]
	v_mfma_f32_16x16x32_bf16 v[30:33], v[150:153], v[198:201], v[30:33]
	v_mfma_f32_16x16x32_bf16 v[26:29], v[158:161], v[198:201], v[26:29]
	v_mfma_f32_16x16x32_bf16 v[14:17], v[150:153], v[206:209], v[14:17]
	v_mfma_f32_16x16x32_bf16 v[10:13], v[158:161], v[206:209], v[10:13]
	v_mfma_f32_16x16x32_bf16 v[54:57], v[162:165], v[178:181], v[54:57]
	v_mfma_f32_16x16x32_bf16 v[50:53], v[170:173], v[178:181], v[50:53]
	v_mfma_f32_16x16x32_bf16 v[38:41], v[162:165], v[186:189], v[38:41]
	v_mfma_f32_16x16x32_bf16 v[34:37], v[170:173], v[186:189], v[34:37]
	v_mfma_f32_16x16x32_bf16 v[22:25], v[162:165], v[194:197], v[22:25]
	v_mfma_f32_16x16x32_bf16 v[18:21], v[170:173], v[194:197], v[18:21]
	v_mfma_f32_16x16x32_bf16 v[6:9], v[162:165], v[202:205], v[6:9]
	v_mfma_f32_16x16x32_bf16 v[2:5], v[170:173], v[202:205], v[2:5]
	v_mfma_f32_16x16x32_bf16 v[54:57], v[166:169], v[182:185], v[54:57]
	v_mfma_f32_16x16x32_bf16 v[50:53], v[174:177], v[182:185], v[50:53]
	v_mfma_f32_16x16x32_bf16 v[38:41], v[166:169], v[190:193], v[38:41]
	v_mfma_f32_16x16x32_bf16 v[34:37], v[174:177], v[190:193], v[34:37]
	v_mfma_f32_16x16x32_bf16 v[22:25], v[166:169], v[198:201], v[22:25]
	v_mfma_f32_16x16x32_bf16 v[18:21], v[174:177], v[198:201], v[18:21]
	v_mfma_f32_16x16x32_bf16 v[6:9], v[166:169], v[206:209], v[6:9]
	v_mfma_f32_16x16x32_bf16 v[2:5], v[174:177], v[206:209], v[2:5]
	s_barrier
; #define PG8_STAGE(bufoff, gbase, voff) do { _Pragma("unroll") for (int _i = 0; _i < 2; ++_i) \
;         __builtin_amdgcn_global_load_lds((const unsigned*)((const char*)(gbase) + (voff)[_i]), (PG8_LAS unsigned*)(lds + (bufoff) + ldsw + _i * 8192), 16, 0, 0); } while (0)
; #define PG8_LDA(dst, b, h) do { _Pragma("unroll") for (int m = 0; m < 4; ++m) _Pragma("unroll") for (int k = 0; k < 2; ++k) dst[m][k] = *(const PG8_LAS bf16x8*)(lds + PG8_SA(b, h) + aoff + m * 2048 + k * 1024); } while (0)
; #define PG8_LDB(dst, b, h) do { _Pragma("unroll") for (int n = 0; n < 2; ++n) _Pragma("unroll") for (int k = 0; k < 2; ++k) dst[n][k] = *(const PG8_LAS bf16x8*)(lds + PG8_SB(b, h) + boff + n * 2048 + k * 1024); } while (0)
; #define PG8_MMA(ai, bj, At, Bt) do { __builtin_amdgcn_s_setprio(1); _Pragma("unroll") for (int m = 0; m < 4; ++m) _Pragma("unroll") for (int n = 0; n < 2; ++n) _Pragma("unroll") for (int k = 0; k < 2; ++k) \
;         acc[ai][bj][m][n] = __builtin_amdgcn_mfma_f32_16x16x32_bf16(Bt[n][k], At[m][k], acc[ai][bj][m][n], 0, 0, 0); __builtin_amdgcn_s_setprio(0); } while (0)
; #define PG8_WAIT_V(n) asm volatile("s_waitcnt vmcnt(" #n ")" ::: "memory")
; #define PG8_WAIT_L(n) asm volatile("s_waitcnt lgkmcnt(" #n ")" ::: "memory")
; #define PG8_BAR __builtin_amdgcn_s_barrier()
; #define PG8_SCHED __builtin_amdgcn_sched_barrier(0)
; template <class Epi, class Sched, bool ALIGN_EPI = false, bool SP2 = false>
; __device__ __forceinline__ void gemm_phase(PG8_LAS unsigned char* lds, const Gemm g, const Sched& S, const Epi& E, int wave_s) {
;     ...
;             PG8_LDA(At, 0, 1); PG8_STAGE(PG8_SB(0, 0), b2, voffB); PG8_STAGE(PG8_SB(0, 1), b2 + hstepB, voffB); PG8_STAGE(PG8_SA(0, 0), a2, voffA);
;             PG8_WAIT_V(8); PG8_WAIT_L(0); PG8_BAR; PG8_MMA(1, 0, At, B0); PG8_MMA(1, 1, At, B1); PG8_BAR; PG8_SCHED;
;             PG8_LDB(B0, 1, 0); PG8_LDB(B1, 1, 1); PG8_SCHED; PG8_LDA(At, 1, 0); PG8_STAGE(PG8_SA(0, 1), a2 + hstepA, voffA);
;             PG8_WAIT_V(8); PG8_WAIT_L(0); PG8_BAR; PG8_MMA(0, 0, At, B0); PG8_MMA(0, 1, At, B1); PG8_BAR; PG8_SCHED;
;             PG8_LDA(At, 1, 1); PG8_STAGE(PG8_SB(1, 0), b3, voffB); PG8_STAGE(PG8_SB(1, 1), b3 + hstepB, voffB); PG8_STAGE(PG8_SA(1, 0), a3, voffA);
;             PG8_WAIT_V(8); PG8_WAIT_L(0); PG8_BAR; PG8_MMA(1, 0, At, B0); PG8_MMA(1, 1, At, B1); PG8_BAR; PG8_SCHED;
	s_add_i32 s95, 0, 0x18000
	v_add_u32_e32 v149, s95, v147
	s_add_i32 s96, 0, 0x1c000
	ds_read_b128 v[142:145], v149
	ds_read_b128 v[150:153], v149 offset:1024
	ds_read_b128 v[154:157], v149 offset:2048
	ds_read_b128 v[158:161], v149 offset:3072
	v_add_u32_e32 v149, s96, v147
	ds_read_b128 v[162:165], v149
	ds_read_b128 v[166:169], v149 offset:1024
	ds_read_b128 v[170:173], v149 offset:2048
	ds_read_b128 v[174:177], v149 offset:3072
	s_add_u32 s40, s40, 0x80000
	s_addc_u32 s41, s41, 0
	s_mov_b32 m0, s37
	ds_read_b128 v[178:181], v148 offset:32768
	ds_read_b128 v[182:185], v148 offset:33792
	ds_read_b128 v[186:189], v148 offset:34816
	ds_read_b128 v[190:193], v148 offset:35840
	ds_read_b128 v[194:197], v148 offset:36864
	ds_read_b128 v[198:201], v148 offset:37888
	ds_read_b128 v[202:205], v148 offset:38912
	ds_read_b128 v[206:209], v148 offset:39936
	global_load_lds_dwordx4 v130, s[40:41]
	v_lshl_add_u64 v[218:219], s[40:41], 0, v[134:135]
	s_mov_b32 m0, s42
	s_nop 0
	global_load_lds_dwordx4 v[218:219], off
	s_waitcnt vmcnt(8)
	s_waitcnt lgkmcnt(0)
	s_barrier
	s_waitcnt lgkmcnt(0)
	v_mfma_f32_16x16x32_bf16 v[126:129], v[142:145], v[178:181], v[126:129]
	v_mfma_f32_16x16x32_bf16 v[122:125], v[154:157], v[178:181], v[122:125]
	v_mfma_f32_16x16x32_bf16 v[110:113], v[142:145], v[186:189], v[110:113]
	v_mfma_f32_16x16x32_bf16 v[106:109], v[154:157], v[186:189], v[106:109]
	v_mfma_f32_16x16x32_bf16 v[94:97], v[142:145], v[194:197], v[94:97]
	v_mfma_f32_16x16x32_bf16 v[90:93], v[154:157], v[194:197], v[90:93]
	v_mfma_f32_16x16x32_bf16 v[78:81], v[142:145], v[202:205], v[78:81]
	v_mfma_f32_16x16x32_bf16 v[74:77], v[154:157], v[202:205], v[74:77]
	v_mfma_f32_16x16x32_bf16 v[126:129], v[150:153], v[182:185], v[126:129]
	v_mfma_f32_16x16x32_bf16 v[122:125], v[158:161], v[182:185], v[122:125]
	v_mfma_f32_16x16x32_bf16 v[110:113], v[150:153], v[190:193], v[110:113]
	v_mfma_f32_16x16x32_bf16 v[106:109], v[158:161], v[190:193], v[106:109]
	v_mfma_f32_16x16x32_bf16 v[94:97], v[150:153], v[198:201], v[94:97]
	v_mfma_f32_16x16x32_bf16 v[90:93], v[158:161], v[198:201], v[90:93]
	v_mfma_f32_16x16x32_bf16 v[78:81], v[150:153], v[206:209], v[78:81]
	v_mfma_f32_16x16x32_bf16 v[74:77], v[158:161], v[206:209], v[74:77]
	v_mfma_f32_16x16x32_bf16 v[118:121], v[162:165], v[178:181], v[118:121]
	v_mfma_f32_16x16x32_bf16 v[114:117], v[170:173], v[178:181], v[114:117]
	v_mfma_f32_16x16x32_bf16 v[102:105], v[162:165], v[186:189], v[102:105]
	v_mfma_f32_16x16x32_bf16 v[98:101], v[170:173], v[186:189], v[98:101]
	v_mfma_f32_16x16x32_bf16 v[86:89], v[162:165], v[194:197], v[86:89]
	v_mfma_f32_16x16x32_bf16 v[82:85], v[170:173], v[194:197], v[82:85]
	v_mfma_f32_16x16x32_bf16 v[70:73], v[162:165], v[202:205], v[70:73]
	v_mfma_f32_16x16x32_bf16 v[66:69], v[170:173], v[202:205], v[66:69]
	v_mfma_f32_16x16x32_bf16 v[118:121], v[166:169], v[182:185], v[118:121]
	v_mfma_f32_16x16x32_bf16 v[114:117], v[174:177], v[182:185], v[114:117]
	v_mfma_f32_16x16x32_bf16 v[102:105], v[166:169], v[190:193], v[102:105]
	v_mfma_f32_16x16x32_bf16 v[98:101], v[174:177], v[190:193], v[98:101]
	v_mfma_f32_16x16x32_bf16 v[86:89], v[166:169], v[198:201], v[86:89]
	v_mfma_f32_16x16x32_bf16 v[82:85], v[174:177], v[198:201], v[82:85]
	v_mfma_f32_16x16x32_bf16 v[70:73], v[166:169], v[206:209], v[70:73]
	v_mfma_f32_16x16x32_bf16 v[66:69], v[174:177], v[206:209], v[66:69]
	s_barrier
	s_add_i32 s40, s95, s34
	v_lshl_add_u64 v[210:211], v[210:211], 0, s[60:61]
	s_mov_b32 m0, s40
	ds_read_b128 v[178:181], v148 offset:49152
	ds_read_b128 v[182:185], v148 offset:50176
	ds_read_b128 v[186:189], v148 offset:51200
	ds_read_b128 v[190:193], v148 offset:52224
	ds_read_b128 v[194:197], v148 offset:53248
	ds_read_b128 v[198:201], v148 offset:54272
	ds_read_b128 v[202:205], v148 offset:55296
	ds_read_b128 v[206:209], v148 offset:56320
	global_load_lds_dwordx4 v[210:211], off
	s_add_i32 m0, s40, 0x2000
	s_add_u32 s30, s30, 0x80080
	v_lshl_add_u64 v[210:211], v[212:213], 0, s[60:61]
	s_addc_u32 s31, s31, 0
	s_add_i32 s40, s96, s34
	global_load_lds_dwordx4 v[210:211], off
	s_mov_b32 m0, s40
	s_nop 0
	global_load_lds_dwordx4 v132, s[30:31]
	s_add_i32 m0, s40, 0x2000
	s_nop 0
	global_load_lds_dwordx4 v136, s[30:31]
	v_lshl_add_u64 v[210:211], v[214:215], 0, s[60:61]
	s_mov_b32 m0, s45
	s_nop 0
	global_load_lds_dwordx4 v[210:211], off
	v_lshl_add_u64 v[210:211], v[216:217], 0, s[60:61]
	s_mov_b32 m0, s46
	s_nop 0
	global_load_lds_dwordx4 v[210:211], off
	s_waitcnt vmcnt(8)
	s_waitcnt lgkmcnt(0)
	s_barrier
	s_waitcnt lgkmcnt(0)
	v_mfma_f32_16x16x32_bf16 v[62:65], v[142:145], v[178:181], v[62:65]
	v_mfma_f32_16x16x32_bf16 v[58:61], v[154:157], v[178:181], v[58:61]
	v_mfma_f32_16x16x32_bf16 v[46:49], v[142:145], v[186:189], v[46:49]
	v_mfma_f32_16x16x32_bf16 v[42:45], v[154:157], v[186:189], v[42:45]
	v_mfma_f32_16x16x32_bf16 v[30:33], v[142:145], v[194:197], v[30:33]
	v_mfma_f32_16x16x32_bf16 v[26:29], v[154:157], v[194:197], v[26:29]
	v_mfma_f32_16x16x32_bf16 v[14:17], v[142:145], v[202:205], v[14:17]
	v_mfma_f32_16x16x32_bf16 v[10:13], v[154:157], v[202:205], v[10:13]
	v_mfma_f32_16x16x32_bf16 v[62:65], v[150:153], v[182:185], v[62:65]
	v_mfma_f32_16x16x32_bf16 v[58:61], v[158:161], v[182:185], v[58:61]
	v_mfma_f32_16x16x32_bf16 v[46:49], v[150:153], v[190:193], v[46:49]
	v_mfma_f32_16x16x32_bf16 v[42:45], v[158:161], v[190:193], v[42:45]
	v_mfma_f32_16x16x32_bf16 v[30:33], v[150:153], v[198:201], v[30:33]
	v_mfma_f32_16x16x32_bf16 v[26:29], v[158:161], v[198:201], v[26:29]
	v_mfma_f32_16x16x32_bf16 v[14:17], v[150:153], v[206:209], v[14:17]
	v_mfma_f32_16x16x32_bf16 v[10:13], v[158:161], v[206:209], v[10:13]
	v_mfma_f32_16x16x32_bf16 v[54:57], v[162:165], v[178:181], v[54:57]
	v_mfma_f32_16x16x32_bf16 v[50:53], v[170:173], v[178:181], v[50:53]
	v_mfma_f32_16x16x32_bf16 v[38:41], v[162:165], v[186:189], v[38:41]
	v_mfma_f32_16x16x32_bf16 v[34:37], v[170:173], v[186:189], v[34:37]
	v_mfma_f32_16x16x32_bf16 v[22:25], v[162:165], v[194:197], v[22:25]
	v_mfma_f32_16x16x32_bf16 v[18:21], v[170:173], v[194:197], v[18:21]
	v_mfma_f32_16x16x32_bf16 v[6:9], v[162:165], v[202:205], v[6:9]
	v_mfma_f32_16x16x32_bf16 v[2:5], v[170:173], v[202:205], v[2:5]
	v_mfma_f32_16x16x32_bf16 v[54:57], v[166:169], v[182:185], v[54:57]
	v_mfma_f32_16x16x32_bf16 v[50:53], v[174:177], v[182:185], v[50:53]
	v_mfma_f32_16x16x32_bf16 v[38:41], v[166:169], v[190:193], v[38:41]
	v_mfma_f32_16x16x32_bf16 v[34:37], v[174:177], v[190:193], v[34:37]
	v_mfma_f32_16x16x32_bf16 v[22:25], v[166:169], v[198:201], v[22:25]
	v_mfma_f32_16x16x32_bf16 v[18:21], v[174:177], v[198:201], v[18:21]
	v_mfma_f32_16x16x32_bf16 v[6:9], v[166:169], v[206:209], v[6:9]
	v_mfma_f32_16x16x32_bf16 v[2:5], v[174:177], v[206:209], v[2:5]
	s_barrier
	s_add_i32 s94, s94, 2
	s_add_u32 s4, s4, 0x100
	s_addc_u32 s5, s5, 0
	s_add_u32 s15, s15, 0x100
	s_addc_u32 s21, s21, 0
	s_cmp_gt_u32 s94, 29
	s_cbranch_scc0 .LBB0_412
	s_and_b64 vcc, exec, s[12:13]
	s_cbranch_vccz .LBB0_415
	s_barrier

; #define PG8_STAGE(bufoff, gbase, voff) do { _Pragma("unroll") for (int _i = 0; _i < 2; ++_i) \
;         __builtin_amdgcn_global_load_lds((const unsigned*)((const char*)(gbase) + (voff)[_i]), (PG8_LAS unsigned*)(lds + (bufoff) + ldsw + _i * 8192), 16, 0, 0); } while (0)
; #define PG8_LDA(dst, b, h) do { _Pragma("unroll") for (int m = 0; m < 4; ++m) _Pragma("unroll") for (int k = 0; k < 2; ++k) dst[m][k] = *(const PG8_LAS bf16x8*)(lds + PG8_SA(b, h) + aoff + m * 2048 + k * 1024); } while (0)
; #define PG8_LDB(dst, b, h) do { _Pragma("unroll") for (int n = 0; n < 2; ++n) _Pragma("unroll") for (int k = 0; k < 2; ++k) dst[n][k] = *(const PG8_LAS bf16x8*)(lds + PG8_SB(b, h) + boff + n * 2048 + k * 1024); } while (0)
; #define PG8_WAIT_V(n) asm volatile("s_waitcnt vmcnt(" #n ")" ::: "memory")
; #define PG8_WAIT_L(n) asm volatile("s_waitcnt lgkmcnt(" #n ")" ::: "memory")
; #define PG8_BAR __builtin_amdgcn_s_barrier()
; #define PG8_SCHED __builtin_amdgcn_sched_barrier(0)
; template <class Epi, class Sched, bool ALIGN_EPI = false, bool SP2 = false>
; __device__ __forceinline__ void gemm_phase(PG8_LAS unsigned char* lds, const Gemm g, const Sched& S, const Epi& E, int wave_s) {
;     ...
;         const bool has_next = S.next(ui + 1, nxt);
;         const char* nA = has_next ? (const char*)g.A + (size_t)nxt.pm * tstepA + (size_t)(nxt.pn / g.npg) * (size_t)(K * 2) : cA; const char* nB = has_next ? (const char*)g.Bt + (size_t)nxt.pn * tstepB : cB;
;         for (int t = 0; t < nt; t += 2) {
;             const bool last = (t == nt - 2);
;             const char* a1 = cA + (size_t)(t + 1) * kstep;
;             const char* a2 = last ? nA : cA + (size_t)(t + 2) * kstep; const char* b2 = last ? nB : cB + (size_t)(t + 2) * kstep;
;             const char* a3 = a2 + kstep; const char* b3 = b2 + kstep;
;             if (last && has_next) S.a_ready(nxt);
;             if constexpr (SP2) {
;             PG8_LDB(B0, 0, 0); PG8_LDB(B1, 0, 1); PG8_SCHED; PG8_LDA(At, 0, 0); PG8_STAGE(PG8_SA(1, 1), a1 + hstepA, voffA);
;             PG8_WAIT_V(8); PG8_WAIT_L(0); PG8_BAR; PG8_MMA(0, 0, At, B0); PG8_MMA(0, 1, At, B1); PG8_BAR; PG8_SCHED;
;             PG8_LDA(At, 0, 1); PG8_STAGE(PG8_SB(0, 0), b2, voffB); PG8_STAGE(PG8_SB(0, 1), b2 + hstepB, voffB); PG8_STAGE(PG8_SA(0, 0), a2, voffA);
.LBB0_601:
	s_ashr_i32 s21, s20, 31
	s_lshl_b64 s[2:3], s[20:21], 20
	s_add_u32 s88, s22, s2
	s_addc_u32 s89, s23, s3
	s_and_b64 s[2:3], s[4:5], exec
	s_cselect_b32 s2, s89, s31
	s_cselect_b32 s3, s88, s30
	s_add_u32 s4, s40, 0x80080
	s_addc_u32 s5, s41, 0
	s_add_u32 s21, s30, 0x100
	s_addc_u32 s27, s31, 0
	s_mov_b32 s81, -2
	s_add_u32 s30, s4, 0xfff80080
	s_addc_u32 s31, s5, -1
	s_add_i32 s84, 0, 0x10000
	s_cmp_eq_u32 s81, 28
	s_cselect_b32 s41, s29, s31
	s_cselect_b32 s40, s28, s30
	s_cselect_b32 s31, s2, s27
	s_cselect_b32 s30, s3, s21
	s_add_i32 s90, 0, 0x14000
	v_add_u32_e32 v134, s84, v207
	v_add_u32_e32 v158, s90, v207
	ds_read_b128 v[118:121], v134
	ds_read_b128 v[126:129], v134 offset:1024
	ds_read_b128 v[130:133], v134 offset:2048
	ds_read_b128 v[134:137], v134 offset:3072
	ds_read_b128 v[138:141], v158
	ds_read_b128 v[142:145], v158 offset:1024
	ds_read_b128 v[154:157], v158 offset:2048
	ds_read_b128 v[158:161], v158 offset:3072
	s_add_i32 m0, s35, 0xc000
	ds_read_b128 v[162:165], v208
	ds_read_b128 v[166:169], v208 offset:1024
	ds_read_b128 v[170:173], v208 offset:2048
	ds_read_b128 v[174:177], v208 offset:3072
	ds_read_b128 v[178:181], v208 offset:4096
	ds_read_b128 v[182:185], v208 offset:5120
	ds_read_b128 v[186:189], v208 offset:6144
	ds_read_b128 v[202:205], v208 offset:7168
	global_load_lds_dwordx4 v198, s[4:5]
	s_add_i32 m0, s35, 0xe000
	s_nop 0
	global_load_lds_dwordx4 v200, s[4:5]
	s_waitcnt vmcnt(8)
	s_waitcnt lgkmcnt(0)
	s_barrier
	s_waitcnt lgkmcnt(0)
	v_mfma_f32_16x16x32_bf16 v[150:153], v[118:121], v[162:165], 0
	v_mfma_f32_16x16x32_bf16 v[146:149], v[130:133], v[162:165], 0
	v_mfma_f32_16x16x32_bf16 v[110:113], v[118:121], v[170:173], 0
	v_mfma_f32_16x16x32_bf16 v[106:109], v[130:133], v[170:173], 0
	v_mfma_f32_16x16x32_bf16 v[94:97], v[118:121], v[178:181], 0
	v_mfma_f32_16x16x32_bf16 v[90:93], v[130:133], v[178:181], 0
	v_mfma_f32_16x16x32_bf16 v[78:81], v[118:121], v[186:189], 0
	v_mfma_f32_16x16x32_bf16 v[74:77], v[130:133], v[186:189], 0
	v_mfma_f32_16x16x32_bf16 v[150:153], v[126:129], v[166:169], v[150:153]
	v_mfma_f32_16x16x32_bf16 v[146:149], v[134:137], v[166:169], v[146:149]
	v_mfma_f32_16x16x32_bf16 v[110:113], v[126:129], v[174:177], v[110:113]
	v_mfma_f32_16x16x32_bf16 v[106:109], v[134:137], v[174:177], v[106:109]
	v_mfma_f32_16x16x32_bf16 v[94:97], v[126:129], v[182:185], v[94:97]
	v_mfma_f32_16x16x32_bf16 v[90:93], v[134:137], v[182:185], v[90:93]
	v_mfma_f32_16x16x32_bf16 v[78:81], v[126:129], v[202:205], v[78:81]
	v_mfma_f32_16x16x32_bf16 v[74:77], v[134:137], v[202:205], v[74:77]
	v_mfma_f32_16x16x32_bf16 v[122:125], v[138:141], v[162:165], 0
	v_mfma_f32_16x16x32_bf16 v[114:117], v[154:157], v[162:165], 0
	v_mfma_f32_16x16x32_bf16 v[102:105], v[138:141], v[170:173], 0
	v_mfma_f32_16x16x32_bf16 v[98:101], v[154:157], v[170:173], 0
	v_mfma_f32_16x16x32_bf16 v[86:89], v[138:141], v[178:181], 0
	v_mfma_f32_16x16x32_bf16 v[82:85], v[154:157], v[178:181], 0
	v_mfma_f32_16x16x32_bf16 v[70:73], v[138:141], v[186:189], 0
	v_mfma_f32_16x16x32_bf16 v[66:69], v[154:157], v[186:189], 0
	v_mfma_f32_16x16x32_bf16 v[122:125], v[142:145], v[166:169], v[122:125]
	v_mfma_f32_16x16x32_bf16 v[114:117], v[158:161], v[166:169], v[114:117]
	v_mfma_f32_16x16x32_bf16 v[102:105], v[142:145], v[174:177], v[102:105]
	v_mfma_f32_16x16x32_bf16 v[98:101], v[158:161], v[174:177], v[98:101]
	v_mfma_f32_16x16x32_bf16 v[86:89], v[142:145], v[182:185], v[86:89]
	v_mfma_f32_16x16x32_bf16 v[82:85], v[158:161], v[182:185], v[82:85]
	v_mfma_f32_16x16x32_bf16 v[70:73], v[142:145], v[202:205], v[70:73]
	v_mfma_f32_16x16x32_bf16 v[66:69], v[158:161], v[202:205], v[66:69]
	s_barrier
	s_add_i32 s84, s84, s34
	v_lshl_add_u64 v[210:211], s[30:31], 0, v[194:195]
	s_mov_b32 m0, s84
	ds_read_b128 v[162:165], v208 offset:16384
	ds_read_b128 v[166:169], v208 offset:17408
	ds_read_b128 v[170:173], v208 offset:18432
	ds_read_b128 v[174:177], v208 offset:19456
	ds_read_b128 v[178:181], v208 offset:20480
	ds_read_b128 v[182:185], v208 offset:21504
	ds_read_b128 v[186:189], v208 offset:22528
	ds_read_b128 v[202:205], v208 offset:23552
	global_load_lds_dwordx4 v[210:211], off
	s_add_i32 m0, s84, 0x2000
	s_add_u32 s84, s30, 0x80000
	v_lshl_add_u64 v[212:213], s[30:31], 0, v[190:191]
	s_addc_u32 s85, s31, 0
	s_add_i32 s90, s90, s34
	global_load_lds_dwordx4 v[212:213], off
	s_mov_b32 m0, s90
	v_lshl_add_u64 v[216:217], s[40:41], 0, v[192:193]
	global_load_lds_dwordx4 v194, s[84:85]
	s_add_i32 m0, s90, 0x2000
	s_nop 0
	global_load_lds_dwordx4 v190, s[84:85]
	v_lshl_add_u64 v[214:215], s[40:41], 0, v[196:197]
	s_mov_b32 m0, s35
	s_nop 0
	global_load_lds_dwordx4 v[214:215], off
	s_mov_b32 m0, s36
	s_nop 0
	global_load_lds_dwordx4 v[216:217], off
	s_waitcnt vmcnt(8)
	s_waitcnt lgkmcnt(0)
	s_barrier
; #define PG8_STAGE(bufoff, gbase, voff) do { _Pragma("unroll") for (int _i = 0; _i < 2; ++_i) \
;         __builtin_amdgcn_global_load_lds((const unsigned*)((const char*)(gbase) + (voff)[_i]), (PG8_LAS unsigned*)(lds + (bufoff) + ldsw + _i * 8192), 16, 0, 0); } while (0)
; #define PG8_LDA(dst, b, h) do { _Pragma("unroll") for (int m = 0; m < 4; ++m) _Pragma("unroll") for (int k = 0; k < 2; ++k) dst[m][k] = *(const PG8_LAS bf16x8*)(lds + PG8_SA(b, h) + aoff + m * 2048 + k * 1024); } while (0)
; #define PG8_LDB(dst, b, h) do { _Pragma("unroll") for (int n = 0; n < 2; ++n) _Pragma("unroll") for (int k = 0; k < 2; ++k) dst[n][k] = *(const PG8_LAS bf16x8*)(lds + PG8_SB(b, h) + boff + n * 2048 + k * 1024); } while (0)
; #define PG8_MMA(ai, bj, At, Bt) do { __builtin_amdgcn_s_setprio(1); _Pragma("unroll") for (int m = 0; m < 4; ++m) _Pragma("unroll") for (int n = 0; n < 2; ++n) _Pragma("unroll") for (int k = 0; k < 2; ++k) \
;         acc[ai][bj][m][n] = __builtin_amdgcn_mfma_f32_16x16x32_bf16(Bt[n][k], At[m][k], acc[ai][bj][m][n], 0, 0, 0); __builtin_amdgcn_s_setprio(0); } while (0)
; #define PG8_WAIT_V(n) asm volatile("s_waitcnt vmcnt(" #n ")" ::: "memory")
; #define PG8_WAIT_L(n) asm volatile("s_waitcnt lgkmcnt(" #n ")" ::: "memory")
; #define PG8_BAR __builtin_amdgcn_s_barrier()
; #define PG8_SCHED __builtin_amdgcn_sched_barrier(0)
; template <class Epi, class Sched, bool ALIGN_EPI = false, bool SP2 = false>
; __device__ __forceinline__ void gemm_phase(PG8_LAS unsigned char* lds, const Gemm g, const Sched& S, const Epi& E, int wave_s) {
;     ...
;             PG8_LDA(At, 0, 1); PG8_STAGE(PG8_SB(0, 0), b2, voffB); PG8_STAGE(PG8_SB(0, 1), b2 + hstepB, voffB); PG8_STAGE(PG8_SA(0, 0), a2, voffA);
;             PG8_WAIT_V(8); PG8_WAIT_L(0); PG8_BAR; PG8_MMA(1, 0, At, B0); PG8_MMA(1, 1, At, B1); PG8_BAR; PG8_SCHED;
;             PG8_LDB(B0, 1, 0); PG8_LDB(B1, 1, 1); PG8_SCHED; PG8_LDA(At, 1, 0); PG8_STAGE(PG8_SA(0, 1), a2 + hstepA, voffA);
;             PG8_WAIT_V(8); PG8_WAIT_L(0); PG8_BAR; PG8_MMA(0, 0, At, B0); PG8_MMA(0, 1, At, B1); PG8_BAR; PG8_SCHED;
	s_waitcnt lgkmcnt(0)
	v_mfma_f32_16x16x32_bf16 v[62:65], v[118:121], v[162:165], 0
	v_mfma_f32_16x16x32_bf16 v[58:61], v[130:133], v[162:165], 0
	v_mfma_f32_16x16x32_bf16 v[46:49], v[118:121], v[170:173], 0
	v_mfma_f32_16x16x32_bf16 v[42:45], v[130:133], v[170:173], 0
	v_mfma_f32_16x16x32_bf16 v[30:33], v[118:121], v[178:181], 0
	v_mfma_f32_16x16x32_bf16 v[26:29], v[130:133], v[178:181], 0
	v_mfma_f32_16x16x32_bf16 v[14:17], v[118:121], v[186:189], 0
	v_mfma_f32_16x16x32_bf16 v[10:13], v[130:133], v[186:189], 0
	v_mfma_f32_16x16x32_bf16 v[62:65], v[126:129], v[166:169], v[62:65]
	v_mfma_f32_16x16x32_bf16 v[58:61], v[134:137], v[166:169], v[58:61]
	v_mfma_f32_16x16x32_bf16 v[46:49], v[126:129], v[174:177], v[46:49]
	v_mfma_f32_16x16x32_bf16 v[42:45], v[134:137], v[174:177], v[42:45]
	v_mfma_f32_16x16x32_bf16 v[30:33], v[126:129], v[182:185], v[30:33]
	v_mfma_f32_16x16x32_bf16 v[26:29], v[134:137], v[182:185], v[26:29]
	v_mfma_f32_16x16x32_bf16 v[14:17], v[126:129], v[202:205], v[14:17]
	v_mfma_f32_16x16x32_bf16 v[10:13], v[134:137], v[202:205], v[10:13]
	v_mfma_f32_16x16x32_bf16 v[54:57], v[138:141], v[162:165], 0
	v_mfma_f32_16x16x32_bf16 v[50:53], v[154:157], v[162:165], 0
	v_mfma_f32_16x16x32_bf16 v[38:41], v[138:141], v[170:173], 0
	v_mfma_f32_16x16x32_bf16 v[34:37], v[154:157], v[170:173], 0
	v_mfma_f32_16x16x32_bf16 v[22:25], v[138:141], v[178:181], 0
	v_mfma_f32_16x16x32_bf16 v[18:21], v[154:157], v[178:181], 0
	v_mfma_f32_16x16x32_bf16 v[6:9], v[138:141], v[186:189], 0
	v_mfma_f32_16x16x32_bf16 v[2:5], v[154:157], v[186:189], 0
	v_mfma_f32_16x16x32_bf16 v[54:57], v[142:145], v[166:169], v[54:57]
	v_mfma_f32_16x16x32_bf16 v[50:53], v[158:161], v[166:169], v[50:53]
	v_mfma_f32_16x16x32_bf16 v[38:41], v[142:145], v[174:177], v[38:41]
	v_mfma_f32_16x16x32_bf16 v[34:37], v[158:161], v[174:177], v[34:37]
	v_mfma_f32_16x16x32_bf16 v[22:25], v[142:145], v[182:185], v[22:25]
	v_mfma_f32_16x16x32_bf16 v[18:21], v[158:161], v[182:185], v[18:21]
	v_mfma_f32_16x16x32_bf16 v[6:9], v[142:145], v[202:205], v[6:9]
	v_mfma_f32_16x16x32_bf16 v[2:5], v[158:161], v[202:205], v[2:5]
	s_barrier
	s_add_i32 s84, 0, 0x18000
	s_add_i32 s85, 0, 0x1c000
	v_add_u32_e32 v134, s84, v207
	v_add_u32_e32 v158, s85, v207
	ds_read_b128 v[118:121], v134
	ds_read_b128 v[126:129], v134 offset:1024
	ds_read_b128 v[130:133], v134 offset:2048
	ds_read_b128 v[134:137], v134 offset:3072
	ds_read_b128 v[138:141], v158
	ds_read_b128 v[142:145], v158 offset:1024
	ds_read_b128 v[154:157], v158 offset:2048
	ds_read_b128 v[158:161], v158 offset:3072
	s_add_u32 s40, s40, 0x80000
	s_addc_u32 s41, s41, 0
	s_mov_b32 m0, s37
	ds_read_b128 v[162:165], v208 offset:32768
	ds_read_b128 v[166:169], v208 offset:33792
	ds_read_b128 v[170:173], v208 offset:34816
	ds_read_b128 v[174:177], v208 offset:35840
	ds_read_b128 v[178:181], v208 offset:36864
	ds_read_b128 v[182:185], v208 offset:37888
	ds_read_b128 v[186:189], v208 offset:38912
	ds_read_b128 v[202:205], v208 offset:39936
	global_load_lds_dwordx4 v196, s[40:41]
	s_mov_b32 m0, s42
	s_nop 0
	global_load_lds_dwordx4 v192, s[40:41]
	s_waitcnt vmcnt(8)
	s_waitcnt lgkmcnt(0)
	s_barrier
	s_waitcnt lgkmcnt(0)
	v_mfma_f32_16x16x32_bf16 v[150:153], v[118:121], v[162:165], v[150:153]
	v_mfma_f32_16x16x32_bf16 v[146:149], v[130:133], v[162:165], v[146:149]
	v_mfma_f32_16x16x32_bf16 v[110:113], v[118:121], v[170:173], v[110:113]
	v_mfma_f32_16x16x32_bf16 v[106:109], v[130:133], v[170:173], v[106:109]
	v_mfma_f32_16x16x32_bf16 v[94:97], v[118:121], v[178:181], v[94:97]
	v_mfma_f32_16x16x32_bf16 v[90:93], v[130:133], v[178:181], v[90:93]
	v_mfma_f32_16x16x32_bf16 v[78:81], v[118:121], v[186:189], v[78:81]
	v_mfma_f32_16x16x32_bf16 v[74:77], v[130:133], v[186:189], v[74:77]
	v_mfma_f32_16x16x32_bf16 v[150:153], v[126:129], v[166:169], v[150:153]
	v_mfma_f32_16x16x32_bf16 v[146:149], v[134:137], v[166:169], v[146:149]
	v_mfma_f32_16x16x32_bf16 v[110:113], v[126:129], v[174:177], v[110:113]
	v_mfma_f32_16x16x32_bf16 v[106:109], v[134:137], v[174:177], v[106:109]
	v_mfma_f32_16x16x32_bf16 v[94:97], v[126:129], v[182:185], v[94:97]
	v_mfma_f32_16x16x32_bf16 v[90:93], v[134:137], v[182:185], v[90:93]
	v_mfma_f32_16x16x32_bf16 v[78:81], v[126:129], v[202:205], v[78:81]
	v_mfma_f32_16x16x32_bf16 v[74:77], v[134:137], v[202:205], v[74:77]
	v_mfma_f32_16x16x32_bf16 v[122:125], v[138:141], v[162:165], v[122:125]
	v_mfma_f32_16x16x32_bf16 v[114:117], v[154:157], v[162:165], v[114:117]
	v_mfma_f32_16x16x32_bf16 v[102:105], v[138:141], v[170:173], v[102:105]
	v_mfma_f32_16x16x32_bf16 v[98:101], v[154:157], v[170:173], v[98:101]
	v_mfma_f32_16x16x32_bf16 v[86:89], v[138:141], v[178:181], v[86:89]
	v_mfma_f32_16x16x32_bf16 v[82:85], v[154:157], v[178:181], v[82:85]
	v_mfma_f32_16x16x32_bf16 v[70:73], v[138:141], v[186:189], v[70:73]
	v_mfma_f32_16x16x32_bf16 v[66:69], v[154:157], v[186:189], v[66:69]
	v_mfma_f32_16x16x32_bf16 v[122:125], v[142:145], v[166:169], v[122:125]
	v_mfma_f32_16x16x32_bf16 v[114:117], v[158:161], v[166:169], v[114:117]
	v_mfma_f32_16x16x32_bf16 v[102:105], v[142:145], v[174:177], v[102:105]
	v_mfma_f32_16x16x32_bf16 v[98:101], v[158:161], v[174:177], v[98:101]
	v_mfma_f32_16x16x32_bf16 v[86:89], v[142:145], v[182:185], v[86:89]
	v_mfma_f32_16x16x32_bf16 v[82:85], v[158:161], v[182:185], v[82:85]
	v_mfma_f32_16x16x32_bf16 v[70:73], v[142:145], v[202:205], v[70:73]
	v_mfma_f32_16x16x32_bf16 v[66:69], v[158:161], v[202:205], v[66:69]
	s_barrier
; #define PG8_STAGE(bufoff, gbase, voff) do { _Pragma("unroll") for (int _i = 0; _i < 2; ++_i) \
;         __builtin_amdgcn_global_load_lds((const unsigned*)((const char*)(gbase) + (voff)[_i]), (PG8_LAS unsigned*)(lds + (bufoff) + ldsw + _i * 8192), 16, 0, 0); } while (0)
; #define PG8_LDA(dst, b, h) do { _Pragma("unroll") for (int m = 0; m < 4; ++m) _Pragma("unroll") for (int k = 0; k < 2; ++k) dst[m][k] = *(const PG8_LAS bf16x8*)(lds + PG8_SA(b, h) + aoff + m * 2048 + k * 1024); } while (0)
; #define PG8_WAIT_V(n) asm volatile("s_waitcnt vmcnt(" #n ")" ::: "memory")
; #define PG8_WAIT_L(n) asm volatile("s_waitcnt lgkmcnt(" #n ")" ::: "memory")
; #define PG8_BAR __builtin_amdgcn_s_barrier()
; template <class Epi, class Sched, bool ALIGN_EPI = false, bool SP2 = false>
; __device__ __forceinline__ void gemm_phase(PG8_LAS unsigned char* lds, const Gemm g, const Sched& S, const Epi& E, int wave_s) {
;     ...
;         for (int t = 0; t < nt; t += 2) {
;             const bool last = (t == nt - 2);
;             const char* a1 = cA + (size_t)(t + 1) * kstep;
;             const char* a2 = last ? nA : cA + (size_t)(t + 2) * kstep; const char* b2 = last ? nB : cB + (size_t)(t + 2) * kstep;
;             const char* a3 = a2 + kstep; const char* b3 = b2 + kstep;
;             if (last && has_next) S.a_ready(nxt);
;             if constexpr (SP2) {
;             PG8_LDB(B0, 0, 0); PG8_LDB(B1, 0, 1); PG8_SCHED; PG8_LDA(At, 0, 0); PG8_STAGE(PG8_SA(1, 1), a1 + hstepA, voffA);
;             PG8_WAIT_V(8); PG8_WAIT_L(0); PG8_BAR; PG8_MMA(0, 0, At, B0); PG8_MMA(0, 1, At, B1); PG8_BAR; PG8_SCHED;
;             PG8_LDA(At, 0, 1); PG8_STAGE(PG8_SB(0, 0), b2, voffB); PG8_STAGE(PG8_SB(0, 1), b2 + hstepB, voffB); PG8_STAGE(PG8_SA(0, 0), a2, voffA);
;             PG8_WAIT_V(8); PG8_WAIT_L(0); PG8_BAR; PG8_MMA(1, 0, At, B0); PG8_MMA(1, 1, At, B1); PG8_BAR; PG8_SCHED;
;             PG8_LDB(B0, 1, 0); PG8_LDB(B1, 1, 1); PG8_SCHED; PG8_LDA(At, 1, 0); PG8_STAGE(PG8_SA(0, 1), a2 + hstepA, voffA);
;             PG8_WAIT_V(8); PG8_WAIT_L(0); PG8_BAR; PG8_MMA(0, 0, At, B0); PG8_MMA(0, 1, At, B1); PG8_BAR; PG8_SCHED;
;             PG8_LDA(At, 1, 1); PG8_STAGE(PG8_SB(1, 0), b3, voffB); PG8_STAGE(PG8_SB(1, 1), b3 + hstepB, voffB); PG8_STAGE(PG8_SA(1, 0), a3, voffA);
;             PG8_WAIT_V(8); PG8_WAIT_L(0); PG8_BAR; PG8_MMA(1, 0, At, B0); PG8_MMA(1, 1, At, B1); PG8_BAR; PG8_SCHED;
	s_add_i32 s40, s84, s34
	v_lshl_add_u64 v[210:211], v[210:211], 0, s[60:61]
	s_mov_b32 m0, s40
	ds_read_b128 v[162:165], v208 offset:49152
	ds_read_b128 v[166:169], v208 offset:50176
	ds_read_b128 v[170:173], v208 offset:51200
	ds_read_b128 v[174:177], v208 offset:52224
	ds_read_b128 v[178:181], v208 offset:53248
	ds_read_b128 v[182:185], v208 offset:54272
	ds_read_b128 v[186:189], v208 offset:55296
	ds_read_b128 v[202:205], v208 offset:56320
	global_load_lds_dwordx4 v[210:211], off
	s_add_i32 m0, s40, 0x2000
	s_add_u32 s30, s30, 0x80080
	v_lshl_add_u64 v[210:211], v[212:213], 0, s[60:61]
	s_addc_u32 s31, s31, 0
	s_add_i32 s40, s85, s34
	global_load_lds_dwordx4 v[210:211], off
	s_mov_b32 m0, s40
	s_nop 0
	global_load_lds_dwordx4 v194, s[30:31]
	s_add_i32 m0, s40, 0x2000
	s_nop 0
	global_load_lds_dwordx4 v190, s[30:31]
	v_lshl_add_u64 v[210:211], v[214:215], 0, s[60:61]
	s_mov_b32 m0, s46
	s_nop 0
	global_load_lds_dwordx4 v[210:211], off
	v_lshl_add_u64 v[210:211], v[216:217], 0, s[60:61]
	s_mov_b32 m0, s47
	s_nop 0
	global_load_lds_dwordx4 v[210:211], off
	s_waitcnt vmcnt(8)
	s_waitcnt lgkmcnt(0)
	s_barrier
	s_waitcnt lgkmcnt(0)
	v_mfma_f32_16x16x32_bf16 v[62:65], v[118:121], v[162:165], v[62:65]
	v_mfma_f32_16x16x32_bf16 v[58:61], v[130:133], v[162:165], v[58:61]
	v_mfma_f32_16x16x32_bf16 v[46:49], v[118:121], v[170:173], v[46:49]
	v_mfma_f32_16x16x32_bf16 v[42:45], v[130:133], v[170:173], v[42:45]
	v_mfma_f32_16x16x32_bf16 v[30:33], v[118:121], v[178:181], v[30:33]
	v_mfma_f32_16x16x32_bf16 v[26:29], v[130:133], v[178:181], v[26:29]
	v_mfma_f32_16x16x32_bf16 v[14:17], v[118:121], v[186:189], v[14:17]
	v_mfma_f32_16x16x32_bf16 v[10:13], v[130:133], v[186:189], v[10:13]
	v_mfma_f32_16x16x32_bf16 v[62:65], v[126:129], v[166:169], v[62:65]
	v_mfma_f32_16x16x32_bf16 v[58:61], v[134:137], v[166:169], v[58:61]
	v_mfma_f32_16x16x32_bf16 v[46:49], v[126:129], v[174:177], v[46:49]
	v_mfma_f32_16x16x32_bf16 v[42:45], v[134:137], v[174:177], v[42:45]
	v_mfma_f32_16x16x32_bf16 v[30:33], v[126:129], v[182:185], v[30:33]
	v_mfma_f32_16x16x32_bf16 v[26:29], v[134:137], v[182:185], v[26:29]
	v_mfma_f32_16x16x32_bf16 v[14:17], v[126:129], v[202:205], v[14:17]
	v_mfma_f32_16x16x32_bf16 v[10:13], v[134:137], v[202:205], v[10:13]
	v_mfma_f32_16x16x32_bf16 v[54:57], v[138:141], v[162:165], v[54:57]
	v_mfma_f32_16x16x32_bf16 v[50:53], v[154:157], v[162:165], v[50:53]
	v_mfma_f32_16x16x32_bf16 v[38:41], v[138:141], v[170:173], v[38:41]
	v_mfma_f32_16x16x32_bf16 v[34:37], v[154:157], v[170:173], v[34:37]
	v_mfma_f32_16x16x32_bf16 v[22:25], v[138:141], v[178:181], v[22:25]
	v_mfma_f32_16x16x32_bf16 v[18:21], v[154:157], v[178:181], v[18:21]
	v_mfma_f32_16x16x32_bf16 v[6:9], v[138:141], v[186:189], v[6:9]
	v_mfma_f32_16x16x32_bf16 v[2:5], v[154:157], v[186:189], v[2:5]
	v_mfma_f32_16x16x32_bf16 v[54:57], v[142:145], v[166:169], v[54:57]
	v_mfma_f32_16x16x32_bf16 v[50:53], v[158:161], v[166:169], v[50:53]
	v_mfma_f32_16x16x32_bf16 v[38:41], v[142:145], v[174:177], v[38:41]
	v_mfma_f32_16x16x32_bf16 v[34:37], v[158:161], v[174:177], v[34:37]
	v_mfma_f32_16x16x32_bf16 v[22:25], v[142:145], v[182:185], v[22:25]
	v_mfma_f32_16x16x32_bf16 v[18:21], v[158:161], v[182:185], v[18:21]
	v_mfma_f32_16x16x32_bf16 v[6:9], v[142:145], v[202:205], v[6:9]
	v_mfma_f32_16x16x32_bf16 v[2:5], v[158:161], v[202:205], v[2:5]
	s_barrier
	s_add_i32 s81, s81, 2
	s_add_u32 s4, s4, 0x100
	s_addc_u32 s5, s5, 0
	s_add_u32 s21, s21, 0x100
	s_addc_u32 s27, s27, 0
	s_cmp_gt_u32 s81, 29
.LBB0_602:
	s_add_u32 s30, s4, 0xfff80080
	s_addc_u32 s31, s5, -1
	s_add_i32 s84, 0, 0x10000
	s_cmp_eq_u32 s81, 28
	s_cselect_b32 s41, s29, s31
	s_cselect_b32 s40, s28, s30
	s_cselect_b32 s31, s2, s27
	s_cselect_b32 s30, s3, s21
	s_add_i32 s90, 0, 0x14000
	v_add_u32_e32 v134, s84, v207
	v_add_u32_e32 v158, s90, v207
	ds_read_b128 v[118:121], v134
	ds_read_b128 v[126:129], v134 offset:1024
	ds_read_b128 v[130:133], v134 offset:2048
	ds_read_b128 v[134:137], v134 offset:3072
	ds_read_b128 v[138:141], v158
	ds_read_b128 v[142:145], v158 offset:1024
	ds_read_b128 v[154:157], v158 offset:2048
	ds_read_b128 v[158:161], v158 offset:3072
	s_add_i32 m0, s35, 0xc000
	ds_read_b128 v[162:165], v208
	ds_read_b128 v[166:169], v208 offset:1024
	ds_read_b128 v[170:173], v208 offset:2048
	ds_read_b128 v[174:177], v208 offset:3072
	ds_read_b128 v[178:181], v208 offset:4096
	ds_read_b128 v[182:185], v208 offset:5120
	ds_read_b128 v[186:189], v208 offset:6144
	ds_read_b128 v[202:205], v208 offset:7168
	global_load_lds_dwordx4 v198, s[4:5]
	s_add_i32 m0, s35, 0xe000
	s_nop 0
	global_load_lds_dwordx4 v200, s[4:5]
	s_waitcnt vmcnt(8)
	s_waitcnt lgkmcnt(0)
	s_barrier
; #define PG8_STAGE(bufoff, gbase, voff) do { _Pragma("unroll") for (int _i = 0; _i < 2; ++_i) \
;         __builtin_amdgcn_global_load_lds((const unsigned*)((const char*)(gbase) + (voff)[_i]), (PG8_LAS unsigned*)(lds + (bufoff) + ldsw + _i * 8192), 16, 0, 0); } while (0)
; #define PG8_LDA(dst, b, h) do { _Pragma("unroll") for (int m = 0; m < 4; ++m) _Pragma("unroll") for (int k = 0; k < 2; ++k) dst[m][k] = *(const PG8_LAS bf16x8*)(lds + PG8_SA(b, h) + aoff + m * 2048 + k * 1024); } while (0)
; #define PG8_LDB(dst, b, h) do { _Pragma("unroll") for (int n = 0; n < 2; ++n) _Pragma("unroll") for (int k = 0; k < 2; ++k) dst[n][k] = *(const PG8_LAS bf16x8*)(lds + PG8_SB(b, h) + boff + n * 2048 + k * 1024); } while (0)
; #define PG8_MMA(ai, bj, At, Bt) do { __builtin_amdgcn_s_setprio(1); _Pragma("unroll") for (int m = 0; m < 4; ++m) _Pragma("unroll") for (int n = 0; n < 2; ++n) _Pragma("unroll") for (int k = 0; k < 2; ++k) \
;         acc[ai][bj][m][n] = __builtin_amdgcn_mfma_f32_16x16x32_bf16(Bt[n][k], At[m][k], acc[ai][bj][m][n], 0, 0, 0); __builtin_amdgcn_s_setprio(0); } while (0)
; #define PG8_WAIT_V(n) asm volatile("s_waitcnt vmcnt(" #n ")" ::: "memory")
; #define PG8_WAIT_L(n) asm volatile("s_waitcnt lgkmcnt(" #n ")" ::: "memory")
; #define PG8_BAR __builtin_amdgcn_s_barrier()
; #define PG8_SCHED __builtin_amdgcn_sched_barrier(0)
; template <class Epi, class Sched, bool ALIGN_EPI = false, bool SP2 = false>
; __device__ __forceinline__ void gemm_phase(PG8_LAS unsigned char* lds, const Gemm g, const Sched& S, const Epi& E, int wave_s) {
;     ...
;             PG8_LDB(B0, 0, 0); PG8_LDB(B1, 0, 1); PG8_SCHED; PG8_LDA(At, 0, 0); PG8_STAGE(PG8_SA(1, 1), a1 + hstepA, voffA);
;             PG8_WAIT_V(8); PG8_WAIT_L(0); PG8_BAR; PG8_MMA(0, 0, At, B0); PG8_MMA(0, 1, At, B1); PG8_BAR; PG8_SCHED;
;             PG8_LDA(At, 0, 1); PG8_STAGE(PG8_SB(0, 0), b2, voffB); PG8_STAGE(PG8_SB(0, 1), b2 + hstepB, voffB); PG8_STAGE(PG8_SA(0, 0), a2, voffA);
;             PG8_WAIT_V(8); PG8_WAIT_L(0); PG8_BAR; PG8_MMA(1, 0, At, B0); PG8_MMA(1, 1, At, B1); PG8_BAR; PG8_SCHED;
	s_waitcnt lgkmcnt(0)
	v_mfma_f32_16x16x32_bf16 v[150:153], v[118:121], v[162:165], v[150:153]
	v_mfma_f32_16x16x32_bf16 v[146:149], v[130:133], v[162:165], v[146:149]
	v_mfma_f32_16x16x32_bf16 v[110:113], v[118:121], v[170:173], v[110:113]
	v_mfma_f32_16x16x32_bf16 v[106:109], v[130:133], v[170:173], v[106:109]
	v_mfma_f32_16x16x32_bf16 v[94:97], v[118:121], v[178:181], v[94:97]
	v_mfma_f32_16x16x32_bf16 v[90:93], v[130:133], v[178:181], v[90:93]
	v_mfma_f32_16x16x32_bf16 v[78:81], v[118:121], v[186:189], v[78:81]
	v_mfma_f32_16x16x32_bf16 v[74:77], v[130:133], v[186:189], v[74:77]
	v_mfma_f32_16x16x32_bf16 v[150:153], v[126:129], v[166:169], v[150:153]
	v_mfma_f32_16x16x32_bf16 v[146:149], v[134:137], v[166:169], v[146:149]
	v_mfma_f32_16x16x32_bf16 v[110:113], v[126:129], v[174:177], v[110:113]
	v_mfma_f32_16x16x32_bf16 v[106:109], v[134:137], v[174:177], v[106:109]
	v_mfma_f32_16x16x32_bf16 v[94:97], v[126:129], v[182:185], v[94:97]
	v_mfma_f32_16x16x32_bf16 v[90:93], v[134:137], v[182:185], v[90:93]
	v_mfma_f32_16x16x32_bf16 v[78:81], v[126:129], v[202:205], v[78:81]
	v_mfma_f32_16x16x32_bf16 v[74:77], v[134:137], v[202:205], v[74:77]
	v_mfma_f32_16x16x32_bf16 v[122:125], v[138:141], v[162:165], v[122:125]
	v_mfma_f32_16x16x32_bf16 v[114:117], v[154:157], v[162:165], v[114:117]
	v_mfma_f32_16x16x32_bf16 v[102:105], v[138:141], v[170:173], v[102:105]
	v_mfma_f32_16x16x32_bf16 v[98:101], v[154:157], v[170:173], v[98:101]
	v_mfma_f32_16x16x32_bf16 v[86:89], v[138:141], v[178:181], v[86:89]
	v_mfma_f32_16x16x32_bf16 v[82:85], v[154:157], v[178:181], v[82:85]
	v_mfma_f32_16x16x32_bf16 v[70:73], v[138:141], v[186:189], v[70:73]
	v_mfma_f32_16x16x32_bf16 v[66:69], v[154:157], v[186:189], v[66:69]
	v_mfma_f32_16x16x32_bf16 v[122:125], v[142:145], v[166:169], v[122:125]
	v_mfma_f32_16x16x32_bf16 v[114:117], v[158:161], v[166:169], v[114:117]
	v_mfma_f32_16x16x32_bf16 v[102:105], v[142:145], v[174:177], v[102:105]
	v_mfma_f32_16x16x32_bf16 v[98:101], v[158:161], v[174:177], v[98:101]
	v_mfma_f32_16x16x32_bf16 v[86:89], v[142:145], v[182:185], v[86:89]
	v_mfma_f32_16x16x32_bf16 v[82:85], v[158:161], v[182:185], v[82:85]
	v_mfma_f32_16x16x32_bf16 v[70:73], v[142:145], v[202:205], v[70:73]
	v_mfma_f32_16x16x32_bf16 v[66:69], v[158:161], v[202:205], v[66:69]
	s_barrier
	s_add_i32 s84, s84, s34
	v_lshl_add_u64 v[210:211], s[30:31], 0, v[194:195]
	s_mov_b32 m0, s84
	ds_read_b128 v[162:165], v208 offset:16384
	ds_read_b128 v[166:169], v208 offset:17408
	ds_read_b128 v[170:173], v208 offset:18432
	ds_read_b128 v[174:177], v208 offset:19456
	ds_read_b128 v[178:181], v208 offset:20480
	ds_read_b128 v[182:185], v208 offset:21504
	ds_read_b128 v[186:189], v208 offset:22528
	ds_read_b128 v[202:205], v208 offset:23552
	global_load_lds_dwordx4 v[210:211], off
	s_add_i32 m0, s84, 0x2000
	s_add_u32 s84, s30, 0x80000
	v_lshl_add_u64 v[212:213], s[30:31], 0, v[190:191]
	s_addc_u32 s85, s31, 0
	s_add_i32 s90, s90, s34
	global_load_lds_dwordx4 v[212:213], off
	s_mov_b32 m0, s90
	v_lshl_add_u64 v[216:217], s[40:41], 0, v[192:193]
	global_load_lds_dwordx4 v194, s[84:85]
	s_add_i32 m0, s90, 0x2000
	s_nop 0
	global_load_lds_dwordx4 v190, s[84:85]
	v_lshl_add_u64 v[214:215], s[40:41], 0, v[196:197]
	s_mov_b32 m0, s35
	s_nop 0
	global_load_lds_dwordx4 v[214:215], off
	s_mov_b32 m0, s36
	s_nop 0
	global_load_lds_dwordx4 v[216:217], off
	s_waitcnt vmcnt(8)
	s_waitcnt lgkmcnt(0)
	s_barrier
	s_waitcnt lgkmcnt(0)
	v_mfma_f32_16x16x32_bf16 v[62:65], v[118:121], v[162:165], v[62:65]
	v_mfma_f32_16x16x32_bf16 v[58:61], v[130:133], v[162:165], v[58:61]
	v_mfma_f32_16x16x32_bf16 v[46:49], v[118:121], v[170:173], v[46:49]
	v_mfma_f32_16x16x32_bf16 v[42:45], v[130:133], v[170:173], v[42:45]
	v_mfma_f32_16x16x32_bf16 v[30:33], v[118:121], v[178:181], v[30:33]
	v_mfma_f32_16x16x32_bf16 v[26:29], v[130:133], v[178:181], v[26:29]
	v_mfma_f32_16x16x32_bf16 v[14:17], v[118:121], v[186:189], v[14:17]
	v_mfma_f32_16x16x32_bf16 v[10:13], v[130:133], v[186:189], v[10:13]
	v_mfma_f32_16x16x32_bf16 v[62:65], v[126:129], v[166:169], v[62:65]
	v_mfma_f32_16x16x32_bf16 v[58:61], v[134:137], v[166:169], v[58:61]
	v_mfma_f32_16x16x32_bf16 v[46:49], v[126:129], v[174:177], v[46:49]
	v_mfma_f32_16x16x32_bf16 v[42:45], v[134:137], v[174:177], v[42:45]
	v_mfma_f32_16x16x32_bf16 v[30:33], v[126:129], v[182:185], v[30:33]
	v_mfma_f32_16x16x32_bf16 v[26:29], v[134:137], v[182:185], v[26:29]
	v_mfma_f32_16x16x32_bf16 v[14:17], v[126:129], v[202:205], v[14:17]
	v_mfma_f32_16x16x32_bf16 v[10:13], v[134:137], v[202:205], v[10:13]
	v_mfma_f32_16x16x32_bf16 v[54:57], v[138:141], v[162:165], v[54:57]
	v_mfma_f32_16x16x32_bf16 v[50:53], v[154:157], v[162:165], v[50:53]
	v_mfma_f32_16x16x32_bf16 v[38:41], v[138:141], v[170:173], v[38:41]
	v_mfma_f32_16x16x32_bf16 v[34:37], v[154:157], v[170:173], v[34:37]
	v_mfma_f32_16x16x32_bf16 v[22:25], v[138:141], v[178:181], v[22:25]
	v_mfma_f32_16x16x32_bf16 v[18:21], v[154:157], v[178:181], v[18:21]
	v_mfma_f32_16x16x32_bf16 v[6:9], v[138:141], v[186:189], v[6:9]
	v_mfma_f32_16x16x32_bf16 v[2:5], v[154:157], v[186:189], v[2:5]
	v_mfma_f32_16x16x32_bf16 v[54:57], v[142:145], v[166:169], v[54:57]
	v_mfma_f32_16x16x32_bf16 v[50:53], v[158:161], v[166:169], v[50:53]
	v_mfma_f32_16x16x32_bf16 v[38:41], v[142:145], v[174:177], v[38:41]
	v_mfma_f32_16x16x32_bf16 v[34:37], v[158:161], v[174:177], v[34:37]
	v_mfma_f32_16x16x32_bf16 v[22:25], v[142:145], v[182:185], v[22:25]
	v_mfma_f32_16x16x32_bf16 v[18:21], v[158:161], v[182:185], v[18:21]
	v_mfma_f32_16x16x32_bf16 v[6:9], v[142:145], v[202:205], v[6:9]
	v_mfma_f32_16x16x32_bf16 v[2:5], v[158:161], v[202:205], v[2:5]
	s_barrier
; #define PG8_STAGE(bufoff, gbase, voff) do { _Pragma("unroll") for (int _i = 0; _i < 2; ++_i) \
;         __builtin_amdgcn_global_load_lds((const unsigned*)((const char*)(gbase) + (voff)[_i]), (PG8_LAS unsigned*)(lds + (bufoff) + ldsw + _i * 8192), 16, 0, 0); } while (0)
; #define PG8_LDA(dst, b, h) do { _Pragma("unroll") for (int m = 0; m < 4; ++m) _Pragma("unroll") for (int k = 0; k < 2; ++k) dst[m][k] = *(const PG8_LAS bf16x8*)(lds + PG8_SA(b, h) + aoff + m * 2048 + k * 1024); } while (0)
; #define PG8_LDB(dst, b, h) do { _Pragma("unroll") for (int n = 0; n < 2; ++n) _Pragma("unroll") for (int k = 0; k < 2; ++k) dst[n][k] = *(const PG8_LAS bf16x8*)(lds + PG8_SB(b, h) + boff + n * 2048 + k * 1024); } while (0)
; #define PG8_MMA(ai, bj, At, Bt) do { __builtin_amdgcn_s_setprio(1); _Pragma("unroll") for (int m = 0; m < 4; ++m) _Pragma("unroll") for (int n = 0; n < 2; ++n) _Pragma("unroll") for (int k = 0; k < 2; ++k) \
;         acc[ai][bj][m][n] = __builtin_amdgcn_mfma_f32_16x16x32_bf16(Bt[n][k], At[m][k], acc[ai][bj][m][n], 0, 0, 0); __builtin_amdgcn_s_setprio(0); } while (0)
; #define PG8_WAIT_V(n) asm volatile("s_waitcnt vmcnt(" #n ")" ::: "memory")
; #define PG8_WAIT_L(n) asm volatile("s_waitcnt lgkmcnt(" #n ")" ::: "memory")
; #define PG8_BAR __builtin_amdgcn_s_barrier()
; template <class Epi, class Sched, bool ALIGN_EPI = false, bool SP2 = false>
; __device__ __forceinline__ void gemm_phase(PG8_LAS unsigned char* lds, const Gemm g, const Sched& S, const Epi& E, int wave_s) {
;     ...
;             PG8_LDA(At, 0, 1); PG8_STAGE(PG8_SB(0, 0), b2, voffB); PG8_STAGE(PG8_SB(0, 1), b2 + hstepB, voffB); PG8_STAGE(PG8_SA(0, 0), a2, voffA);
;             PG8_WAIT_V(8); PG8_WAIT_L(0); PG8_BAR; PG8_MMA(1, 0, At, B0); PG8_MMA(1, 1, At, B1); PG8_BAR; PG8_SCHED;
;             PG8_LDB(B0, 1, 0); PG8_LDB(B1, 1, 1); PG8_SCHED; PG8_LDA(At, 1, 0); PG8_STAGE(PG8_SA(0, 1), a2 + hstepA, voffA);
;             PG8_WAIT_V(8); PG8_WAIT_L(0); PG8_BAR; PG8_MMA(0, 0, At, B0); PG8_MMA(0, 1, At, B1); PG8_BAR; PG8_SCHED;
;             PG8_LDA(At, 1, 1); PG8_STAGE(PG8_SB(1, 0), b3, voffB); PG8_STAGE(PG8_SB(1, 1), b3 + hstepB, voffB); PG8_STAGE(PG8_SA(1, 0), a3, voffA);
;             PG8_WAIT_V(8); PG8_WAIT_L(0); PG8_BAR; PG8_MMA(1, 0, At, B0); PG8_MMA(1, 1, At, B1); PG8_BAR; PG8_SCHED;
;     ...
;         if constexpr (ALIGN_EPI) { if (wr == 0) PG8_BAR; }
	s_add_i32 s84, 0, 0x18000
	s_add_i32 s85, 0, 0x1c000
	v_add_u32_e32 v134, s84, v207
	v_add_u32_e32 v158, s85, v207
	ds_read_b128 v[118:121], v134
	ds_read_b128 v[126:129], v134 offset:1024
	ds_read_b128 v[130:133], v134 offset:2048
	ds_read_b128 v[134:137], v134 offset:3072
	ds_read_b128 v[138:141], v158
	ds_read_b128 v[142:145], v158 offset:1024
	ds_read_b128 v[154:157], v158 offset:2048
	ds_read_b128 v[158:161], v158 offset:3072
	s_add_u32 s40, s40, 0x80000
	s_addc_u32 s41, s41, 0
	s_mov_b32 m0, s37
	ds_read_b128 v[162:165], v208 offset:32768
	ds_read_b128 v[166:169], v208 offset:33792
	ds_read_b128 v[170:173], v208 offset:34816
	ds_read_b128 v[174:177], v208 offset:35840
	ds_read_b128 v[178:181], v208 offset:36864
	ds_read_b128 v[182:185], v208 offset:37888
	ds_read_b128 v[186:189], v208 offset:38912
	ds_read_b128 v[202:205], v208 offset:39936
	global_load_lds_dwordx4 v196, s[40:41]
	v_lshl_add_u64 v[218:219], s[40:41], 0, v[192:193]
	s_mov_b32 m0, s42
	s_nop 0
	global_load_lds_dwordx4 v[218:219], off
	s_waitcnt vmcnt(8)
	s_waitcnt lgkmcnt(0)
	s_barrier
	s_waitcnt lgkmcnt(0)
	v_mfma_f32_16x16x32_bf16 v[150:153], v[118:121], v[162:165], v[150:153]
	v_mfma_f32_16x16x32_bf16 v[146:149], v[130:133], v[162:165], v[146:149]
	v_mfma_f32_16x16x32_bf16 v[110:113], v[118:121], v[170:173], v[110:113]
	v_mfma_f32_16x16x32_bf16 v[106:109], v[130:133], v[170:173], v[106:109]
	v_mfma_f32_16x16x32_bf16 v[94:97], v[118:121], v[178:181], v[94:97]
	v_mfma_f32_16x16x32_bf16 v[90:93], v[130:133], v[178:181], v[90:93]
	v_mfma_f32_16x16x32_bf16 v[78:81], v[118:121], v[186:189], v[78:81]
	v_mfma_f32_16x16x32_bf16 v[74:77], v[130:133], v[186:189], v[74:77]
	v_mfma_f32_16x16x32_bf16 v[150:153], v[126:129], v[166:169], v[150:153]
	v_mfma_f32_16x16x32_bf16 v[146:149], v[134:137], v[166:169], v[146:149]
	v_mfma_f32_16x16x32_bf16 v[110:113], v[126:129], v[174:177], v[110:113]
	v_mfma_f32_16x16x32_bf16 v[106:109], v[134:137], v[174:177], v[106:109]
	v_mfma_f32_16x16x32_bf16 v[94:97], v[126:129], v[182:185], v[94:97]
	v_mfma_f32_16x16x32_bf16 v[90:93], v[134:137], v[182:185], v[90:93]
	v_mfma_f32_16x16x32_bf16 v[78:81], v[126:129], v[202:205], v[78:81]
	v_mfma_f32_16x16x32_bf16 v[74:77], v[134:137], v[202:205], v[74:77]
	v_mfma_f32_16x16x32_bf16 v[122:125], v[138:141], v[162:165], v[122:125]
	v_mfma_f32_16x16x32_bf16 v[114:117], v[154:157], v[162:165], v[114:117]
	v_mfma_f32_16x16x32_bf16 v[102:105], v[138:141], v[170:173], v[102:105]
	v_mfma_f32_16x16x32_bf16 v[98:101], v[154:157], v[170:173], v[98:101]
	v_mfma_f32_16x16x32_bf16 v[86:89], v[138:141], v[178:181], v[86:89]
	v_mfma_f32_16x16x32_bf16 v[82:85], v[154:157], v[178:181], v[82:85]
	v_mfma_f32_16x16x32_bf16 v[70:73], v[138:141], v[186:189], v[70:73]
	v_mfma_f32_16x16x32_bf16 v[66:69], v[154:157], v[186:189], v[66:69]
	v_mfma_f32_16x16x32_bf16 v[122:125], v[142:145], v[166:169], v[122:125]
	v_mfma_f32_16x16x32_bf16 v[114:117], v[158:161], v[166:169], v[114:117]
	v_mfma_f32_16x16x32_bf16 v[102:105], v[142:145], v[174:177], v[102:105]
	v_mfma_f32_16x16x32_bf16 v[98:101], v[158:161], v[174:177], v[98:101]
	v_mfma_f32_16x16x32_bf16 v[86:89], v[142:145], v[182:185], v[86:89]
	v_mfma_f32_16x16x32_bf16 v[82:85], v[158:161], v[182:185], v[82:85]
	v_mfma_f32_16x16x32_bf16 v[70:73], v[142:145], v[202:205], v[70:73]
	v_mfma_f32_16x16x32_bf16 v[66:69], v[158:161], v[202:205], v[66:69]
	s_barrier
	s_add_i32 s40, s84, s34
	v_lshl_add_u64 v[210:211], v[210:211], 0, s[60:61]
	s_mov_b32 m0, s40
	ds_read_b128 v[162:165], v208 offset:49152
	ds_read_b128 v[166:169], v208 offset:50176
	ds_read_b128 v[170:173], v208 offset:51200
	ds_read_b128 v[174:177], v208 offset:52224
	ds_read_b128 v[178:181], v208 offset:53248
	ds_read_b128 v[182:185], v208 offset:54272
	ds_read_b128 v[186:189], v208 offset:55296
	ds_read_b128 v[202:205], v208 offset:56320
	global_load_lds_dwordx4 v[210:211], off
	s_add_i32 m0, s40, 0x2000
	s_add_u32 s30, s30, 0x80080
	v_lshl_add_u64 v[210:211], v[212:213], 0, s[60:61]
	s_addc_u32 s31, s31, 0
	s_add_i32 s40, s85, s34
	global_load_lds_dwordx4 v[210:211], off
	s_mov_b32 m0, s40
	s_nop 0
	global_load_lds_dwordx4 v194, s[30:31]
	s_add_i32 m0, s40, 0x2000
	s_nop 0
	global_load_lds_dwordx4 v190, s[30:31]
	v_lshl_add_u64 v[210:211], v[214:215], 0, s[60:61]
	s_mov_b32 m0, s46
	s_nop 0
	global_load_lds_dwordx4 v[210:211], off
	v_lshl_add_u64 v[210:211], v[216:217], 0, s[60:61]
	s_mov_b32 m0, s47
	s_nop 0
	global_load_lds_dwordx4 v[210:211], off
	s_waitcnt vmcnt(8)
	s_waitcnt lgkmcnt(0)
	s_barrier
	s_waitcnt lgkmcnt(0)
	v_mfma_f32_16x16x32_bf16 v[62:65], v[118:121], v[162:165], v[62:65]
	v_mfma_f32_16x16x32_bf16 v[58:61], v[130:133], v[162:165], v[58:61]
	v_mfma_f32_16x16x32_bf16 v[46:49], v[118:121], v[170:173], v[46:49]
	v_mfma_f32_16x16x32_bf16 v[42:45], v[130:133], v[170:173], v[42:45]
	v_mfma_f32_16x16x32_bf16 v[30:33], v[118:121], v[178:181], v[30:33]
	v_mfma_f32_16x16x32_bf16 v[26:29], v[130:133], v[178:181], v[26:29]
	v_mfma_f32_16x16x32_bf16 v[14:17], v[118:121], v[186:189], v[14:17]
	v_mfma_f32_16x16x32_bf16 v[10:13], v[130:133], v[186:189], v[10:13]
	v_mfma_f32_16x16x32_bf16 v[62:65], v[126:129], v[166:169], v[62:65]
	v_mfma_f32_16x16x32_bf16 v[58:61], v[134:137], v[166:169], v[58:61]
	v_mfma_f32_16x16x32_bf16 v[46:49], v[126:129], v[174:177], v[46:49]
	v_mfma_f32_16x16x32_bf16 v[42:45], v[134:137], v[174:177], v[42:45]
	v_mfma_f32_16x16x32_bf16 v[30:33], v[126:129], v[182:185], v[30:33]
	v_mfma_f32_16x16x32_bf16 v[26:29], v[134:137], v[182:185], v[26:29]
	v_mfma_f32_16x16x32_bf16 v[14:17], v[126:129], v[202:205], v[14:17]
	v_mfma_f32_16x16x32_bf16 v[10:13], v[134:137], v[202:205], v[10:13]
	v_mfma_f32_16x16x32_bf16 v[54:57], v[138:141], v[162:165], v[54:57]
	v_mfma_f32_16x16x32_bf16 v[50:53], v[154:157], v[162:165], v[50:53]
	v_mfma_f32_16x16x32_bf16 v[38:41], v[138:141], v[170:173], v[38:41]
	v_mfma_f32_16x16x32_bf16 v[34:37], v[154:157], v[170:173], v[34:37]
	v_mfma_f32_16x16x32_bf16 v[22:25], v[138:141], v[178:181], v[22:25]
	v_mfma_f32_16x16x32_bf16 v[18:21], v[154:157], v[178:181], v[18:21]
	v_mfma_f32_16x16x32_bf16 v[6:9], v[138:141], v[186:189], v[6:9]
	v_mfma_f32_16x16x32_bf16 v[2:5], v[154:157], v[186:189], v[2:5]
	v_mfma_f32_16x16x32_bf16 v[54:57], v[142:145], v[166:169], v[54:57]
	v_mfma_f32_16x16x32_bf16 v[50:53], v[158:161], v[166:169], v[50:53]
	v_mfma_f32_16x16x32_bf16 v[38:41], v[142:145], v[174:177], v[38:41]
	v_mfma_f32_16x16x32_bf16 v[34:37], v[158:161], v[174:177], v[34:37]
	v_mfma_f32_16x16x32_bf16 v[22:25], v[142:145], v[182:185], v[22:25]
	v_mfma_f32_16x16x32_bf16 v[18:21], v[158:161], v[182:185], v[18:21]
	v_mfma_f32_16x16x32_bf16 v[6:9], v[142:145], v[202:205], v[6:9]
	v_mfma_f32_16x16x32_bf16 v[2:5], v[158:161], v[202:205], v[2:5]
	s_barrier
	s_add_i32 s81, s81, 2
	s_add_u32 s4, s4, 0x100
	s_addc_u32 s5, s5, 0
	s_add_u32 s21, s21, 0x100
	s_addc_u32 s27, s27, 0
	s_cmp_gt_u32 s81, 29
	s_cbranch_scc0 .LBB0_602
	s_and_b64 vcc, exec, s[14:15]
	s_cbranch_vccz .LBB0_605
	s_barrier

; #define PG8_STAGE(bufoff, gbase, voff) do { _Pragma("unroll") for (int _i = 0; _i < 2; ++_i) \
;         __builtin_amdgcn_global_load_lds((const unsigned*)((const char*)(gbase) + (voff)[_i]), (PG8_LAS unsigned*)(lds + (bufoff) + ldsw + _i * 8192), 16, 0, 0); } while (0)
; #define PG8_LDA(dst, b, h) do { _Pragma("unroll") for (int m = 0; m < 4; ++m) _Pragma("unroll") for (int k = 0; k < 2; ++k) dst[m][k] = *(const PG8_LAS bf16x8*)(lds + PG8_SA(b, h) + aoff + m * 2048 + k * 1024); } while (0)
; #define PG8_LDB(dst, b, h) do { _Pragma("unroll") for (int n = 0; n < 2; ++n) _Pragma("unroll") for (int k = 0; k < 2; ++k) dst[n][k] = *(const PG8_LAS bf16x8*)(lds + PG8_SB(b, h) + boff + n * 2048 + k * 1024); } while (0)
; #define PG8_MMA(ai, bj, At, Bt) do { __builtin_amdgcn_s_setprio(1); _Pragma("unroll") for (int m = 0; m < 4; ++m) _Pragma("unroll") for (int n = 0; n < 2; ++n) _Pragma("unroll") for (int k = 0; k < 2; ++k) \
;         acc[ai][bj][m][n] = __builtin_amdgcn_mfma_f32_16x16x32_bf16(Bt[n][k], At[m][k], acc[ai][bj][m][n], 0, 0, 0); __builtin_amdgcn_s_setprio(0); } while (0)
; #define PG8_WAIT_V(n) asm volatile("s_waitcnt vmcnt(" #n ")" ::: "memory")
; #define PG8_BAR __builtin_amdgcn_s_barrier()
; template <class Epi, class Sched, bool ALIGN_EPI = false, bool SP2 = false>
; __device__ __forceinline__ void gemm_phase(PG8_LAS unsigned char* lds, const Gemm g, const Sched& S, const Epi& E, int wave_s) {
;     ...
;         const bool has_next = S.next(ui + 1, nxt);
;         const char* nA = has_next ? (const char*)g.A + (size_t)nxt.pm * tstepA + (size_t)(nxt.pn / g.npg) * (size_t)(K * 2) : cA; const char* nB = has_next ? (const char*)g.Bt + (size_t)nxt.pn * tstepB : cB;
;         for (int t = 0; t < nt; t += 2) {
;             const bool last = (t == nt - 2);
;             const char* a1 = cA + (size_t)(t + 1) * kstep;
;             const char* a2 = last ? nA : cA + (size_t)(t + 2) * kstep; const char* b2 = last ? nB : cB + (size_t)(t + 2) * kstep;
;             const char* a3 = a2 + kstep; const char* b3 = b2 + kstep;
;             if (last && has_next) S.a_ready(nxt);
;             if constexpr (SP2) {
;             PG8_LDB(B0, 0, 0); PG8_LDB(B1, 0, 1); PG8_SCHED; PG8_LDA(At, 0, 0); PG8_STAGE(PG8_SA(1, 1), a1 + hstepA, voffA);
;             PG8_WAIT_V(8); PG8_WAIT_L(0); PG8_BAR; PG8_MMA(0, 0, At, B0); PG8_MMA(0, 1, At, B1); PG8_BAR; PG8_SCHED;
.LBB0_690:
	s_ashr_i32 s89, s88, 31
	s_lshl_b64 s[2:3], s[88:89], 20
	s_add_u32 s28, s22, s2
	s_addc_u32 s29, s23, s3
	s_and_b64 s[2:3], s[4:5], exec
	s_cselect_b32 s2, s29, s41
	s_cselect_b32 s3, s28, s40
	s_add_u32 s89, s40, 0x100
	s_addc_u32 s91, s41, 0
	s_mov_b32 vcc_lo, -2
	s_add_u32 s4, s30, 0x100
	s_addc_u32 s5, s31, 0
	s_add_i32 vcc_hi, 0, 0x10000
	s_cmp_eq_u32 vcc_lo, 28
	s_cselect_b32 s41, s21, s5
	s_cselect_b32 s40, s20, s4
	s_cselect_b32 s7, s2, s91
	s_cselect_b32 s6, s3, s89
	s_add_i32 s86, 0, 0x14000
	v_add_u32_e32 v142, vcc_hi, v251
	v_add_u32_e32 v158, s86, v251
	ds_read_b128 v[126:129], v142
	ds_read_b128 v[134:137], v142 offset:1024
	ds_read_b128 v[138:141], v142 offset:2048
	ds_read_b128 v[142:145], v142 offset:3072
	ds_read_b128 v[146:149], v158
	ds_read_b128 v[150:153], v158 offset:1024
	ds_read_b128 v[154:157], v158 offset:2048
	ds_read_b128 v[158:161], v158 offset:3072
	s_add_i32 m0, s36, 0xc000
	ds_read_b128 v[162:165], v252
	ds_read_b128 v[166:169], v252 offset:1024
	ds_read_b128 v[170:173], v252 offset:2048
	ds_read_b128 v[174:177], v252 offset:3072
	ds_read_b128 v[178:181], v252 offset:4096
	ds_read_b128 v[182:185], v252 offset:5120
	ds_read_b128 v[186:189], v252 offset:6144
	ds_read_b128 v[190:193], v252 offset:7168
	global_load_lds_dwordx4 v244, s[30:31]
	s_add_i32 m0, s36, 0xe000
	s_nop 0
	global_load_lds_dwordx4 v246, s[30:31]
	s_waitcnt vmcnt(8)
	s_waitcnt lgkmcnt(0)
	s_barrier
	s_waitcnt lgkmcnt(0)
	v_mfma_f32_16x16x32_bf16 v[130:133], v[126:129], v[162:165], 0
	v_mfma_f32_16x16x32_bf16 v[118:121], v[138:141], v[162:165], 0
	v_mfma_f32_16x16x32_bf16 v[110:113], v[126:129], v[170:173], 0
	v_mfma_f32_16x16x32_bf16 v[98:101], v[138:141], v[170:173], 0
	v_mfma_f32_16x16x32_bf16 v[62:65], v[126:129], v[178:181], 0
	v_mfma_f32_16x16x32_bf16 v[58:61], v[138:141], v[178:181], 0
	v_mfma_f32_16x16x32_bf16 v[46:49], v[126:129], v[186:189], 0
	v_mfma_f32_16x16x32_bf16 v[42:45], v[138:141], v[186:189], 0
	v_mfma_f32_16x16x32_bf16 v[130:133], v[134:137], v[166:169], v[130:133]
	v_mfma_f32_16x16x32_bf16 v[118:121], v[142:145], v[166:169], v[118:121]
	v_mfma_f32_16x16x32_bf16 v[110:113], v[134:137], v[174:177], v[110:113]
	v_mfma_f32_16x16x32_bf16 v[98:101], v[142:145], v[174:177], v[98:101]
	v_mfma_f32_16x16x32_bf16 v[62:65], v[134:137], v[182:185], v[62:65]
	v_mfma_f32_16x16x32_bf16 v[58:61], v[142:145], v[182:185], v[58:61]
	v_mfma_f32_16x16x32_bf16 v[46:49], v[134:137], v[190:193], v[46:49]
	v_mfma_f32_16x16x32_bf16 v[42:45], v[142:145], v[190:193], v[42:45]
	v_mfma_f32_16x16x32_bf16 v[102:105], v[146:149], v[162:165], 0
	v_mfma_f32_16x16x32_bf16 v[74:77], v[154:157], v[162:165], 0
	v_mfma_f32_16x16x32_bf16 v[78:81], v[146:149], v[170:173], 0
	v_mfma_f32_16x16x32_bf16 v[90:93], v[154:157], v[170:173], 0
	v_mfma_f32_16x16x32_bf16 v[34:37], v[146:149], v[178:181], 0
	v_mfma_f32_16x16x32_bf16 v[26:29], v[154:157], v[178:181], 0
	v_mfma_f32_16x16x32_bf16 v[14:17], v[146:149], v[186:189], 0
	v_mfma_f32_16x16x32_bf16 v[2:5], v[154:157], v[186:189], 0
	v_mfma_f32_16x16x32_bf16 v[102:105], v[150:153], v[166:169], v[102:105]
	v_mfma_f32_16x16x32_bf16 v[74:77], v[158:161], v[166:169], v[74:77]
	v_mfma_f32_16x16x32_bf16 v[78:81], v[150:153], v[174:177], v[78:81]
	v_mfma_f32_16x16x32_bf16 v[90:93], v[158:161], v[174:177], v[90:93]
	v_mfma_f32_16x16x32_bf16 v[34:37], v[150:153], v[182:185], v[34:37]
	v_mfma_f32_16x16x32_bf16 v[26:29], v[158:161], v[182:185], v[26:29]
	v_mfma_f32_16x16x32_bf16 v[14:17], v[150:153], v[190:193], v[14:17]
	v_mfma_f32_16x16x32_bf16 v[2:5], v[158:161], v[190:193], v[2:5]
	s_barrier
	s_add_i32 s30, vcc_hi, s35
	v_lshl_add_u64 v[194:195], s[6:7], 0, v[238:239]
	s_mov_b32 m0, s30
	ds_read_b128 v[162:165], v252 offset:16384
	ds_read_b128 v[166:169], v252 offset:17408
	ds_read_b128 v[170:173], v252 offset:18432
	ds_read_b128 v[174:177], v252 offset:19456
	ds_read_b128 v[178:181], v252 offset:20480
	ds_read_b128 v[182:185], v252 offset:21504
	ds_read_b128 v[186:189], v252 offset:22528
	ds_read_b128 v[190:193], v252 offset:23552
	global_load_lds_dwordx4 v[194:195], off
	s_add_i32 m0, s30, 0x2000
	s_add_u32 s30, s6, 0x80000
	v_lshl_add_u64 v[196:197], s[6:7], 0, v[242:243]
	s_addc_u32 s31, s7, 0
	s_add_i32 s86, s86, s35
	global_load_lds_dwordx4 v[196:197], off
	s_mov_b32 m0, s86
	v_lshl_add_u64 v[200:201], s[40:41], 0, v[240:241]
	global_load_lds_dwordx4 v238, s[30:31]
	s_add_i32 m0, s86, 0x2000
	s_nop 0
	global_load_lds_dwordx4 v242, s[30:31]
	v_lshl_add_u64 v[198:199], s[40:41], 0, v[236:237]
	s_mov_b32 m0, s36
	s_nop 0
	global_load_lds_dwordx4 v[198:199], off
	s_mov_b32 m0, s37
	s_nop 0
	global_load_lds_dwordx4 v[200:201], off
	s_waitcnt vmcnt(8)
	s_waitcnt lgkmcnt(0)
	s_barrier
; #define PG8_STAGE(bufoff, gbase, voff) do { _Pragma("unroll") for (int _i = 0; _i < 2; ++_i) \
;         __builtin_amdgcn_global_load_lds((const unsigned*)((const char*)(gbase) + (voff)[_i]), (PG8_LAS unsigned*)(lds + (bufoff) + ldsw + _i * 8192), 16, 0, 0); } while (0)
; #define PG8_LDA(dst, b, h) do { _Pragma("unroll") for (int m = 0; m < 4; ++m) _Pragma("unroll") for (int k = 0; k < 2; ++k) dst[m][k] = *(const PG8_LAS bf16x8*)(lds + PG8_SA(b, h) + aoff + m * 2048 + k * 1024); } while (0)
; #define PG8_LDB(dst, b, h) do { _Pragma("unroll") for (int n = 0; n < 2; ++n) _Pragma("unroll") for (int k = 0; k < 2; ++k) dst[n][k] = *(const PG8_LAS bf16x8*)(lds + PG8_SB(b, h) + boff + n * 2048 + k * 1024); } while (0)
; #define PG8_MMA(ai, bj, At, Bt) do { __builtin_amdgcn_s_setprio(1); _Pragma("unroll") for (int m = 0; m < 4; ++m) _Pragma("unroll") for (int n = 0; n < 2; ++n) _Pragma("unroll") for (int k = 0; k < 2; ++k) \
;         acc[ai][bj][m][n] = __builtin_amdgcn_mfma_f32_16x16x32_bf16(Bt[n][k], At[m][k], acc[ai][bj][m][n], 0, 0, 0); __builtin_amdgcn_s_setprio(0); } while (0)
; #define PG8_WAIT_V(n) asm volatile("s_waitcnt vmcnt(" #n ")" ::: "memory")
; #define PG8_WAIT_L(n) asm volatile("s_waitcnt lgkmcnt(" #n ")" ::: "memory")
; #define PG8_BAR __builtin_amdgcn_s_barrier()
; #define PG8_SCHED __builtin_amdgcn_sched_barrier(0)
; template <class Epi, class Sched, bool ALIGN_EPI = false, bool SP2 = false>
; __device__ __forceinline__ void gemm_phase(PG8_LAS unsigned char* lds, const Gemm g, const Sched& S, const Epi& E, int wave_s) {
;     ...
;             PG8_WAIT_V(8); PG8_WAIT_L(0); PG8_BAR; PG8_MMA(0, 0, At, B0); PG8_MMA(0, 1, At, B1); PG8_BAR; PG8_SCHED;
;             PG8_LDA(At, 0, 1); PG8_STAGE(PG8_SB(0, 0), b2, voffB); PG8_STAGE(PG8_SB(0, 1), b2 + hstepB, voffB); PG8_STAGE(PG8_SA(0, 0), a2, voffA);
;             PG8_WAIT_V(8); PG8_WAIT_L(0); PG8_BAR; PG8_MMA(1, 0, At, B0); PG8_MMA(1, 1, At, B1); PG8_BAR; PG8_SCHED;
;             PG8_LDB(B0, 1, 0); PG8_LDB(B1, 1, 1); PG8_SCHED; PG8_LDA(At, 1, 0); PG8_STAGE(PG8_SA(0, 1), a2 + hstepA, voffA);
;             PG8_WAIT_V(8); PG8_WAIT_L(0); PG8_BAR; PG8_MMA(0, 0, At, B0); PG8_MMA(0, 1, At, B1); PG8_BAR; PG8_SCHED;
	s_waitcnt lgkmcnt(0)
	v_mfma_f32_16x16x32_bf16 v[54:57], v[126:129], v[162:165], 0
	v_mfma_f32_16x16x32_bf16 v[50:53], v[138:141], v[162:165], 0
	v_mfma_f32_16x16x32_bf16 v[38:41], v[126:129], v[170:173], 0
	v_mfma_f32_16x16x32_bf16 v[30:33], v[138:141], v[170:173], 0
	v_mfma_f32_16x16x32_bf16 v[86:89], v[126:129], v[178:181], 0
	v_mfma_f32_16x16x32_bf16 v[122:125], v[138:141], v[178:181], 0
	v_mfma_f32_16x16x32_bf16 v[114:117], v[126:129], v[186:189], 0
	v_mfma_f32_16x16x32_bf16 v[106:109], v[138:141], v[186:189], 0
	v_mfma_f32_16x16x32_bf16 v[54:57], v[134:137], v[166:169], v[54:57]
	v_mfma_f32_16x16x32_bf16 v[50:53], v[142:145], v[166:169], v[50:53]
	v_mfma_f32_16x16x32_bf16 v[38:41], v[134:137], v[174:177], v[38:41]
	v_mfma_f32_16x16x32_bf16 v[30:33], v[142:145], v[174:177], v[30:33]
	v_mfma_f32_16x16x32_bf16 v[86:89], v[134:137], v[182:185], v[86:89]
	v_mfma_f32_16x16x32_bf16 v[122:125], v[142:145], v[182:185], v[122:125]
	v_mfma_f32_16x16x32_bf16 v[114:117], v[134:137], v[190:193], v[114:117]
	v_mfma_f32_16x16x32_bf16 v[106:109], v[142:145], v[190:193], v[106:109]
	v_mfma_f32_16x16x32_bf16 v[22:25], v[146:149], v[162:165], 0
	v_mfma_f32_16x16x32_bf16 v[18:21], v[154:157], v[162:165], 0
	v_mfma_f32_16x16x32_bf16 v[10:13], v[146:149], v[170:173], 0
	v_mfma_f32_16x16x32_bf16 v[6:9], v[154:157], v[170:173], 0
	v_mfma_f32_16x16x32_bf16 v[82:85], v[146:149], v[178:181], 0
	v_mfma_f32_16x16x32_bf16 v[94:97], v[154:157], v[178:181], 0
	v_mfma_f32_16x16x32_bf16 v[70:73], v[146:149], v[186:189], 0
	v_mfma_f32_16x16x32_bf16 v[66:69], v[154:157], v[186:189], 0
	v_mfma_f32_16x16x32_bf16 v[22:25], v[150:153], v[166:169], v[22:25]
	v_mfma_f32_16x16x32_bf16 v[18:21], v[158:161], v[166:169], v[18:21]
	v_mfma_f32_16x16x32_bf16 v[10:13], v[150:153], v[174:177], v[10:13]
	v_mfma_f32_16x16x32_bf16 v[6:9], v[158:161], v[174:177], v[6:9]
	v_mfma_f32_16x16x32_bf16 v[82:85], v[150:153], v[182:185], v[82:85]
	v_mfma_f32_16x16x32_bf16 v[94:97], v[158:161], v[182:185], v[94:97]
	v_mfma_f32_16x16x32_bf16 v[70:73], v[150:153], v[190:193], v[70:73]
	v_mfma_f32_16x16x32_bf16 v[66:69], v[158:161], v[190:193], v[66:69]
	s_barrier
	s_add_i32 s86, 0, 0x18000
	s_add_i32 s87, 0, 0x1c000
	v_add_u32_e32 v142, s86, v251
	v_add_u32_e32 v158, s87, v251
	ds_read_b128 v[126:129], v142
	ds_read_b128 v[134:137], v142 offset:1024
	ds_read_b128 v[138:141], v142 offset:2048
	ds_read_b128 v[142:145], v142 offset:3072
	ds_read_b128 v[146:149], v158
	ds_read_b128 v[150:153], v158 offset:1024
	ds_read_b128 v[154:157], v158 offset:2048
	ds_read_b128 v[158:161], v158 offset:3072
	s_add_u32 s30, s40, 0x4000
	s_addc_u32 s31, s41, 0
	s_mov_b32 m0, s42
	ds_read_b128 v[162:165], v252 offset:32768
	ds_read_b128 v[166:169], v252 offset:33792
	ds_read_b128 v[170:173], v252 offset:34816
	ds_read_b128 v[174:177], v252 offset:35840
	ds_read_b128 v[178:181], v252 offset:36864
	ds_read_b128 v[182:185], v252 offset:37888
	ds_read_b128 v[186:189], v252 offset:38912
	ds_read_b128 v[190:193], v252 offset:39936
	global_load_lds_dwordx4 v236, s[30:31]
	s_mov_b32 m0, s43
	s_nop 0
	global_load_lds_dwordx4 v240, s[30:31]
	s_waitcnt vmcnt(8)
	s_waitcnt lgkmcnt(0)
	s_barrier
	s_waitcnt lgkmcnt(0)
	v_mfma_f32_16x16x32_bf16 v[130:133], v[126:129], v[162:165], v[130:133]
	v_mfma_f32_16x16x32_bf16 v[118:121], v[138:141], v[162:165], v[118:121]
	v_mfma_f32_16x16x32_bf16 v[110:113], v[126:129], v[170:173], v[110:113]
	v_mfma_f32_16x16x32_bf16 v[98:101], v[138:141], v[170:173], v[98:101]
	v_mfma_f32_16x16x32_bf16 v[62:65], v[126:129], v[178:181], v[62:65]
	v_mfma_f32_16x16x32_bf16 v[58:61], v[138:141], v[178:181], v[58:61]
	v_mfma_f32_16x16x32_bf16 v[46:49], v[126:129], v[186:189], v[46:49]
	v_mfma_f32_16x16x32_bf16 v[42:45], v[138:141], v[186:189], v[42:45]
	v_mfma_f32_16x16x32_bf16 v[130:133], v[134:137], v[166:169], v[130:133]
	v_mfma_f32_16x16x32_bf16 v[118:121], v[142:145], v[166:169], v[118:121]
	v_mfma_f32_16x16x32_bf16 v[110:113], v[134:137], v[174:177], v[110:113]
	v_mfma_f32_16x16x32_bf16 v[98:101], v[142:145], v[174:177], v[98:101]
	v_mfma_f32_16x16x32_bf16 v[62:65], v[134:137], v[182:185], v[62:65]
	v_mfma_f32_16x16x32_bf16 v[58:61], v[142:145], v[182:185], v[58:61]
	v_mfma_f32_16x16x32_bf16 v[46:49], v[134:137], v[190:193], v[46:49]
	v_mfma_f32_16x16x32_bf16 v[42:45], v[142:145], v[190:193], v[42:45]
	v_mfma_f32_16x16x32_bf16 v[102:105], v[146:149], v[162:165], v[102:105]
	v_mfma_f32_16x16x32_bf16 v[74:77], v[154:157], v[162:165], v[74:77]
	v_mfma_f32_16x16x32_bf16 v[78:81], v[146:149], v[170:173], v[78:81]
	v_mfma_f32_16x16x32_bf16 v[90:93], v[154:157], v[170:173], v[90:93]
	v_mfma_f32_16x16x32_bf16 v[34:37], v[146:149], v[178:181], v[34:37]
	v_mfma_f32_16x16x32_bf16 v[26:29], v[154:157], v[178:181], v[26:29]
	v_mfma_f32_16x16x32_bf16 v[14:17], v[146:149], v[186:189], v[14:17]
	v_mfma_f32_16x16x32_bf16 v[2:5], v[154:157], v[186:189], v[2:5]
	v_mfma_f32_16x16x32_bf16 v[102:105], v[150:153], v[166:169], v[102:105]
	v_mfma_f32_16x16x32_bf16 v[74:77], v[158:161], v[166:169], v[74:77]
	v_mfma_f32_16x16x32_bf16 v[78:81], v[150:153], v[174:177], v[78:81]
	v_mfma_f32_16x16x32_bf16 v[90:93], v[158:161], v[174:177], v[90:93]
	v_mfma_f32_16x16x32_bf16 v[34:37], v[150:153], v[182:185], v[34:37]
	v_mfma_f32_16x16x32_bf16 v[26:29], v[158:161], v[182:185], v[26:29]
	v_mfma_f32_16x16x32_bf16 v[14:17], v[150:153], v[190:193], v[14:17]
	v_mfma_f32_16x16x32_bf16 v[2:5], v[158:161], v[190:193], v[2:5]
	s_barrier
; #define PG8_STAGE(bufoff, gbase, voff) do { _Pragma("unroll") for (int _i = 0; _i < 2; ++_i) \
;         __builtin_amdgcn_global_load_lds((const unsigned*)((const char*)(gbase) + (voff)[_i]), (PG8_LAS unsigned*)(lds + (bufoff) + ldsw + _i * 8192), 16, 0, 0); } while (0)
; #define PG8_LDA(dst, b, h) do { _Pragma("unroll") for (int m = 0; m < 4; ++m) _Pragma("unroll") for (int k = 0; k < 2; ++k) dst[m][k] = *(const PG8_LAS bf16x8*)(lds + PG8_SA(b, h) + aoff + m * 2048 + k * 1024); } while (0)
; #define PG8_WAIT_V(n) asm volatile("s_waitcnt vmcnt(" #n ")" ::: "memory")
; #define PG8_WAIT_L(n) asm volatile("s_waitcnt lgkmcnt(" #n ")" ::: "memory")
; #define PG8_BAR __builtin_amdgcn_s_barrier()
; template <class Epi, class Sched, bool ALIGN_EPI = false, bool SP2 = false>
; __device__ __forceinline__ void gemm_phase(PG8_LAS unsigned char* lds, const Gemm g, const Sched& S, const Epi& E, int wave_s) {
;     ...
;         for (int t = 0; t < nt; t += 2) {
;             const bool last = (t == nt - 2);
;             const char* a1 = cA + (size_t)(t + 1) * kstep;
;             const char* a2 = last ? nA : cA + (size_t)(t + 2) * kstep; const char* b2 = last ? nB : cB + (size_t)(t + 2) * kstep;
;             const char* a3 = a2 + kstep; const char* b3 = b2 + kstep;
;             if (last && has_next) S.a_ready(nxt);
;             if constexpr (SP2) {
;             PG8_LDB(B0, 0, 0); PG8_LDB(B1, 0, 1); PG8_SCHED; PG8_LDA(At, 0, 0); PG8_STAGE(PG8_SA(1, 1), a1 + hstepA, voffA);
;             PG8_WAIT_V(8); PG8_WAIT_L(0); PG8_BAR; PG8_MMA(0, 0, At, B0); PG8_MMA(0, 1, At, B1); PG8_BAR; PG8_SCHED;
;             PG8_LDA(At, 0, 1); PG8_STAGE(PG8_SB(0, 0), b2, voffB); PG8_STAGE(PG8_SB(0, 1), b2 + hstepB, voffB); PG8_STAGE(PG8_SA(0, 0), a2, voffA);
;             PG8_WAIT_V(8); PG8_WAIT_L(0); PG8_BAR; PG8_MMA(1, 0, At, B0); PG8_MMA(1, 1, At, B1); PG8_BAR; PG8_SCHED;
;             PG8_LDB(B0, 1, 0); PG8_LDB(B1, 1, 1); PG8_SCHED; PG8_LDA(At, 1, 0); PG8_STAGE(PG8_SA(0, 1), a2 + hstepA, voffA);
;             PG8_WAIT_V(8); PG8_WAIT_L(0); PG8_BAR; PG8_MMA(0, 0, At, B0); PG8_MMA(0, 1, At, B1); PG8_BAR; PG8_SCHED;
;             PG8_LDA(At, 1, 1); PG8_STAGE(PG8_SB(1, 0), b3, voffB); PG8_STAGE(PG8_SB(1, 1), b3 + hstepB, voffB); PG8_STAGE(PG8_SA(1, 0), a3, voffA);
;             PG8_WAIT_V(8); PG8_WAIT_L(0); PG8_BAR; PG8_MMA(1, 0, At, B0); PG8_MMA(1, 1, At, B1); PG8_BAR; PG8_SCHED;
	s_add_i32 s30, s86, s35
	v_lshl_add_u64 v[194:195], v[194:195], 0, s[60:61]
	s_mov_b32 m0, s30
	ds_read_b128 v[162:165], v252 offset:49152
	ds_read_b128 v[166:169], v252 offset:50176
	ds_read_b128 v[170:173], v252 offset:51200
	ds_read_b128 v[174:177], v252 offset:52224
	ds_read_b128 v[178:181], v252 offset:53248
	ds_read_b128 v[182:185], v252 offset:54272
	ds_read_b128 v[186:189], v252 offset:55296
	ds_read_b128 v[190:193], v252 offset:56320
	global_load_lds_dwordx4 v[194:195], off
	s_add_i32 m0, s30, 0x2000
	s_add_u32 s6, s6, 0x80080
	v_lshl_add_u64 v[194:195], v[196:197], 0, s[60:61]
	s_addc_u32 s7, s7, 0
	s_add_i32 s30, s87, s35
	global_load_lds_dwordx4 v[194:195], off
	s_mov_b32 m0, s30
	s_nop 0
	global_load_lds_dwordx4 v238, s[6:7]
	s_add_i32 m0, s30, 0x2000
	s_nop 0
	global_load_lds_dwordx4 v242, s[6:7]
	v_lshl_add_u64 v[194:195], v[198:199], 0, s[60:61]
	s_mov_b32 m0, s77
	s_nop 0
	global_load_lds_dwordx4 v[194:195], off
	v_lshl_add_u64 v[194:195], v[200:201], 0, s[60:61]
	s_mov_b32 m0, s94
	s_nop 0
	global_load_lds_dwordx4 v[194:195], off
	s_waitcnt vmcnt(8)
	s_waitcnt lgkmcnt(0)
	s_barrier
	s_waitcnt lgkmcnt(0)
	v_mfma_f32_16x16x32_bf16 v[54:57], v[126:129], v[162:165], v[54:57]
	v_mfma_f32_16x16x32_bf16 v[50:53], v[138:141], v[162:165], v[50:53]
	v_mfma_f32_16x16x32_bf16 v[38:41], v[126:129], v[170:173], v[38:41]
	v_mfma_f32_16x16x32_bf16 v[30:33], v[138:141], v[170:173], v[30:33]
	v_mfma_f32_16x16x32_bf16 v[86:89], v[126:129], v[178:181], v[86:89]
	v_mfma_f32_16x16x32_bf16 v[122:125], v[138:141], v[178:181], v[122:125]
	v_mfma_f32_16x16x32_bf16 v[114:117], v[126:129], v[186:189], v[114:117]
	v_mfma_f32_16x16x32_bf16 v[106:109], v[138:141], v[186:189], v[106:109]
	v_mfma_f32_16x16x32_bf16 v[54:57], v[134:137], v[166:169], v[54:57]
	v_mfma_f32_16x16x32_bf16 v[50:53], v[142:145], v[166:169], v[50:53]
	v_mfma_f32_16x16x32_bf16 v[38:41], v[134:137], v[174:177], v[38:41]
	v_mfma_f32_16x16x32_bf16 v[30:33], v[142:145], v[174:177], v[30:33]
	v_mfma_f32_16x16x32_bf16 v[86:89], v[134:137], v[182:185], v[86:89]
	v_mfma_f32_16x16x32_bf16 v[122:125], v[142:145], v[182:185], v[122:125]
	v_mfma_f32_16x16x32_bf16 v[114:117], v[134:137], v[190:193], v[114:117]
	v_mfma_f32_16x16x32_bf16 v[106:109], v[142:145], v[190:193], v[106:109]
	v_mfma_f32_16x16x32_bf16 v[22:25], v[146:149], v[162:165], v[22:25]
	v_mfma_f32_16x16x32_bf16 v[18:21], v[154:157], v[162:165], v[18:21]
	v_mfma_f32_16x16x32_bf16 v[10:13], v[146:149], v[170:173], v[10:13]
	v_mfma_f32_16x16x32_bf16 v[6:9], v[154:157], v[170:173], v[6:9]
	v_mfma_f32_16x16x32_bf16 v[82:85], v[146:149], v[178:181], v[82:85]
	v_mfma_f32_16x16x32_bf16 v[94:97], v[154:157], v[178:181], v[94:97]
	v_mfma_f32_16x16x32_bf16 v[70:73], v[146:149], v[186:189], v[70:73]
	v_mfma_f32_16x16x32_bf16 v[66:69], v[154:157], v[186:189], v[66:69]
	v_mfma_f32_16x16x32_bf16 v[22:25], v[150:153], v[166:169], v[22:25]
	v_mfma_f32_16x16x32_bf16 v[18:21], v[158:161], v[166:169], v[18:21]
	v_mfma_f32_16x16x32_bf16 v[10:13], v[150:153], v[174:177], v[10:13]
	v_mfma_f32_16x16x32_bf16 v[6:9], v[158:161], v[174:177], v[6:9]
	v_mfma_f32_16x16x32_bf16 v[82:85], v[150:153], v[182:185], v[82:85]
	v_mfma_f32_16x16x32_bf16 v[94:97], v[158:161], v[182:185], v[94:97]
	v_mfma_f32_16x16x32_bf16 v[70:73], v[150:153], v[190:193], v[70:73]
	v_mfma_f32_16x16x32_bf16 v[66:69], v[158:161], v[190:193], v[66:69]
	s_barrier
	s_add_i32 vcc_lo, vcc_lo, 2
	s_add_u32 s89, s89, 0x100
	s_addc_u32 s91, s91, 0
	s_cmp_gt_u32 vcc_lo, 29
	s_mov_b64 s[30:31], s[4:5]
.LBB0_691:
	s_add_u32 s4, s30, 0x100
	s_addc_u32 s5, s31, 0
	s_add_i32 vcc_hi, 0, 0x10000
	s_cmp_eq_u32 vcc_lo, 28
	s_cselect_b32 s41, s21, s5
	s_cselect_b32 s40, s20, s4
	s_cselect_b32 s7, s2, s91
	s_cselect_b32 s6, s3, s89
	s_add_i32 s86, 0, 0x14000
	v_add_u32_e32 v142, vcc_hi, v251
	v_add_u32_e32 v158, s86, v251
	ds_read_b128 v[126:129], v142
	ds_read_b128 v[134:137], v142 offset:1024
	ds_read_b128 v[138:141], v142 offset:2048
	ds_read_b128 v[142:145], v142 offset:3072
	ds_read_b128 v[146:149], v158
	ds_read_b128 v[150:153], v158 offset:1024
	ds_read_b128 v[154:157], v158 offset:2048
	ds_read_b128 v[158:161], v158 offset:3072
	s_add_i32 m0, s36, 0xc000
	ds_read_b128 v[162:165], v252
	ds_read_b128 v[166:169], v252 offset:1024
	ds_read_b128 v[170:173], v252 offset:2048
	ds_read_b128 v[174:177], v252 offset:3072
	ds_read_b128 v[178:181], v252 offset:4096
	ds_read_b128 v[182:185], v252 offset:5120
	ds_read_b128 v[186:189], v252 offset:6144
	ds_read_b128 v[190:193], v252 offset:7168
	global_load_lds_dwordx4 v244, s[30:31]
	s_add_i32 m0, s36, 0xe000
	s_nop 0
	global_load_lds_dwordx4 v246, s[30:31]
	s_waitcnt vmcnt(8)
	s_waitcnt lgkmcnt(0)
	s_barrier
; #define PG8_STAGE(bufoff, gbase, voff) do { _Pragma("unroll") for (int _i = 0; _i < 2; ++_i) \
;         __builtin_amdgcn_global_load_lds((const unsigned*)((const char*)(gbase) + (voff)[_i]), (PG8_LAS unsigned*)(lds + (bufoff) + ldsw + _i * 8192), 16, 0, 0); } while (0)
; #define PG8_LDA(dst, b, h) do { _Pragma("unroll") for (int m = 0; m < 4; ++m) _Pragma("unroll") for (int k = 0; k < 2; ++k) dst[m][k] = *(const PG8_LAS bf16x8*)(lds + PG8_SA(b, h) + aoff + m * 2048 + k * 1024); } while (0)
; #define PG8_LDB(dst, b, h) do { _Pragma("unroll") for (int n = 0; n < 2; ++n) _Pragma("unroll") for (int k = 0; k < 2; ++k) dst[n][k] = *(const PG8_LAS bf16x8*)(lds + PG8_SB(b, h) + boff + n * 2048 + k * 1024); } while (0)
; #define PG8_MMA(ai, bj, At, Bt) do { __builtin_amdgcn_s_setprio(1); _Pragma("unroll") for (int m = 0; m < 4; ++m) _Pragma("unroll") for (int n = 0; n < 2; ++n) _Pragma("unroll") for (int k = 0; k < 2; ++k) \
;         acc[ai][bj][m][n] = __builtin_amdgcn_mfma_f32_16x16x32_bf16(Bt[n][k], At[m][k], acc[ai][bj][m][n], 0, 0, 0); __builtin_amdgcn_s_setprio(0); } while (0)
; #define PG8_WAIT_V(n) asm volatile("s_waitcnt vmcnt(" #n ")" ::: "memory")
; #define PG8_WAIT_L(n) asm volatile("s_waitcnt lgkmcnt(" #n ")" ::: "memory")
; #define PG8_BAR __builtin_amdgcn_s_barrier()
; #define PG8_SCHED __builtin_amdgcn_sched_barrier(0)
; template <class Epi, class Sched, bool ALIGN_EPI = false, bool SP2 = false>
; __device__ __forceinline__ void gemm_phase(PG8_LAS unsigned char* lds, const Gemm g, const Sched& S, const Epi& E, int wave_s) {
;     ...
;             PG8_LDB(B0, 0, 0); PG8_LDB(B1, 0, 1); PG8_SCHED; PG8_LDA(At, 0, 0); PG8_STAGE(PG8_SA(1, 1), a1 + hstepA, voffA);
;             PG8_WAIT_V(8); PG8_WAIT_L(0); PG8_BAR; PG8_MMA(0, 0, At, B0); PG8_MMA(0, 1, At, B1); PG8_BAR; PG8_SCHED;
;             PG8_LDA(At, 0, 1); PG8_STAGE(PG8_SB(0, 0), b2, voffB); PG8_STAGE(PG8_SB(0, 1), b2 + hstepB, voffB); PG8_STAGE(PG8_SA(0, 0), a2, voffA);
;             PG8_WAIT_V(8); PG8_WAIT_L(0); PG8_BAR; PG8_MMA(1, 0, At, B0); PG8_MMA(1, 1, At, B1); PG8_BAR; PG8_SCHED;
	s_waitcnt lgkmcnt(0)
	v_mfma_f32_16x16x32_bf16 v[130:133], v[126:129], v[162:165], v[130:133]
	v_mfma_f32_16x16x32_bf16 v[118:121], v[138:141], v[162:165], v[118:121]
	v_mfma_f32_16x16x32_bf16 v[110:113], v[126:129], v[170:173], v[110:113]
	v_mfma_f32_16x16x32_bf16 v[98:101], v[138:141], v[170:173], v[98:101]
	v_mfma_f32_16x16x32_bf16 v[62:65], v[126:129], v[178:181], v[62:65]
	v_mfma_f32_16x16x32_bf16 v[58:61], v[138:141], v[178:181], v[58:61]
	v_mfma_f32_16x16x32_bf16 v[46:49], v[126:129], v[186:189], v[46:49]
	v_mfma_f32_16x16x32_bf16 v[42:45], v[138:141], v[186:189], v[42:45]
	v_mfma_f32_16x16x32_bf16 v[130:133], v[134:137], v[166:169], v[130:133]
	v_mfma_f32_16x16x32_bf16 v[118:121], v[142:145], v[166:169], v[118:121]
	v_mfma_f32_16x16x32_bf16 v[110:113], v[134:137], v[174:177], v[110:113]
	v_mfma_f32_16x16x32_bf16 v[98:101], v[142:145], v[174:177], v[98:101]
	v_mfma_f32_16x16x32_bf16 v[62:65], v[134:137], v[182:185], v[62:65]
	v_mfma_f32_16x16x32_bf16 v[58:61], v[142:145], v[182:185], v[58:61]
	v_mfma_f32_16x16x32_bf16 v[46:49], v[134:137], v[190:193], v[46:49]
	v_mfma_f32_16x16x32_bf16 v[42:45], v[142:145], v[190:193], v[42:45]
	v_mfma_f32_16x16x32_bf16 v[102:105], v[146:149], v[162:165], v[102:105]
	v_mfma_f32_16x16x32_bf16 v[74:77], v[154:157], v[162:165], v[74:77]
	v_mfma_f32_16x16x32_bf16 v[78:81], v[146:149], v[170:173], v[78:81]
	v_mfma_f32_16x16x32_bf16 v[90:93], v[154:157], v[170:173], v[90:93]
	v_mfma_f32_16x16x32_bf16 v[34:37], v[146:149], v[178:181], v[34:37]
	v_mfma_f32_16x16x32_bf16 v[26:29], v[154:157], v[178:181], v[26:29]
	v_mfma_f32_16x16x32_bf16 v[14:17], v[146:149], v[186:189], v[14:17]
	v_mfma_f32_16x16x32_bf16 v[2:5], v[154:157], v[186:189], v[2:5]
	v_mfma_f32_16x16x32_bf16 v[102:105], v[150:153], v[166:169], v[102:105]
	v_mfma_f32_16x16x32_bf16 v[74:77], v[158:161], v[166:169], v[74:77]
	v_mfma_f32_16x16x32_bf16 v[78:81], v[150:153], v[174:177], v[78:81]
	v_mfma_f32_16x16x32_bf16 v[90:93], v[158:161], v[174:177], v[90:93]
	v_mfma_f32_16x16x32_bf16 v[34:37], v[150:153], v[182:185], v[34:37]
	v_mfma_f32_16x16x32_bf16 v[26:29], v[158:161], v[182:185], v[26:29]
	v_mfma_f32_16x16x32_bf16 v[14:17], v[150:153], v[190:193], v[14:17]
	v_mfma_f32_16x16x32_bf16 v[2:5], v[158:161], v[190:193], v[2:5]
	s_barrier
	s_add_i32 s30, vcc_hi, s35
	v_lshl_add_u64 v[194:195], s[6:7], 0, v[238:239]
	s_mov_b32 m0, s30
	ds_read_b128 v[162:165], v252 offset:16384
	ds_read_b128 v[166:169], v252 offset:17408
	ds_read_b128 v[170:173], v252 offset:18432
	ds_read_b128 v[174:177], v252 offset:19456
	ds_read_b128 v[178:181], v252 offset:20480
	ds_read_b128 v[182:185], v252 offset:21504
	ds_read_b128 v[186:189], v252 offset:22528
	ds_read_b128 v[190:193], v252 offset:23552
	global_load_lds_dwordx4 v[194:195], off
	s_add_i32 m0, s30, 0x2000
	s_add_u32 s30, s6, 0x80000
	v_lshl_add_u64 v[196:197], s[6:7], 0, v[242:243]
	s_addc_u32 s31, s7, 0
	s_add_i32 s86, s86, s35
	global_load_lds_dwordx4 v[196:197], off
	s_mov_b32 m0, s86
	v_lshl_add_u64 v[200:201], s[40:41], 0, v[240:241]
	global_load_lds_dwordx4 v238, s[30:31]
	s_add_i32 m0, s86, 0x2000
	s_nop 0
	global_load_lds_dwordx4 v242, s[30:31]
	v_lshl_add_u64 v[198:199], s[40:41], 0, v[236:237]
	s_mov_b32 m0, s36
	s_nop 0
	global_load_lds_dwordx4 v[198:199], off
	s_mov_b32 m0, s37
	s_nop 0
	global_load_lds_dwordx4 v[200:201], off
	s_waitcnt vmcnt(8)
	s_waitcnt lgkmcnt(0)
	s_barrier
	s_waitcnt lgkmcnt(0)
	v_mfma_f32_16x16x32_bf16 v[54:57], v[126:129], v[162:165], v[54:57]
	v_mfma_f32_16x16x32_bf16 v[50:53], v[138:141], v[162:165], v[50:53]
	v_mfma_f32_16x16x32_bf16 v[38:41], v[126:129], v[170:173], v[38:41]
	v_mfma_f32_16x16x32_bf16 v[30:33], v[138:141], v[170:173], v[30:33]
	v_mfma_f32_16x16x32_bf16 v[86:89], v[126:129], v[178:181], v[86:89]
	v_mfma_f32_16x16x32_bf16 v[122:125], v[138:141], v[178:181], v[122:125]
	v_mfma_f32_16x16x32_bf16 v[114:117], v[126:129], v[186:189], v[114:117]
	v_mfma_f32_16x16x32_bf16 v[106:109], v[138:141], v[186:189], v[106:109]
	v_mfma_f32_16x16x32_bf16 v[54:57], v[134:137], v[166:169], v[54:57]
	v_mfma_f32_16x16x32_bf16 v[50:53], v[142:145], v[166:169], v[50:53]
	v_mfma_f32_16x16x32_bf16 v[38:41], v[134:137], v[174:177], v[38:41]
	v_mfma_f32_16x16x32_bf16 v[30:33], v[142:145], v[174:177], v[30:33]
	v_mfma_f32_16x16x32_bf16 v[86:89], v[134:137], v[182:185], v[86:89]
	v_mfma_f32_16x16x32_bf16 v[122:125], v[142:145], v[182:185], v[122:125]
	v_mfma_f32_16x16x32_bf16 v[114:117], v[134:137], v[190:193], v[114:117]
	v_mfma_f32_16x16x32_bf16 v[106:109], v[142:145], v[190:193], v[106:109]
	v_mfma_f32_16x16x32_bf16 v[22:25], v[146:149], v[162:165], v[22:25]
	v_mfma_f32_16x16x32_bf16 v[18:21], v[154:157], v[162:165], v[18:21]
	v_mfma_f32_16x16x32_bf16 v[10:13], v[146:149], v[170:173], v[10:13]
	v_mfma_f32_16x16x32_bf16 v[6:9], v[154:157], v[170:173], v[6:9]
	v_mfma_f32_16x16x32_bf16 v[82:85], v[146:149], v[178:181], v[82:85]
	v_mfma_f32_16x16x32_bf16 v[94:97], v[154:157], v[178:181], v[94:97]
	v_mfma_f32_16x16x32_bf16 v[70:73], v[146:149], v[186:189], v[70:73]
	v_mfma_f32_16x16x32_bf16 v[66:69], v[154:157], v[186:189], v[66:69]
	v_mfma_f32_16x16x32_bf16 v[22:25], v[150:153], v[166:169], v[22:25]
	v_mfma_f32_16x16x32_bf16 v[18:21], v[158:161], v[166:169], v[18:21]
	v_mfma_f32_16x16x32_bf16 v[10:13], v[150:153], v[174:177], v[10:13]
	v_mfma_f32_16x16x32_bf16 v[6:9], v[158:161], v[174:177], v[6:9]
	v_mfma_f32_16x16x32_bf16 v[82:85], v[150:153], v[182:185], v[82:85]
	v_mfma_f32_16x16x32_bf16 v[94:97], v[158:161], v[182:185], v[94:97]
	v_mfma_f32_16x16x32_bf16 v[70:73], v[150:153], v[190:193], v[70:73]
	v_mfma_f32_16x16x32_bf16 v[66:69], v[158:161], v[190:193], v[66:69]
	s_barrier
; #define PG8_STAGE(bufoff, gbase, voff) do { _Pragma("unroll") for (int _i = 0; _i < 2; ++_i) \
;         __builtin_amdgcn_global_load_lds((const unsigned*)((const char*)(gbase) + (voff)[_i]), (PG8_LAS unsigned*)(lds + (bufoff) + ldsw + _i * 8192), 16, 0, 0); } while (0)
; #define PG8_LDA(dst, b, h) do { _Pragma("unroll") for (int m = 0; m < 4; ++m) _Pragma("unroll") for (int k = 0; k < 2; ++k) dst[m][k] = *(const PG8_LAS bf16x8*)(lds + PG8_SA(b, h) + aoff + m * 2048 + k * 1024); } while (0)
; #define PG8_LDB(dst, b, h) do { _Pragma("unroll") for (int n = 0; n < 2; ++n) _Pragma("unroll") for (int k = 0; k < 2; ++k) dst[n][k] = *(const PG8_LAS bf16x8*)(lds + PG8_SB(b, h) + boff + n * 2048 + k * 1024); } while (0)
; #define PG8_MMA(ai, bj, At, Bt) do { __builtin_amdgcn_s_setprio(1); _Pragma("unroll") for (int m = 0; m < 4; ++m) _Pragma("unroll") for (int n = 0; n < 2; ++n) _Pragma("unroll") for (int k = 0; k < 2; ++k) \
;         acc[ai][bj][m][n] = __builtin_amdgcn_mfma_f32_16x16x32_bf16(Bt[n][k], At[m][k], acc[ai][bj][m][n], 0, 0, 0); __builtin_amdgcn_s_setprio(0); } while (0)
; #define PG8_WAIT_V(n) asm volatile("s_waitcnt vmcnt(" #n ")" ::: "memory")
; #define PG8_WAIT_L(n) asm volatile("s_waitcnt lgkmcnt(" #n ")" ::: "memory")
; #define PG8_BAR __builtin_amdgcn_s_barrier()
; template <class Epi, class Sched, bool ALIGN_EPI = false, bool SP2 = false>
; __device__ __forceinline__ void gemm_phase(PG8_LAS unsigned char* lds, const Gemm g, const Sched& S, const Epi& E, int wave_s) {
;     ...
;             PG8_LDA(At, 0, 1); PG8_STAGE(PG8_SB(0, 0), b2, voffB); PG8_STAGE(PG8_SB(0, 1), b2 + hstepB, voffB); PG8_STAGE(PG8_SA(0, 0), a2, voffA);
;             PG8_WAIT_V(8); PG8_WAIT_L(0); PG8_BAR; PG8_MMA(1, 0, At, B0); PG8_MMA(1, 1, At, B1); PG8_BAR; PG8_SCHED;
;             PG8_LDB(B0, 1, 0); PG8_LDB(B1, 1, 1); PG8_SCHED; PG8_LDA(At, 1, 0); PG8_STAGE(PG8_SA(0, 1), a2 + hstepA, voffA);
;             PG8_WAIT_V(8); PG8_WAIT_L(0); PG8_BAR; PG8_MMA(0, 0, At, B0); PG8_MMA(0, 1, At, B1); PG8_BAR; PG8_SCHED;
;             PG8_LDA(At, 1, 1); PG8_STAGE(PG8_SB(1, 0), b3, voffB); PG8_STAGE(PG8_SB(1, 1), b3 + hstepB, voffB); PG8_STAGE(PG8_SA(1, 0), a3, voffA);
;             PG8_WAIT_V(8); PG8_WAIT_L(0); PG8_BAR; PG8_MMA(1, 0, At, B0); PG8_MMA(1, 1, At, B1); PG8_BAR; PG8_SCHED;
;     ...
;         if constexpr (ALIGN_EPI) { if (wr == 0) PG8_BAR; }
	s_add_i32 s86, 0, 0x18000
	s_add_i32 s87, 0, 0x1c000
	v_add_u32_e32 v142, s86, v251
	v_add_u32_e32 v158, s87, v251
	ds_read_b128 v[126:129], v142
	ds_read_b128 v[134:137], v142 offset:1024
	ds_read_b128 v[138:141], v142 offset:2048
	ds_read_b128 v[142:145], v142 offset:3072
	ds_read_b128 v[146:149], v158
	ds_read_b128 v[150:153], v158 offset:1024
	ds_read_b128 v[154:157], v158 offset:2048
	ds_read_b128 v[158:161], v158 offset:3072
	s_add_u32 s30, s40, 0x4000
	s_addc_u32 s31, s41, 0
	s_mov_b32 m0, s42
	ds_read_b128 v[162:165], v252 offset:32768
	ds_read_b128 v[166:169], v252 offset:33792
	ds_read_b128 v[170:173], v252 offset:34816
	ds_read_b128 v[174:177], v252 offset:35840
	ds_read_b128 v[178:181], v252 offset:36864
	ds_read_b128 v[182:185], v252 offset:37888
	ds_read_b128 v[186:189], v252 offset:38912
	ds_read_b128 v[190:193], v252 offset:39936
	global_load_lds_dwordx4 v236, s[30:31]
	v_lshl_add_u64 v[202:203], s[30:31], 0, v[240:241]
	s_mov_b32 m0, s43
	s_nop 0
	global_load_lds_dwordx4 v[202:203], off
	s_waitcnt vmcnt(8)
	s_waitcnt lgkmcnt(0)
	s_barrier
	s_waitcnt lgkmcnt(0)
	v_mfma_f32_16x16x32_bf16 v[130:133], v[126:129], v[162:165], v[130:133]
	v_mfma_f32_16x16x32_bf16 v[118:121], v[138:141], v[162:165], v[118:121]
	v_mfma_f32_16x16x32_bf16 v[110:113], v[126:129], v[170:173], v[110:113]
	v_mfma_f32_16x16x32_bf16 v[98:101], v[138:141], v[170:173], v[98:101]
	v_mfma_f32_16x16x32_bf16 v[62:65], v[126:129], v[178:181], v[62:65]
	v_mfma_f32_16x16x32_bf16 v[58:61], v[138:141], v[178:181], v[58:61]
	v_mfma_f32_16x16x32_bf16 v[46:49], v[126:129], v[186:189], v[46:49]
	v_mfma_f32_16x16x32_bf16 v[42:45], v[138:141], v[186:189], v[42:45]
	v_mfma_f32_16x16x32_bf16 v[130:133], v[134:137], v[166:169], v[130:133]
	v_mfma_f32_16x16x32_bf16 v[118:121], v[142:145], v[166:169], v[118:121]
	v_mfma_f32_16x16x32_bf16 v[110:113], v[134:137], v[174:177], v[110:113]
	v_mfma_f32_16x16x32_bf16 v[98:101], v[142:145], v[174:177], v[98:101]
	v_mfma_f32_16x16x32_bf16 v[62:65], v[134:137], v[182:185], v[62:65]
	v_mfma_f32_16x16x32_bf16 v[58:61], v[142:145], v[182:185], v[58:61]
	v_mfma_f32_16x16x32_bf16 v[46:49], v[134:137], v[190:193], v[46:49]
	v_mfma_f32_16x16x32_bf16 v[42:45], v[142:145], v[190:193], v[42:45]
	v_mfma_f32_16x16x32_bf16 v[102:105], v[146:149], v[162:165], v[102:105]
	v_mfma_f32_16x16x32_bf16 v[74:77], v[154:157], v[162:165], v[74:77]
	v_mfma_f32_16x16x32_bf16 v[78:81], v[146:149], v[170:173], v[78:81]
	v_mfma_f32_16x16x32_bf16 v[90:93], v[154:157], v[170:173], v[90:93]
	v_mfma_f32_16x16x32_bf16 v[34:37], v[146:149], v[178:181], v[34:37]
	v_mfma_f32_16x16x32_bf16 v[26:29], v[154:157], v[178:181], v[26:29]
	v_mfma_f32_16x16x32_bf16 v[14:17], v[146:149], v[186:189], v[14:17]
	v_mfma_f32_16x16x32_bf16 v[2:5], v[154:157], v[186:189], v[2:5]
	v_mfma_f32_16x16x32_bf16 v[102:105], v[150:153], v[166:169], v[102:105]
	v_mfma_f32_16x16x32_bf16 v[74:77], v[158:161], v[166:169], v[74:77]
	v_mfma_f32_16x16x32_bf16 v[78:81], v[150:153], v[174:177], v[78:81]
	v_mfma_f32_16x16x32_bf16 v[90:93], v[158:161], v[174:177], v[90:93]
	v_mfma_f32_16x16x32_bf16 v[34:37], v[150:153], v[182:185], v[34:37]
	v_mfma_f32_16x16x32_bf16 v[26:29], v[158:161], v[182:185], v[26:29]
	v_mfma_f32_16x16x32_bf16 v[14:17], v[150:153], v[190:193], v[14:17]
	v_mfma_f32_16x16x32_bf16 v[2:5], v[158:161], v[190:193], v[2:5]
	s_barrier
	s_add_i32 s30, s86, s35
	v_lshl_add_u64 v[194:195], v[194:195], 0, s[60:61]
	s_mov_b32 m0, s30
	ds_read_b128 v[162:165], v252 offset:49152
	ds_read_b128 v[166:169], v252 offset:50176
	ds_read_b128 v[170:173], v252 offset:51200
	ds_read_b128 v[174:177], v252 offset:52224
	ds_read_b128 v[178:181], v252 offset:53248
	ds_read_b128 v[182:185], v252 offset:54272
	ds_read_b128 v[186:189], v252 offset:55296
	ds_read_b128 v[190:193], v252 offset:56320
	global_load_lds_dwordx4 v[194:195], off
	s_add_i32 m0, s30, 0x2000
	s_add_u32 s6, s6, 0x80080
	v_lshl_add_u64 v[194:195], v[196:197], 0, s[60:61]
	s_addc_u32 s7, s7, 0
	s_add_i32 s30, s87, s35
	global_load_lds_dwordx4 v[194:195], off
	s_mov_b32 m0, s30
	s_nop 0
	global_load_lds_dwordx4 v238, s[6:7]
	s_add_i32 m0, s30, 0x2000
	s_nop 0
	global_load_lds_dwordx4 v242, s[6:7]
	v_lshl_add_u64 v[194:195], v[198:199], 0, s[60:61]
	s_mov_b32 m0, s77
	s_nop 0
	global_load_lds_dwordx4 v[194:195], off
	v_lshl_add_u64 v[194:195], v[200:201], 0, s[60:61]
	s_mov_b32 m0, s94
	s_nop 0
	global_load_lds_dwordx4 v[194:195], off
	s_waitcnt vmcnt(8)
	s_waitcnt lgkmcnt(0)
	s_barrier
	s_waitcnt lgkmcnt(0)
	v_mfma_f32_16x16x32_bf16 v[54:57], v[126:129], v[162:165], v[54:57]
	v_mfma_f32_16x16x32_bf16 v[50:53], v[138:141], v[162:165], v[50:53]
	v_mfma_f32_16x16x32_bf16 v[38:41], v[126:129], v[170:173], v[38:41]
	v_mfma_f32_16x16x32_bf16 v[30:33], v[138:141], v[170:173], v[30:33]
	v_mfma_f32_16x16x32_bf16 v[86:89], v[126:129], v[178:181], v[86:89]
	v_mfma_f32_16x16x32_bf16 v[122:125], v[138:141], v[178:181], v[122:125]
	v_mfma_f32_16x16x32_bf16 v[114:117], v[126:129], v[186:189], v[114:117]
	v_mfma_f32_16x16x32_bf16 v[106:109], v[138:141], v[186:189], v[106:109]
	v_mfma_f32_16x16x32_bf16 v[54:57], v[134:137], v[166:169], v[54:57]
	v_mfma_f32_16x16x32_bf16 v[50:53], v[142:145], v[166:169], v[50:53]
	v_mfma_f32_16x16x32_bf16 v[38:41], v[134:137], v[174:177], v[38:41]
	v_mfma_f32_16x16x32_bf16 v[30:33], v[142:145], v[174:177], v[30:33]
	v_mfma_f32_16x16x32_bf16 v[86:89], v[134:137], v[182:185], v[86:89]
	v_mfma_f32_16x16x32_bf16 v[122:125], v[142:145], v[182:185], v[122:125]
	v_mfma_f32_16x16x32_bf16 v[114:117], v[134:137], v[190:193], v[114:117]
	v_mfma_f32_16x16x32_bf16 v[106:109], v[142:145], v[190:193], v[106:109]
	v_mfma_f32_16x16x32_bf16 v[22:25], v[146:149], v[162:165], v[22:25]
	v_mfma_f32_16x16x32_bf16 v[18:21], v[154:157], v[162:165], v[18:21]
	v_mfma_f32_16x16x32_bf16 v[10:13], v[146:149], v[170:173], v[10:13]
	v_mfma_f32_16x16x32_bf16 v[6:9], v[154:157], v[170:173], v[6:9]
	v_mfma_f32_16x16x32_bf16 v[82:85], v[146:149], v[178:181], v[82:85]
	v_mfma_f32_16x16x32_bf16 v[94:97], v[154:157], v[178:181], v[94:97]
	v_mfma_f32_16x16x32_bf16 v[70:73], v[146:149], v[186:189], v[70:73]
	v_mfma_f32_16x16x32_bf16 v[66:69], v[154:157], v[186:189], v[66:69]
	v_mfma_f32_16x16x32_bf16 v[22:25], v[150:153], v[166:169], v[22:25]
	v_mfma_f32_16x16x32_bf16 v[18:21], v[158:161], v[166:169], v[18:21]
	v_mfma_f32_16x16x32_bf16 v[10:13], v[150:153], v[174:177], v[10:13]
	v_mfma_f32_16x16x32_bf16 v[6:9], v[158:161], v[174:177], v[6:9]
	v_mfma_f32_16x16x32_bf16 v[82:85], v[150:153], v[182:185], v[82:85]
	v_mfma_f32_16x16x32_bf16 v[94:97], v[158:161], v[182:185], v[94:97]
	v_mfma_f32_16x16x32_bf16 v[70:73], v[150:153], v[190:193], v[70:73]
	v_mfma_f32_16x16x32_bf16 v[66:69], v[158:161], v[190:193], v[66:69]
	s_barrier
	s_add_i32 vcc_lo, vcc_lo, 2
	s_add_u32 s89, s89, 0x100
	s_addc_u32 s91, s91, 0
	s_cmp_gt_u32 vcc_lo, 29
	s_mov_b64 s[30:31], s[4:5]
	s_cbranch_scc0 .LBB0_691
	s_and_b64 vcc, exec, s[26:27]
	s_cbranch_vccz .LBB0_694
	s_barrier

; #define PG8_STAGE(bufoff, gbase, voff) do { _Pragma("unroll") for (int _i = 0; _i < 2; ++_i) \
;         __builtin_amdgcn_global_load_lds((const unsigned*)((const char*)(gbase) + (voff)[_i]), (PG8_LAS unsigned*)(lds + (bufoff) + ldsw + _i * 8192), 16, 0, 0); } while (0)
; #define PG8_LDA(dst, b, h) do { _Pragma("unroll") for (int m = 0; m < 4; ++m) _Pragma("unroll") for (int k = 0; k < 2; ++k) dst[m][k] = *(const PG8_LAS bf16x8*)(lds + PG8_SA(b, h) + aoff + m * 2048 + k * 1024); } while (0)
; #define PG8_LDB(dst, b, h) do { _Pragma("unroll") for (int n = 0; n < 2; ++n) _Pragma("unroll") for (int k = 0; k < 2; ++k) dst[n][k] = *(const PG8_LAS bf16x8*)(lds + PG8_SB(b, h) + boff + n * 2048 + k * 1024); } while (0)
; #define PG8_WAIT_V(n) asm volatile("s_waitcnt vmcnt(" #n ")" ::: "memory")
; #define PG8_WAIT_L(n) asm volatile("s_waitcnt lgkmcnt(" #n ")" ::: "memory")
; #define PG8_BAR __builtin_amdgcn_s_barrier()
; template <class Epi, class Sched, bool ALIGN_EPI = false, bool SP2 = false>
; __device__ __forceinline__ void gemm_phase(PG8_LAS unsigned char* lds, const Gemm g, const Sched& S, const Epi& E, int wave_s) {
;     ...
;         const bool has_next = S.next(ui + 1, nxt);
;         const char* nA = has_next ? (const char*)g.A + (size_t)nxt.pm * tstepA + (size_t)(nxt.pn / g.npg) * (size_t)(K * 2) : cA; const char* nB = has_next ? (const char*)g.Bt + (size_t)nxt.pn * tstepB : cB;
;         for (int t = 0; t < nt; t += 2) {
;             const bool last = (t == nt - 2);
;             const char* a1 = cA + (size_t)(t + 1) * kstep;
;             const char* a2 = last ? nA : cA + (size_t)(t + 2) * kstep; const char* b2 = last ? nB : cB + (size_t)(t + 2) * kstep;
;             const char* a3 = a2 + kstep; const char* b3 = b2 + kstep;
;             if (last && has_next) S.a_ready(nxt);
;             if constexpr (SP2) {
;             PG8_LDB(B0, 0, 0); PG8_LDB(B1, 0, 1); PG8_SCHED; PG8_LDA(At, 0, 0); PG8_STAGE(PG8_SA(1, 1), a1 + hstepA, voffA);
;             PG8_WAIT_V(8); PG8_WAIT_L(0); PG8_BAR; PG8_MMA(0, 0, At, B0); PG8_MMA(0, 1, At, B1); PG8_BAR; PG8_SCHED;
;             PG8_LDA(At, 0, 1); PG8_STAGE(PG8_SB(0, 0), b2, voffB); PG8_STAGE(PG8_SB(0, 1), b2 + hstepB, voffB); PG8_STAGE(PG8_SA(0, 0), a2, voffA);
;             PG8_WAIT_V(8); PG8_WAIT_L(0); PG8_BAR; PG8_MMA(1, 0, At, B0); PG8_MMA(1, 1, At, B1); PG8_BAR; PG8_SCHED;
.LBB0_785:
	s_add_u32 s2, s30, 0x100
	s_addc_u32 s3, s31, 0
	s_mov_b32 s81, -2
	s_add_u32 s4, s8, 0x100
	s_addc_u32 s5, s9, 0
	s_add_i32 s84, 0, 0x10000
	s_cmpk_eq_i32 s81, 0x54
	s_cselect_b32 s31, s95, s5
	s_cselect_b32 s30, s94, s4
	s_cselect_b32 s7, s97, s3
	s_cselect_b32 s6, s96, s2
	s_add_i32 s85, 0, 0x14000
	v_add_u32_e32 v110, s84, v211
	v_add_u32_e32 v150, s85, v211
	ds_read_b128 v[78:81], v110
	ds_read_b128 v[86:89], v110 offset:1024
	ds_read_b128 v[102:105], v110 offset:2048
	ds_read_b128 v[110:113], v110 offset:3072
	ds_read_b128 v[122:125], v150
	ds_read_b128 v[134:137], v150 offset:1024
	ds_read_b128 v[146:149], v150 offset:2048
	ds_read_b128 v[150:153], v150 offset:3072
	s_add_i32 m0, s35, 0xc000
	ds_read_b128 v[162:165], v212
	ds_read_b128 v[166:169], v212 offset:1024
	ds_read_b128 v[170:173], v212 offset:2048
	ds_read_b128 v[174:177], v212 offset:3072
	ds_read_b128 v[178:181], v212 offset:4096
	ds_read_b128 v[182:185], v212 offset:5120
	ds_read_b128 v[186:189], v212 offset:6144
	ds_read_b128 v[202:205], v212 offset:7168
	global_load_lds_dwordx4 v198, s[8:9]
	s_add_i32 m0, s35, 0xe000
	s_nop 0
	global_load_lds_dwordx4 v200, s[8:9]
	s_waitcnt vmcnt(8)
	s_waitcnt lgkmcnt(0)
	s_barrier
	s_waitcnt lgkmcnt(0)
	v_mfma_f32_16x16x32_bf16 v[158:161], v[78:81], v[162:165], 0
	v_mfma_f32_16x16x32_bf16 v[154:157], v[102:105], v[162:165], 0
	v_mfma_f32_16x16x32_bf16 v[130:133], v[78:81], v[170:173], 0
	v_mfma_f32_16x16x32_bf16 v[126:129], v[102:105], v[170:173], 0
	v_mfma_f32_16x16x32_bf16 v[106:109], v[78:81], v[178:181], 0
	v_mfma_f32_16x16x32_bf16 v[98:101], v[102:105], v[178:181], 0
	v_mfma_f32_16x16x32_bf16 v[82:85], v[78:81], v[186:189], 0
	v_mfma_f32_16x16x32_bf16 v[74:77], v[102:105], v[186:189], 0
	v_mfma_f32_16x16x32_bf16 v[158:161], v[86:89], v[166:169], v[158:161]
	v_mfma_f32_16x16x32_bf16 v[154:157], v[110:113], v[166:169], v[154:157]
	v_mfma_f32_16x16x32_bf16 v[130:133], v[86:89], v[174:177], v[130:133]
	v_mfma_f32_16x16x32_bf16 v[126:129], v[110:113], v[174:177], v[126:129]
	v_mfma_f32_16x16x32_bf16 v[106:109], v[86:89], v[182:185], v[106:109]
	v_mfma_f32_16x16x32_bf16 v[98:101], v[110:113], v[182:185], v[98:101]
	v_mfma_f32_16x16x32_bf16 v[82:85], v[86:89], v[202:205], v[82:85]
	v_mfma_f32_16x16x32_bf16 v[74:77], v[110:113], v[202:205], v[74:77]
	v_mfma_f32_16x16x32_bf16 v[142:145], v[122:125], v[162:165], 0
	v_mfma_f32_16x16x32_bf16 v[138:141], v[146:149], v[162:165], 0
	v_mfma_f32_16x16x32_bf16 v[118:121], v[122:125], v[170:173], 0
	v_mfma_f32_16x16x32_bf16 v[114:117], v[146:149], v[170:173], 0
	v_mfma_f32_16x16x32_bf16 v[94:97], v[122:125], v[178:181], 0
	v_mfma_f32_16x16x32_bf16 v[90:93], v[146:149], v[178:181], 0
	v_mfma_f32_16x16x32_bf16 v[70:73], v[122:125], v[186:189], 0
	v_mfma_f32_16x16x32_bf16 v[66:69], v[146:149], v[186:189], 0
	v_mfma_f32_16x16x32_bf16 v[142:145], v[134:137], v[166:169], v[142:145]
	v_mfma_f32_16x16x32_bf16 v[138:141], v[150:153], v[166:169], v[138:141]
	v_mfma_f32_16x16x32_bf16 v[118:121], v[134:137], v[174:177], v[118:121]
	v_mfma_f32_16x16x32_bf16 v[114:117], v[150:153], v[174:177], v[114:117]
	v_mfma_f32_16x16x32_bf16 v[94:97], v[134:137], v[182:185], v[94:97]
	v_mfma_f32_16x16x32_bf16 v[90:93], v[150:153], v[182:185], v[90:93]
	v_mfma_f32_16x16x32_bf16 v[70:73], v[134:137], v[202:205], v[70:73]
	v_mfma_f32_16x16x32_bf16 v[66:69], v[150:153], v[202:205], v[66:69]
	s_barrier
	s_add_i32 s8, s84, s22
	v_lshl_add_u64 v[206:207], s[6:7], 0, v[194:195]
	s_mov_b32 m0, s8
	ds_read_b128 v[162:165], v212 offset:16384
	ds_read_b128 v[166:169], v212 offset:17408
	ds_read_b128 v[170:173], v212 offset:18432
	ds_read_b128 v[174:177], v212 offset:19456
	ds_read_b128 v[178:181], v212 offset:20480
	ds_read_b128 v[182:185], v212 offset:21504
	ds_read_b128 v[186:189], v212 offset:22528
	ds_read_b128 v[202:205], v212 offset:23552
	global_load_lds_dwordx4 v[206:207], off
	s_add_i32 m0, s8, 0x2000
	s_add_u32 s8, s6, 0x160000
	v_lshl_add_u64 v[208:209], s[6:7], 0, v[190:191]
	s_addc_u32 s9, s7, 0
	s_add_i32 s84, s85, s22
	global_load_lds_dwordx4 v[208:209], off
	s_mov_b32 m0, s84
	v_lshl_add_u64 v[216:217], s[30:31], 0, v[192:193]
	global_load_lds_dwordx4 v194, s[8:9]
	s_add_i32 m0, s84, 0x2000
	s_nop 0
	global_load_lds_dwordx4 v190, s[8:9]
	v_lshl_add_u64 v[214:215], s[30:31], 0, v[196:197]
	s_mov_b32 m0, s35
	s_nop 0
	global_load_lds_dwordx4 v[214:215], off
	s_mov_b32 m0, s36
	s_nop 0
	global_load_lds_dwordx4 v[216:217], off
	s_waitcnt vmcnt(8)
	s_waitcnt lgkmcnt(0)
	s_barrier
	s_waitcnt lgkmcnt(0)
	v_mfma_f32_16x16x32_bf16 v[62:65], v[78:81], v[162:165], 0
	v_mfma_f32_16x16x32_bf16 v[58:61], v[102:105], v[162:165], 0
	v_mfma_f32_16x16x32_bf16 v[46:49], v[78:81], v[170:173], 0
	v_mfma_f32_16x16x32_bf16 v[42:45], v[102:105], v[170:173], 0
	v_mfma_f32_16x16x32_bf16 v[30:33], v[78:81], v[178:181], 0
	v_mfma_f32_16x16x32_bf16 v[26:29], v[102:105], v[178:181], 0
	v_mfma_f32_16x16x32_bf16 v[14:17], v[78:81], v[186:189], 0
	v_mfma_f32_16x16x32_bf16 v[10:13], v[102:105], v[186:189], 0
	v_mfma_f32_16x16x32_bf16 v[62:65], v[86:89], v[166:169], v[62:65]
	v_mfma_f32_16x16x32_bf16 v[58:61], v[110:113], v[166:169], v[58:61]
	v_mfma_f32_16x16x32_bf16 v[46:49], v[86:89], v[174:177], v[46:49]
	v_mfma_f32_16x16x32_bf16 v[42:45], v[110:113], v[174:177], v[42:45]
	v_mfma_f32_16x16x32_bf16 v[30:33], v[86:89], v[182:185], v[30:33]
	v_mfma_f32_16x16x32_bf16 v[26:29], v[110:113], v[182:185], v[26:29]
	v_mfma_f32_16x16x32_bf16 v[14:17], v[86:89], v[202:205], v[14:17]
	v_mfma_f32_16x16x32_bf16 v[10:13], v[110:113], v[202:205], v[10:13]
	v_mfma_f32_16x16x32_bf16 v[54:57], v[122:125], v[162:165], 0
	v_mfma_f32_16x16x32_bf16 v[50:53], v[146:149], v[162:165], 0
	v_mfma_f32_16x16x32_bf16 v[38:41], v[122:125], v[170:173], 0
	v_mfma_f32_16x16x32_bf16 v[34:37], v[146:149], v[170:173], 0
	v_mfma_f32_16x16x32_bf16 v[22:25], v[122:125], v[178:181], 0
	v_mfma_f32_16x16x32_bf16 v[18:21], v[146:149], v[178:181], 0
	v_mfma_f32_16x16x32_bf16 v[6:9], v[122:125], v[186:189], 0
	v_mfma_f32_16x16x32_bf16 v[2:5], v[146:149], v[186:189], 0
	v_mfma_f32_16x16x32_bf16 v[54:57], v[134:137], v[166:169], v[54:57]
	v_mfma_f32_16x16x32_bf16 v[50:53], v[150:153], v[166:169], v[50:53]
	v_mfma_f32_16x16x32_bf16 v[38:41], v[134:137], v[174:177], v[38:41]
	v_mfma_f32_16x16x32_bf16 v[34:37], v[150:153], v[174:177], v[34:37]
	v_mfma_f32_16x16x32_bf16 v[22:25], v[134:137], v[182:185], v[22:25]
	v_mfma_f32_16x16x32_bf16 v[18:21], v[150:153], v[182:185], v[18:21]
	v_mfma_f32_16x16x32_bf16 v[6:9], v[134:137], v[202:205], v[6:9]
	v_mfma_f32_16x16x32_bf16 v[2:5], v[150:153], v[202:205], v[2:5]
	s_barrier
; #define PG8_STAGE(bufoff, gbase, voff) do { _Pragma("unroll") for (int _i = 0; _i < 2; ++_i) \
;         __builtin_amdgcn_global_load_lds((const unsigned*)((const char*)(gbase) + (voff)[_i]), (PG8_LAS unsigned*)(lds + (bufoff) + ldsw + _i * 8192), 16, 0, 0); } while (0)
; #define PG8_LDA(dst, b, h) do { _Pragma("unroll") for (int m = 0; m < 4; ++m) _Pragma("unroll") for (int k = 0; k < 2; ++k) dst[m][k] = *(const PG8_LAS bf16x8*)(lds + PG8_SA(b, h) + aoff + m * 2048 + k * 1024); } while (0)
; #define PG8_LDB(dst, b, h) do { _Pragma("unroll") for (int n = 0; n < 2; ++n) _Pragma("unroll") for (int k = 0; k < 2; ++k) dst[n][k] = *(const PG8_LAS bf16x8*)(lds + PG8_SB(b, h) + boff + n * 2048 + k * 1024); } while (0)
; #define PG8_MMA(ai, bj, At, Bt) do { __builtin_amdgcn_s_setprio(1); _Pragma("unroll") for (int m = 0; m < 4; ++m) _Pragma("unroll") for (int n = 0; n < 2; ++n) _Pragma("unroll") for (int k = 0; k < 2; ++k) \
;         acc[ai][bj][m][n] = __builtin_amdgcn_mfma_f32_16x16x32_bf16(Bt[n][k], At[m][k], acc[ai][bj][m][n], 0, 0, 0); __builtin_amdgcn_s_setprio(0); } while (0)
; #define PG8_WAIT_V(n) asm volatile("s_waitcnt vmcnt(" #n ")" ::: "memory")
; #define PG8_WAIT_L(n) asm volatile("s_waitcnt lgkmcnt(" #n ")" ::: "memory")
; #define PG8_BAR __builtin_amdgcn_s_barrier()
; #define PG8_SCHED __builtin_amdgcn_sched_barrier(0)
; template <class Epi, class Sched, bool ALIGN_EPI = false, bool SP2 = false>
; __device__ __forceinline__ void gemm_phase(PG8_LAS unsigned char* lds, const Gemm g, const Sched& S, const Epi& E, int wave_s) {
;     ...
;             PG8_LDB(B0, 1, 0); PG8_LDB(B1, 1, 1); PG8_SCHED; PG8_LDA(At, 1, 0); PG8_STAGE(PG8_SA(0, 1), a2 + hstepA, voffA);
;             PG8_WAIT_V(8); PG8_WAIT_L(0); PG8_BAR; PG8_MMA(0, 0, At, B0); PG8_MMA(0, 1, At, B1); PG8_BAR; PG8_SCHED;
;             PG8_LDA(At, 1, 1); PG8_STAGE(PG8_SB(1, 0), b3, voffB); PG8_STAGE(PG8_SB(1, 1), b3 + hstepB, voffB); PG8_STAGE(PG8_SA(1, 0), a3, voffA);
;             PG8_WAIT_V(8); PG8_WAIT_L(0); PG8_BAR; PG8_MMA(1, 0, At, B0); PG8_MMA(1, 1, At, B1); PG8_BAR; PG8_SCHED;
	s_add_i32 s84, 0, 0x18000
	s_add_i32 s85, 0, 0x1c000
	v_add_u32_e32 v110, s84, v211
	v_add_u32_e32 v150, s85, v211
	ds_read_b128 v[78:81], v110
	ds_read_b128 v[86:89], v110 offset:1024
	ds_read_b128 v[102:105], v110 offset:2048
	ds_read_b128 v[110:113], v110 offset:3072
	ds_read_b128 v[122:125], v150
	ds_read_b128 v[134:137], v150 offset:1024
	ds_read_b128 v[146:149], v150 offset:2048
	ds_read_b128 v[150:153], v150 offset:3072
	s_add_u32 s8, s30, 0x160000
	s_addc_u32 s9, s31, 0
	s_mov_b32 m0, s37
	ds_read_b128 v[162:165], v212 offset:32768
	ds_read_b128 v[166:169], v212 offset:33792
	ds_read_b128 v[170:173], v212 offset:34816
	ds_read_b128 v[174:177], v212 offset:35840
	ds_read_b128 v[178:181], v212 offset:36864
	ds_read_b128 v[182:185], v212 offset:37888
	ds_read_b128 v[186:189], v212 offset:38912
	ds_read_b128 v[202:205], v212 offset:39936
	global_load_lds_dwordx4 v196, s[8:9]
	s_mov_b32 m0, s40
	s_nop 0
	global_load_lds_dwordx4 v192, s[8:9]
	s_waitcnt vmcnt(8)
	s_waitcnt lgkmcnt(0)
	s_barrier
	s_waitcnt lgkmcnt(0)
	v_mfma_f32_16x16x32_bf16 v[158:161], v[78:81], v[162:165], v[158:161]
	v_mfma_f32_16x16x32_bf16 v[154:157], v[102:105], v[162:165], v[154:157]
	v_mfma_f32_16x16x32_bf16 v[130:133], v[78:81], v[170:173], v[130:133]
	v_mfma_f32_16x16x32_bf16 v[126:129], v[102:105], v[170:173], v[126:129]
	v_mfma_f32_16x16x32_bf16 v[106:109], v[78:81], v[178:181], v[106:109]
	v_mfma_f32_16x16x32_bf16 v[98:101], v[102:105], v[178:181], v[98:101]
	v_mfma_f32_16x16x32_bf16 v[82:85], v[78:81], v[186:189], v[82:85]
	v_mfma_f32_16x16x32_bf16 v[74:77], v[102:105], v[186:189], v[74:77]
	v_mfma_f32_16x16x32_bf16 v[158:161], v[86:89], v[166:169], v[158:161]
	v_mfma_f32_16x16x32_bf16 v[154:157], v[110:113], v[166:169], v[154:157]
	v_mfma_f32_16x16x32_bf16 v[130:133], v[86:89], v[174:177], v[130:133]
	v_mfma_f32_16x16x32_bf16 v[126:129], v[110:113], v[174:177], v[126:129]
	v_mfma_f32_16x16x32_bf16 v[106:109], v[86:89], v[182:185], v[106:109]
	v_mfma_f32_16x16x32_bf16 v[98:101], v[110:113], v[182:185], v[98:101]
	v_mfma_f32_16x16x32_bf16 v[82:85], v[86:89], v[202:205], v[82:85]
	v_mfma_f32_16x16x32_bf16 v[74:77], v[110:113], v[202:205], v[74:77]
	v_mfma_f32_16x16x32_bf16 v[142:145], v[122:125], v[162:165], v[142:145]
	v_mfma_f32_16x16x32_bf16 v[138:141], v[146:149], v[162:165], v[138:141]
	v_mfma_f32_16x16x32_bf16 v[118:121], v[122:125], v[170:173], v[118:121]
	v_mfma_f32_16x16x32_bf16 v[114:117], v[146:149], v[170:173], v[114:117]
	v_mfma_f32_16x16x32_bf16 v[94:97], v[122:125], v[178:181], v[94:97]
	v_mfma_f32_16x16x32_bf16 v[90:93], v[146:149], v[178:181], v[90:93]
	v_mfma_f32_16x16x32_bf16 v[70:73], v[122:125], v[186:189], v[70:73]
	v_mfma_f32_16x16x32_bf16 v[66:69], v[146:149], v[186:189], v[66:69]
	v_mfma_f32_16x16x32_bf16 v[142:145], v[134:137], v[166:169], v[142:145]
	v_mfma_f32_16x16x32_bf16 v[138:141], v[150:153], v[166:169], v[138:141]
	v_mfma_f32_16x16x32_bf16 v[118:121], v[134:137], v[174:177], v[118:121]
	v_mfma_f32_16x16x32_bf16 v[114:117], v[150:153], v[174:177], v[114:117]
	v_mfma_f32_16x16x32_bf16 v[94:97], v[134:137], v[182:185], v[94:97]
	v_mfma_f32_16x16x32_bf16 v[90:93], v[150:153], v[182:185], v[90:93]
	v_mfma_f32_16x16x32_bf16 v[70:73], v[134:137], v[202:205], v[70:73]
	v_mfma_f32_16x16x32_bf16 v[66:69], v[150:153], v[202:205], v[66:69]
	s_barrier
	s_add_i32 s8, s84, s22
	v_lshl_add_u64 v[206:207], v[206:207], 0, s[60:61]
	s_mov_b32 m0, s8
	ds_read_b128 v[162:165], v212 offset:49152
	ds_read_b128 v[166:169], v212 offset:50176
	ds_read_b128 v[170:173], v212 offset:51200
	ds_read_b128 v[174:177], v212 offset:52224
	ds_read_b128 v[178:181], v212 offset:53248
	ds_read_b128 v[182:185], v212 offset:54272
	ds_read_b128 v[186:189], v212 offset:55296
	ds_read_b128 v[202:205], v212 offset:56320
	global_load_lds_dwordx4 v[206:207], off
	s_add_i32 m0, s8, 0x2000
	s_add_u32 s6, s6, 0x160080
	v_lshl_add_u64 v[206:207], v[208:209], 0, s[60:61]
	s_addc_u32 s7, s7, 0
	s_add_i32 s8, s85, s22
	global_load_lds_dwordx4 v[206:207], off
	s_mov_b32 m0, s8
	s_nop 0
	global_load_lds_dwordx4 v194, s[6:7]
	s_add_i32 m0, s8, 0x2000
	s_nop 0
	global_load_lds_dwordx4 v190, s[6:7]
	v_lshl_add_u64 v[206:207], v[214:215], 0, s[60:61]
	s_mov_b32 m0, s44
	s_nop 0
	global_load_lds_dwordx4 v[206:207], off
	v_lshl_add_u64 v[206:207], v[216:217], 0, s[60:61]
	s_mov_b32 m0, s45
	s_nop 0
	global_load_lds_dwordx4 v[206:207], off
	s_waitcnt vmcnt(8)
	s_waitcnt lgkmcnt(0)
	s_barrier
	s_waitcnt lgkmcnt(0)
	v_mfma_f32_16x16x32_bf16 v[62:65], v[78:81], v[162:165], v[62:65]
	v_mfma_f32_16x16x32_bf16 v[58:61], v[102:105], v[162:165], v[58:61]
	v_mfma_f32_16x16x32_bf16 v[46:49], v[78:81], v[170:173], v[46:49]
	v_mfma_f32_16x16x32_bf16 v[42:45], v[102:105], v[170:173], v[42:45]
	v_mfma_f32_16x16x32_bf16 v[30:33], v[78:81], v[178:181], v[30:33]
	v_mfma_f32_16x16x32_bf16 v[26:29], v[102:105], v[178:181], v[26:29]
	v_mfma_f32_16x16x32_bf16 v[14:17], v[78:81], v[186:189], v[14:17]
	v_mfma_f32_16x16x32_bf16 v[10:13], v[102:105], v[186:189], v[10:13]
	v_mfma_f32_16x16x32_bf16 v[62:65], v[86:89], v[166:169], v[62:65]
	v_mfma_f32_16x16x32_bf16 v[58:61], v[110:113], v[166:169], v[58:61]
	v_mfma_f32_16x16x32_bf16 v[46:49], v[86:89], v[174:177], v[46:49]
	v_mfma_f32_16x16x32_bf16 v[42:45], v[110:113], v[174:177], v[42:45]
	v_mfma_f32_16x16x32_bf16 v[30:33], v[86:89], v[182:185], v[30:33]
	v_mfma_f32_16x16x32_bf16 v[26:29], v[110:113], v[182:185], v[26:29]
	v_mfma_f32_16x16x32_bf16 v[14:17], v[86:89], v[202:205], v[14:17]
	v_mfma_f32_16x16x32_bf16 v[10:13], v[110:113], v[202:205], v[10:13]
	v_mfma_f32_16x16x32_bf16 v[54:57], v[122:125], v[162:165], v[54:57]
	v_mfma_f32_16x16x32_bf16 v[50:53], v[146:149], v[162:165], v[50:53]
	v_mfma_f32_16x16x32_bf16 v[38:41], v[122:125], v[170:173], v[38:41]
	v_mfma_f32_16x16x32_bf16 v[34:37], v[146:149], v[170:173], v[34:37]
	v_mfma_f32_16x16x32_bf16 v[22:25], v[122:125], v[178:181], v[22:25]
	v_mfma_f32_16x16x32_bf16 v[18:21], v[146:149], v[178:181], v[18:21]
	v_mfma_f32_16x16x32_bf16 v[6:9], v[122:125], v[186:189], v[6:9]
	v_mfma_f32_16x16x32_bf16 v[2:5], v[146:149], v[186:189], v[2:5]
	v_mfma_f32_16x16x32_bf16 v[54:57], v[134:137], v[166:169], v[54:57]
	v_mfma_f32_16x16x32_bf16 v[50:53], v[150:153], v[166:169], v[50:53]
	v_mfma_f32_16x16x32_bf16 v[38:41], v[134:137], v[174:177], v[38:41]
	v_mfma_f32_16x16x32_bf16 v[34:37], v[150:153], v[174:177], v[34:37]
	v_mfma_f32_16x16x32_bf16 v[22:25], v[134:137], v[182:185], v[22:25]
	v_mfma_f32_16x16x32_bf16 v[18:21], v[150:153], v[182:185], v[18:21]
	v_mfma_f32_16x16x32_bf16 v[6:9], v[134:137], v[202:205], v[6:9]
	v_mfma_f32_16x16x32_bf16 v[2:5], v[150:153], v[202:205], v[2:5]
	s_barrier
	s_add_i32 s81, s81, 2
	s_add_u32 s2, s2, 0x100
	s_addc_u32 s3, s3, 0
	s_cmpk_gt_u32 s81, 0x55
	s_mov_b64 s[8:9], s[4:5]
; #define PG8_STAGE(bufoff, gbase, voff) do { _Pragma("unroll") for (int _i = 0; _i < 2; ++_i) \
;         __builtin_amdgcn_global_load_lds((const unsigned*)((const char*)(gbase) + (voff)[_i]), (PG8_LAS unsigned*)(lds + (bufoff) + ldsw + _i * 8192), 16, 0, 0); } while (0)
; #define PG8_LDA(dst, b, h) do { _Pragma("unroll") for (int m = 0; m < 4; ++m) _Pragma("unroll") for (int k = 0; k < 2; ++k) dst[m][k] = *(const PG8_LAS bf16x8*)(lds + PG8_SA(b, h) + aoff + m * 2048 + k * 1024); } while (0)
; #define PG8_LDB(dst, b, h) do { _Pragma("unroll") for (int n = 0; n < 2; ++n) _Pragma("unroll") for (int k = 0; k < 2; ++k) dst[n][k] = *(const PG8_LAS bf16x8*)(lds + PG8_SB(b, h) + boff + n * 2048 + k * 1024); } while (0)
; #define PG8_MMA(ai, bj, At, Bt) do { __builtin_amdgcn_s_setprio(1); _Pragma("unroll") for (int m = 0; m < 4; ++m) _Pragma("unroll") for (int n = 0; n < 2; ++n) _Pragma("unroll") for (int k = 0; k < 2; ++k) \
;         acc[ai][bj][m][n] = __builtin_amdgcn_mfma_f32_16x16x32_bf16(Bt[n][k], At[m][k], acc[ai][bj][m][n], 0, 0, 0); __builtin_amdgcn_s_setprio(0); } while (0)
; #define PG8_WAIT_V(n) asm volatile("s_waitcnt vmcnt(" #n ")" ::: "memory")
; #define PG8_BAR __builtin_amdgcn_s_barrier()
; template <class Epi, class Sched, bool ALIGN_EPI = false, bool SP2 = false>
; __device__ __forceinline__ void gemm_phase(PG8_LAS unsigned char* lds, const Gemm g, const Sched& S, const Epi& E, int wave_s) {
;     ...
;         for (int t = 0; t < nt; t += 2) {
;             const bool last = (t == nt - 2);
;             const char* a1 = cA + (size_t)(t + 1) * kstep;
;             const char* a2 = last ? nA : cA + (size_t)(t + 2) * kstep; const char* b2 = last ? nB : cB + (size_t)(t + 2) * kstep;
;             const char* a3 = a2 + kstep; const char* b3 = b2 + kstep;
;             if (last && has_next) S.a_ready(nxt);
;             if constexpr (SP2) {
;             PG8_LDB(B0, 0, 0); PG8_LDB(B1, 0, 1); PG8_SCHED; PG8_LDA(At, 0, 0); PG8_STAGE(PG8_SA(1, 1), a1 + hstepA, voffA);
;             PG8_WAIT_V(8); PG8_WAIT_L(0); PG8_BAR; PG8_MMA(0, 0, At, B0); PG8_MMA(0, 1, At, B1); PG8_BAR; PG8_SCHED;
;             PG8_LDA(At, 0, 1); PG8_STAGE(PG8_SB(0, 0), b2, voffB); PG8_STAGE(PG8_SB(0, 1), b2 + hstepB, voffB); PG8_STAGE(PG8_SA(0, 0), a2, voffA);
;             PG8_WAIT_V(8); PG8_WAIT_L(0); PG8_BAR; PG8_MMA(1, 0, At, B0); PG8_MMA(1, 1, At, B1); PG8_BAR; PG8_SCHED;
.LBB0_786:
	s_add_u32 s4, s8, 0x100
	s_addc_u32 s5, s9, 0
	s_add_i32 s84, 0, 0x10000
	s_cmpk_eq_i32 s81, 0x54
	s_cselect_b32 s31, s95, s5
	s_cselect_b32 s30, s94, s4
	s_cselect_b32 s7, s97, s3
	s_cselect_b32 s6, s96, s2
	s_add_i32 s85, 0, 0x14000
	v_add_u32_e32 v110, s84, v211
	v_add_u32_e32 v150, s85, v211
	ds_read_b128 v[78:81], v110
	ds_read_b128 v[86:89], v110 offset:1024
	ds_read_b128 v[102:105], v110 offset:2048
	ds_read_b128 v[110:113], v110 offset:3072
	ds_read_b128 v[122:125], v150
	ds_read_b128 v[134:137], v150 offset:1024
	ds_read_b128 v[146:149], v150 offset:2048
	ds_read_b128 v[150:153], v150 offset:3072
	s_add_i32 m0, s35, 0xc000
	ds_read_b128 v[162:165], v212
	ds_read_b128 v[166:169], v212 offset:1024
	ds_read_b128 v[170:173], v212 offset:2048
	ds_read_b128 v[174:177], v212 offset:3072
	ds_read_b128 v[178:181], v212 offset:4096
	ds_read_b128 v[182:185], v212 offset:5120
	ds_read_b128 v[186:189], v212 offset:6144
	ds_read_b128 v[202:205], v212 offset:7168
	global_load_lds_dwordx4 v198, s[8:9]
	s_add_i32 m0, s35, 0xe000
	s_nop 0
	global_load_lds_dwordx4 v200, s[8:9]
	s_waitcnt vmcnt(8)
	s_waitcnt lgkmcnt(0)
	s_barrier
	s_waitcnt lgkmcnt(0)
	v_mfma_f32_16x16x32_bf16 v[158:161], v[78:81], v[162:165], v[158:161]
	v_mfma_f32_16x16x32_bf16 v[154:157], v[102:105], v[162:165], v[154:157]
	v_mfma_f32_16x16x32_bf16 v[130:133], v[78:81], v[170:173], v[130:133]
	v_mfma_f32_16x16x32_bf16 v[126:129], v[102:105], v[170:173], v[126:129]
	v_mfma_f32_16x16x32_bf16 v[106:109], v[78:81], v[178:181], v[106:109]
	v_mfma_f32_16x16x32_bf16 v[98:101], v[102:105], v[178:181], v[98:101]
	v_mfma_f32_16x16x32_bf16 v[82:85], v[78:81], v[186:189], v[82:85]
	v_mfma_f32_16x16x32_bf16 v[74:77], v[102:105], v[186:189], v[74:77]
	v_mfma_f32_16x16x32_bf16 v[158:161], v[86:89], v[166:169], v[158:161]
	v_mfma_f32_16x16x32_bf16 v[154:157], v[110:113], v[166:169], v[154:157]
	v_mfma_f32_16x16x32_bf16 v[130:133], v[86:89], v[174:177], v[130:133]
	v_mfma_f32_16x16x32_bf16 v[126:129], v[110:113], v[174:177], v[126:129]
	v_mfma_f32_16x16x32_bf16 v[106:109], v[86:89], v[182:185], v[106:109]
	v_mfma_f32_16x16x32_bf16 v[98:101], v[110:113], v[182:185], v[98:101]
	v_mfma_f32_16x16x32_bf16 v[82:85], v[86:89], v[202:205], v[82:85]
	v_mfma_f32_16x16x32_bf16 v[74:77], v[110:113], v[202:205], v[74:77]
	v_mfma_f32_16x16x32_bf16 v[142:145], v[122:125], v[162:165], v[142:145]
	v_mfma_f32_16x16x32_bf16 v[138:141], v[146:149], v[162:165], v[138:141]
	v_mfma_f32_16x16x32_bf16 v[118:121], v[122:125], v[170:173], v[118:121]
	v_mfma_f32_16x16x32_bf16 v[114:117], v[146:149], v[170:173], v[114:117]
	v_mfma_f32_16x16x32_bf16 v[94:97], v[122:125], v[178:181], v[94:97]
	v_mfma_f32_16x16x32_bf16 v[90:93], v[146:149], v[178:181], v[90:93]
	v_mfma_f32_16x16x32_bf16 v[70:73], v[122:125], v[186:189], v[70:73]
	v_mfma_f32_16x16x32_bf16 v[66:69], v[146:149], v[186:189], v[66:69]
	v_mfma_f32_16x16x32_bf16 v[142:145], v[134:137], v[166:169], v[142:145]
	v_mfma_f32_16x16x32_bf16 v[138:141], v[150:153], v[166:169], v[138:141]
	v_mfma_f32_16x16x32_bf16 v[118:121], v[134:137], v[174:177], v[118:121]
	v_mfma_f32_16x16x32_bf16 v[114:117], v[150:153], v[174:177], v[114:117]
	v_mfma_f32_16x16x32_bf16 v[94:97], v[134:137], v[182:185], v[94:97]
	v_mfma_f32_16x16x32_bf16 v[90:93], v[150:153], v[182:185], v[90:93]
	v_mfma_f32_16x16x32_bf16 v[70:73], v[134:137], v[202:205], v[70:73]
	v_mfma_f32_16x16x32_bf16 v[66:69], v[150:153], v[202:205], v[66:69]
	s_barrier
	s_add_i32 s8, s84, s22
	v_lshl_add_u64 v[206:207], s[6:7], 0, v[194:195]
	s_mov_b32 m0, s8
	ds_read_b128 v[162:165], v212 offset:16384
	ds_read_b128 v[166:169], v212 offset:17408
	ds_read_b128 v[170:173], v212 offset:18432
	ds_read_b128 v[174:177], v212 offset:19456
	ds_read_b128 v[178:181], v212 offset:20480
	ds_read_b128 v[182:185], v212 offset:21504
	ds_read_b128 v[186:189], v212 offset:22528
	ds_read_b128 v[202:205], v212 offset:23552
	global_load_lds_dwordx4 v[206:207], off
	s_add_i32 m0, s8, 0x2000
	s_add_u32 s8, s6, 0x160000
	v_lshl_add_u64 v[208:209], s[6:7], 0, v[190:191]
	s_addc_u32 s9, s7, 0
	s_add_i32 s84, s85, s22
	global_load_lds_dwordx4 v[208:209], off
	s_mov_b32 m0, s84
	v_lshl_add_u64 v[216:217], s[30:31], 0, v[192:193]
	global_load_lds_dwordx4 v194, s[8:9]
	s_add_i32 m0, s84, 0x2000
	s_nop 0
	global_load_lds_dwordx4 v190, s[8:9]
	v_lshl_add_u64 v[214:215], s[30:31], 0, v[196:197]
	s_mov_b32 m0, s35
	s_nop 0
	global_load_lds_dwordx4 v[214:215], off
	s_mov_b32 m0, s36
	s_nop 0
	global_load_lds_dwordx4 v[216:217], off
	s_waitcnt vmcnt(8)
	s_waitcnt lgkmcnt(0)
	s_barrier
; #define PG8_STAGE(bufoff, gbase, voff) do { _Pragma("unroll") for (int _i = 0; _i < 2; ++_i) \
;         __builtin_amdgcn_global_load_lds((const unsigned*)((const char*)(gbase) + (voff)[_i]), (PG8_LAS unsigned*)(lds + (bufoff) + ldsw + _i * 8192), 16, 0, 0); } while (0)
; #define PG8_LDA(dst, b, h) do { _Pragma("unroll") for (int m = 0; m < 4; ++m) _Pragma("unroll") for (int k = 0; k < 2; ++k) dst[m][k] = *(const PG8_LAS bf16x8*)(lds + PG8_SA(b, h) + aoff + m * 2048 + k * 1024); } while (0)
; #define PG8_LDB(dst, b, h) do { _Pragma("unroll") for (int n = 0; n < 2; ++n) _Pragma("unroll") for (int k = 0; k < 2; ++k) dst[n][k] = *(const PG8_LAS bf16x8*)(lds + PG8_SB(b, h) + boff + n * 2048 + k * 1024); } while (0)
; #define PG8_MMA(ai, bj, At, Bt) do { __builtin_amdgcn_s_setprio(1); _Pragma("unroll") for (int m = 0; m < 4; ++m) _Pragma("unroll") for (int n = 0; n < 2; ++n) _Pragma("unroll") for (int k = 0; k < 2; ++k) \
;         acc[ai][bj][m][n] = __builtin_amdgcn_mfma_f32_16x16x32_bf16(Bt[n][k], At[m][k], acc[ai][bj][m][n], 0, 0, 0); __builtin_amdgcn_s_setprio(0); } while (0)
; #define PG8_WAIT_V(n) asm volatile("s_waitcnt vmcnt(" #n ")" ::: "memory")
; #define PG8_WAIT_L(n) asm volatile("s_waitcnt lgkmcnt(" #n ")" ::: "memory")
; #define PG8_BAR __builtin_amdgcn_s_barrier()
; #define PG8_SCHED __builtin_amdgcn_sched_barrier(0)
; template <class Epi, class Sched, bool ALIGN_EPI = false, bool SP2 = false>
; __device__ __forceinline__ void gemm_phase(PG8_LAS unsigned char* lds, const Gemm g, const Sched& S, const Epi& E, int wave_s) {
;     ...
;             PG8_LDA(At, 0, 1); PG8_STAGE(PG8_SB(0, 0), b2, voffB); PG8_STAGE(PG8_SB(0, 1), b2 + hstepB, voffB); PG8_STAGE(PG8_SA(0, 0), a2, voffA);
;             PG8_WAIT_V(8); PG8_WAIT_L(0); PG8_BAR; PG8_MMA(1, 0, At, B0); PG8_MMA(1, 1, At, B1); PG8_BAR; PG8_SCHED;
;             PG8_LDB(B0, 1, 0); PG8_LDB(B1, 1, 1); PG8_SCHED; PG8_LDA(At, 1, 0); PG8_STAGE(PG8_SA(0, 1), a2 + hstepA, voffA);
;             PG8_WAIT_V(8); PG8_WAIT_L(0); PG8_BAR; PG8_MMA(0, 0, At, B0); PG8_MMA(0, 1, At, B1); PG8_BAR; PG8_SCHED;
	s_waitcnt lgkmcnt(0)
	v_mfma_f32_16x16x32_bf16 v[62:65], v[78:81], v[162:165], v[62:65]
	v_mfma_f32_16x16x32_bf16 v[58:61], v[102:105], v[162:165], v[58:61]
	v_mfma_f32_16x16x32_bf16 v[46:49], v[78:81], v[170:173], v[46:49]
	v_mfma_f32_16x16x32_bf16 v[42:45], v[102:105], v[170:173], v[42:45]
	v_mfma_f32_16x16x32_bf16 v[30:33], v[78:81], v[178:181], v[30:33]
	v_mfma_f32_16x16x32_bf16 v[26:29], v[102:105], v[178:181], v[26:29]
	v_mfma_f32_16x16x32_bf16 v[14:17], v[78:81], v[186:189], v[14:17]
	v_mfma_f32_16x16x32_bf16 v[10:13], v[102:105], v[186:189], v[10:13]
	v_mfma_f32_16x16x32_bf16 v[62:65], v[86:89], v[166:169], v[62:65]
	v_mfma_f32_16x16x32_bf16 v[58:61], v[110:113], v[166:169], v[58:61]
	v_mfma_f32_16x16x32_bf16 v[46:49], v[86:89], v[174:177], v[46:49]
	v_mfma_f32_16x16x32_bf16 v[42:45], v[110:113], v[174:177], v[42:45]
	v_mfma_f32_16x16x32_bf16 v[30:33], v[86:89], v[182:185], v[30:33]
	v_mfma_f32_16x16x32_bf16 v[26:29], v[110:113], v[182:185], v[26:29]
	v_mfma_f32_16x16x32_bf16 v[14:17], v[86:89], v[202:205], v[14:17]
	v_mfma_f32_16x16x32_bf16 v[10:13], v[110:113], v[202:205], v[10:13]
	v_mfma_f32_16x16x32_bf16 v[54:57], v[122:125], v[162:165], v[54:57]
	v_mfma_f32_16x16x32_bf16 v[50:53], v[146:149], v[162:165], v[50:53]
	v_mfma_f32_16x16x32_bf16 v[38:41], v[122:125], v[170:173], v[38:41]
	v_mfma_f32_16x16x32_bf16 v[34:37], v[146:149], v[170:173], v[34:37]
	v_mfma_f32_16x16x32_bf16 v[22:25], v[122:125], v[178:181], v[22:25]
	v_mfma_f32_16x16x32_bf16 v[18:21], v[146:149], v[178:181], v[18:21]
	v_mfma_f32_16x16x32_bf16 v[6:9], v[122:125], v[186:189], v[6:9]
	v_mfma_f32_16x16x32_bf16 v[2:5], v[146:149], v[186:189], v[2:5]
	v_mfma_f32_16x16x32_bf16 v[54:57], v[134:137], v[166:169], v[54:57]
	v_mfma_f32_16x16x32_bf16 v[50:53], v[150:153], v[166:169], v[50:53]
	v_mfma_f32_16x16x32_bf16 v[38:41], v[134:137], v[174:177], v[38:41]
	v_mfma_f32_16x16x32_bf16 v[34:37], v[150:153], v[174:177], v[34:37]
	v_mfma_f32_16x16x32_bf16 v[22:25], v[134:137], v[182:185], v[22:25]
	v_mfma_f32_16x16x32_bf16 v[18:21], v[150:153], v[182:185], v[18:21]
	v_mfma_f32_16x16x32_bf16 v[6:9], v[134:137], v[202:205], v[6:9]
	v_mfma_f32_16x16x32_bf16 v[2:5], v[150:153], v[202:205], v[2:5]
	s_barrier
	s_add_i32 s84, 0, 0x18000
	s_add_i32 s85, 0, 0x1c000
	v_add_u32_e32 v110, s84, v211
	v_add_u32_e32 v150, s85, v211
	ds_read_b128 v[78:81], v110
	ds_read_b128 v[86:89], v110 offset:1024
	ds_read_b128 v[102:105], v110 offset:2048
	ds_read_b128 v[110:113], v110 offset:3072
	ds_read_b128 v[122:125], v150
	ds_read_b128 v[134:137], v150 offset:1024
	ds_read_b128 v[146:149], v150 offset:2048
	ds_read_b128 v[150:153], v150 offset:3072
	s_add_u32 s8, s30, 0x160000
	s_addc_u32 s9, s31, 0
	s_mov_b32 m0, s37
	ds_read_b128 v[162:165], v212 offset:32768
	ds_read_b128 v[166:169], v212 offset:33792
	ds_read_b128 v[170:173], v212 offset:34816
	ds_read_b128 v[174:177], v212 offset:35840
	ds_read_b128 v[178:181], v212 offset:36864
	ds_read_b128 v[182:185], v212 offset:37888
	ds_read_b128 v[186:189], v212 offset:38912
	ds_read_b128 v[202:205], v212 offset:39936
	global_load_lds_dwordx4 v196, s[8:9]
	v_lshl_add_u64 v[218:219], s[8:9], 0, v[192:193]
	s_mov_b32 m0, s40
	s_nop 0
	global_load_lds_dwordx4 v[218:219], off
	s_waitcnt vmcnt(8)
	s_waitcnt lgkmcnt(0)
	s_barrier
	s_waitcnt lgkmcnt(0)
	v_mfma_f32_16x16x32_bf16 v[158:161], v[78:81], v[162:165], v[158:161]
	v_mfma_f32_16x16x32_bf16 v[154:157], v[102:105], v[162:165], v[154:157]
	v_mfma_f32_16x16x32_bf16 v[130:133], v[78:81], v[170:173], v[130:133]
	v_mfma_f32_16x16x32_bf16 v[126:129], v[102:105], v[170:173], v[126:129]
	v_mfma_f32_16x16x32_bf16 v[106:109], v[78:81], v[178:181], v[106:109]
	v_mfma_f32_16x16x32_bf16 v[98:101], v[102:105], v[178:181], v[98:101]
	v_mfma_f32_16x16x32_bf16 v[82:85], v[78:81], v[186:189], v[82:85]
	v_mfma_f32_16x16x32_bf16 v[74:77], v[102:105], v[186:189], v[74:77]
	v_mfma_f32_16x16x32_bf16 v[158:161], v[86:89], v[166:169], v[158:161]
	v_mfma_f32_16x16x32_bf16 v[154:157], v[110:113], v[166:169], v[154:157]
	v_mfma_f32_16x16x32_bf16 v[130:133], v[86:89], v[174:177], v[130:133]
	v_mfma_f32_16x16x32_bf16 v[126:129], v[110:113], v[174:177], v[126:129]
	v_mfma_f32_16x16x32_bf16 v[106:109], v[86:89], v[182:185], v[106:109]
	v_mfma_f32_16x16x32_bf16 v[98:101], v[110:113], v[182:185], v[98:101]
	v_mfma_f32_16x16x32_bf16 v[82:85], v[86:89], v[202:205], v[82:85]
	v_mfma_f32_16x16x32_bf16 v[74:77], v[110:113], v[202:205], v[74:77]
	v_mfma_f32_16x16x32_bf16 v[142:145], v[122:125], v[162:165], v[142:145]
	v_mfma_f32_16x16x32_bf16 v[138:141], v[146:149], v[162:165], v[138:141]
	v_mfma_f32_16x16x32_bf16 v[118:121], v[122:125], v[170:173], v[118:121]
	v_mfma_f32_16x16x32_bf16 v[114:117], v[146:149], v[170:173], v[114:117]
	v_mfma_f32_16x16x32_bf16 v[94:97], v[122:125], v[178:181], v[94:97]
	v_mfma_f32_16x16x32_bf16 v[90:93], v[146:149], v[178:181], v[90:93]
	v_mfma_f32_16x16x32_bf16 v[70:73], v[122:125], v[186:189], v[70:73]
	v_mfma_f32_16x16x32_bf16 v[66:69], v[146:149], v[186:189], v[66:69]
	v_mfma_f32_16x16x32_bf16 v[142:145], v[134:137], v[166:169], v[142:145]
	v_mfma_f32_16x16x32_bf16 v[138:141], v[150:153], v[166:169], v[138:141]
	v_mfma_f32_16x16x32_bf16 v[118:121], v[134:137], v[174:177], v[118:121]
	v_mfma_f32_16x16x32_bf16 v[114:117], v[150:153], v[174:177], v[114:117]
	v_mfma_f32_16x16x32_bf16 v[94:97], v[134:137], v[182:185], v[94:97]
	v_mfma_f32_16x16x32_bf16 v[90:93], v[150:153], v[182:185], v[90:93]
	v_mfma_f32_16x16x32_bf16 v[70:73], v[134:137], v[202:205], v[70:73]
	v_mfma_f32_16x16x32_bf16 v[66:69], v[150:153], v[202:205], v[66:69]
	s_barrier
; #define PG8_STAGE(bufoff, gbase, voff) do { _Pragma("unroll") for (int _i = 0; _i < 2; ++_i) \
;         __builtin_amdgcn_global_load_lds((const unsigned*)((const char*)(gbase) + (voff)[_i]), (PG8_LAS unsigned*)(lds + (bufoff) + ldsw + _i * 8192), 16, 0, 0); } while (0)
; #define PG8_LDA(dst, b, h) do { _Pragma("unroll") for (int m = 0; m < 4; ++m) _Pragma("unroll") for (int k = 0; k < 2; ++k) dst[m][k] = *(const PG8_LAS bf16x8*)(lds + PG8_SA(b, h) + aoff + m * 2048 + k * 1024); } while (0)
; #define PG8_MMA(ai, bj, At, Bt) do { __builtin_amdgcn_s_setprio(1); _Pragma("unroll") for (int m = 0; m < 4; ++m) _Pragma("unroll") for (int n = 0; n < 2; ++n) _Pragma("unroll") for (int k = 0; k < 2; ++k) \
;         acc[ai][bj][m][n] = __builtin_amdgcn_mfma_f32_16x16x32_bf16(Bt[n][k], At[m][k], acc[ai][bj][m][n], 0, 0, 0); __builtin_amdgcn_s_setprio(0); } while (0)
; #define PG8_WAIT_V(n) asm volatile("s_waitcnt vmcnt(" #n ")" ::: "memory")
; #define PG8_WAIT_L(n) asm volatile("s_waitcnt lgkmcnt(" #n ")" ::: "memory")
; #define PG8_BAR __builtin_amdgcn_s_barrier()
; #define PG8_SCHED __builtin_amdgcn_sched_barrier(0)
; template <class Epi, class Sched, bool ALIGN_EPI = false, bool SP2 = false>
; __device__ __forceinline__ void gemm_phase(PG8_LAS unsigned char* lds, const Gemm g, const Sched& S, const Epi& E, int wave_s) {
;     ...
;             PG8_LDA(At, 1, 1); PG8_STAGE(PG8_SB(1, 0), b3, voffB); PG8_STAGE(PG8_SB(1, 1), b3 + hstepB, voffB); PG8_STAGE(PG8_SA(1, 0), a3, voffA);
;             PG8_WAIT_V(8); PG8_WAIT_L(0); PG8_BAR; PG8_MMA(1, 0, At, B0); PG8_MMA(1, 1, At, B1); PG8_BAR; PG8_SCHED;
;     ...
;         if constexpr (ALIGN_EPI) { if (wr == 0) PG8_BAR; }
	s_add_i32 s8, s84, s22
	v_lshl_add_u64 v[206:207], v[206:207], 0, s[60:61]
	s_mov_b32 m0, s8
	ds_read_b128 v[162:165], v212 offset:49152
	ds_read_b128 v[166:169], v212 offset:50176
	ds_read_b128 v[170:173], v212 offset:51200
	ds_read_b128 v[174:177], v212 offset:52224
	ds_read_b128 v[178:181], v212 offset:53248
	ds_read_b128 v[182:185], v212 offset:54272
	ds_read_b128 v[186:189], v212 offset:55296
	ds_read_b128 v[202:205], v212 offset:56320
	global_load_lds_dwordx4 v[206:207], off
	s_add_i32 m0, s8, 0x2000
	s_add_u32 s6, s6, 0x160080
	v_lshl_add_u64 v[206:207], v[208:209], 0, s[60:61]
	s_addc_u32 s7, s7, 0
	s_add_i32 s8, s85, s22
	global_load_lds_dwordx4 v[206:207], off
	s_mov_b32 m0, s8
	s_nop 0
	global_load_lds_dwordx4 v194, s[6:7]
	s_add_i32 m0, s8, 0x2000
	s_nop 0
	global_load_lds_dwordx4 v190, s[6:7]
	v_lshl_add_u64 v[206:207], v[214:215], 0, s[60:61]
	s_mov_b32 m0, s44
	s_nop 0
	global_load_lds_dwordx4 v[206:207], off
	v_lshl_add_u64 v[206:207], v[216:217], 0, s[60:61]
	s_mov_b32 m0, s45
	s_nop 0
	global_load_lds_dwordx4 v[206:207], off
	s_waitcnt vmcnt(8)
	s_waitcnt lgkmcnt(0)
	s_barrier
	s_waitcnt lgkmcnt(0)
	v_mfma_f32_16x16x32_bf16 v[62:65], v[78:81], v[162:165], v[62:65]
	v_mfma_f32_16x16x32_bf16 v[58:61], v[102:105], v[162:165], v[58:61]
	v_mfma_f32_16x16x32_bf16 v[46:49], v[78:81], v[170:173], v[46:49]
	v_mfma_f32_16x16x32_bf16 v[42:45], v[102:105], v[170:173], v[42:45]
	v_mfma_f32_16x16x32_bf16 v[30:33], v[78:81], v[178:181], v[30:33]
	v_mfma_f32_16x16x32_bf16 v[26:29], v[102:105], v[178:181], v[26:29]
	v_mfma_f32_16x16x32_bf16 v[14:17], v[78:81], v[186:189], v[14:17]
	v_mfma_f32_16x16x32_bf16 v[10:13], v[102:105], v[186:189], v[10:13]
	v_mfma_f32_16x16x32_bf16 v[62:65], v[86:89], v[166:169], v[62:65]
	v_mfma_f32_16x16x32_bf16 v[58:61], v[110:113], v[166:169], v[58:61]
	v_mfma_f32_16x16x32_bf16 v[46:49], v[86:89], v[174:177], v[46:49]
	v_mfma_f32_16x16x32_bf16 v[42:45], v[110:113], v[174:177], v[42:45]
	v_mfma_f32_16x16x32_bf16 v[30:33], v[86:89], v[182:185], v[30:33]
	v_mfma_f32_16x16x32_bf16 v[26:29], v[110:113], v[182:185], v[26:29]
	v_mfma_f32_16x16x32_bf16 v[14:17], v[86:89], v[202:205], v[14:17]
	v_mfma_f32_16x16x32_bf16 v[10:13], v[110:113], v[202:205], v[10:13]
	v_mfma_f32_16x16x32_bf16 v[54:57], v[122:125], v[162:165], v[54:57]
	v_mfma_f32_16x16x32_bf16 v[50:53], v[146:149], v[162:165], v[50:53]
	v_mfma_f32_16x16x32_bf16 v[38:41], v[122:125], v[170:173], v[38:41]
	v_mfma_f32_16x16x32_bf16 v[34:37], v[146:149], v[170:173], v[34:37]
	v_mfma_f32_16x16x32_bf16 v[22:25], v[122:125], v[178:181], v[22:25]
	v_mfma_f32_16x16x32_bf16 v[18:21], v[146:149], v[178:181], v[18:21]
	v_mfma_f32_16x16x32_bf16 v[6:9], v[122:125], v[186:189], v[6:9]
	v_mfma_f32_16x16x32_bf16 v[2:5], v[146:149], v[186:189], v[2:5]
	v_mfma_f32_16x16x32_bf16 v[54:57], v[134:137], v[166:169], v[54:57]
	v_mfma_f32_16x16x32_bf16 v[50:53], v[150:153], v[166:169], v[50:53]
	v_mfma_f32_16x16x32_bf16 v[38:41], v[134:137], v[174:177], v[38:41]
	v_mfma_f32_16x16x32_bf16 v[34:37], v[150:153], v[174:177], v[34:37]
	v_mfma_f32_16x16x32_bf16 v[22:25], v[134:137], v[182:185], v[22:25]
	v_mfma_f32_16x16x32_bf16 v[18:21], v[150:153], v[182:185], v[18:21]
	v_mfma_f32_16x16x32_bf16 v[6:9], v[134:137], v[202:205], v[6:9]
	v_mfma_f32_16x16x32_bf16 v[2:5], v[150:153], v[202:205], v[2:5]
	s_barrier
	s_add_i32 s81, s81, 2
	s_add_u32 s2, s2, 0x100
	s_addc_u32 s3, s3, 0
	s_cmpk_gt_u32 s81, 0x55
	s_mov_b64 s[8:9], s[4:5]
	s_cbranch_scc0 .LBB0_786
	s_and_b64 vcc, exec, s[88:89]
	s_cbranch_vccz .LBB0_789
	s_barrier
